# v35 + B-fragment LDS base biased once per phase so all B slots are reached through ds_read offsets: no VALU instruction left in the K-loops besides the MFMAs
# speedup vs baseline: 1.0078x; 1.0032x over previous
.LBB0_388:
	v_bfe_u32 v18, v8, 4, 2
	v_and_b32_e32 v9, 15, v8
	v_lshlrev_b32_e32 v20, 4, v18
	v_lshlrev_b32_e32 v8, 2, v8
	v_mov_b32_e32 v133, v203
	s_and_b32 s38, s0, 3
	v_lshl_or_b32 v150, s1, 6, v9
	v_lshl_or_b32 v9, v9, 6, v20
	s_lshl_b32 s0, s1, 13
	v_and_b32_e32 v8, 32, v8
	v_lshl_add_u64 v[10:11], s[26:27], 0, v[132:133]
	v_mov_b32_e32 v137, v203
	v_bitop3_b32 v20, v9, s0, v8 bitop3:0xde
	s_lshl_b32 s0, s38, 12
	v_lshl_add_u64 v[12:13], s[26:27], 0, v[136:137]
	v_mov_b32_e32 v131, v203
	v_bitop3_b32 v151, v9, s0, v8 bitop3:0xde
	v_add_u32_e32 v151, 0x10000, v151
	s_add_i32 m0, s9, 0x18000
	v_lshl_add_u64 v[8:9], v[10:11], 0, s[80:81]
	v_lshl_add_u64 v[14:15], s[24:25], 0, v[130:131]
	v_mov_b32_e32 v135, v203
	s_waitcnt vmcnt(2)
	s_barrier
	global_load_lds_dwordx4 v[8:9], off
	v_lshl_add_u64 v[8:9], v[12:13], 0, s[80:81]
	s_add_i32 m0, s9, 0x1a000
	s_add_i32 s39, s9, 0x8000
	s_add_i32 s40, s9, 0xa000
	v_lshl_add_u64 v[16:17], s[24:25], 0, v[134:135]
	global_load_lds_dwordx4 v[8:9], off
	v_lshl_add_u64 v[8:9], v[14:15], 0, s[80:81]
	s_mov_b32 m0, s39
	s_add_u32 s0, s26, 0x80080
	global_load_lds_dwordx4 v[8:9], off
	v_lshl_add_u64 v[8:9], v[16:17], 0, s[80:81]
	s_mov_b32 m0, s40
	s_addc_u32 s1, s27, 0
	global_load_lds_dwordx4 v[8:9], off
	s_add_i32 m0, s9, 0x1c000
	v_lshl_add_u64 v[8:9], s[0:1], 0, v[132:133]
	global_load_lds_dwordx4 v[8:9], off
	v_lshl_add_u64 v[8:9], s[0:1], 0, v[136:137]
	s_add_i32 m0, s9, 0x1e000
	v_lshlrev_b32_e32 v19, 3, v18
	global_load_lds_dwordx4 v[8:9], off
	v_lshlrev_b32_e32 v8, 15, v2
	v_and_b32_e32 v8, 0xffff0000, v8
	v_lshl_add_u32 v3, v3, 12, v8
	v_and_b32_e32 v2, 1, v2
	v_lshl_or_b32 v2, v2, 6, v3
	v_lshl_add_u32 v138, v4, 1, v2
	v_lshlrev_b32_e32 v2, 15, v5
	v_and_b32_e32 v2, 0xffff0000, v2
	s_waitcnt vmcnt(6)
	v_lshl_add_u32 v2, v6, 12, v2
	v_and_b32_e32 v3, 1, v5
	s_cmpk_lt_u32 s2, 0x100
	v_lshl_or_b32 v2, v3, 6, v2
	v_lshl_or_b32 v152, s38, 5, v19
	s_cselect_b64 s[14:15], -1, 0
	s_mov_b32 s41, 0
	v_cmp_eq_u32_e64 s[2:3], 0, v18
	v_mov_b32_e32 v139, v203
	v_lshl_add_u32 v140, v7, 1, v2
	v_mov_b32_e32 v141, v203
	v_add_u32_e32 v153, 0, v20
	s_barrier
	s_branch .LBB0_391

.LBB0_394:
	s_add_u32 s0, s24, 0xfff80080
	s_addc_u32 s1, s25, -1
	s_add_i32 s33, 0, 0x10000
	s_cmp_eq_u32 s60, 28
	s_cselect_b32 s29, s7, s1
	s_cselect_b32 s28, s19, s0
	s_cselect_b32 s27, s17, s59
	s_cselect_b32 s26, s49, s58
	s_add_i32 s55, 0, 0x14000
	ds_read_b128 v[142:145], v151
	ds_read_b128 v[146:149], v151 offset:1024
	ds_read_b128 v[154:157], v151 offset:2048
	ds_read_b128 v[158:161], v151 offset:3072
	ds_read_b128 v[162:165], v151 offset:16384
	ds_read_b128 v[166:169], v151 offset:17408
	ds_read_b128 v[170:173], v151 offset:18432
	ds_read_b128 v[174:177], v151 offset:19456
	s_add_i32 m0, s9, 0xc000
	ds_read_b128 v[178:181], v153
	ds_read_b128 v[182:185], v153 offset:1024
	ds_read_b128 v[186:189], v153 offset:2048
	ds_read_b128 v[190:193], v153 offset:3072
	ds_read_b128 v[194:197], v153 offset:4096
	ds_read_b128 v[198:201], v153 offset:5120
	ds_read_b128 v[208:211], v153 offset:6144
	ds_read_b128 v[212:215], v153 offset:7168
	global_load_lds_dwordx4 v138, s[24:25]
	s_add_i32 m0, s9, 0xe000
	s_nop 0
	global_load_lds_dwordx4 v140, s[24:25]
	s_waitcnt vmcnt(8)
	s_waitcnt lgkmcnt(0)
	s_setprio 1
	s_barrier
	v_mfma_f32_16x16x32_bf16 v[126:129], v[142:145], v[178:181], v[126:129]
	v_mfma_f32_16x16x32_bf16 v[122:125], v[154:157], v[178:181], v[122:125]
	v_mfma_f32_16x16x32_bf16 v[110:113], v[142:145], v[186:189], v[110:113]
	v_mfma_f32_16x16x32_bf16 v[106:109], v[154:157], v[186:189], v[106:109]
	v_mfma_f32_16x16x32_bf16 v[94:97], v[142:145], v[194:197], v[94:97]
	v_mfma_f32_16x16x32_bf16 v[90:93], v[154:157], v[194:197], v[90:93]
	v_mfma_f32_16x16x32_bf16 v[78:81], v[142:145], v[208:211], v[78:81]
	v_mfma_f32_16x16x32_bf16 v[74:77], v[154:157], v[208:211], v[74:77]
	v_mfma_f32_16x16x32_bf16 v[126:129], v[146:149], v[182:185], v[126:129]
	v_mfma_f32_16x16x32_bf16 v[122:125], v[158:161], v[182:185], v[122:125]
	v_mfma_f32_16x16x32_bf16 v[110:113], v[146:149], v[190:193], v[110:113]
	v_mfma_f32_16x16x32_bf16 v[106:109], v[158:161], v[190:193], v[106:109]
	v_mfma_f32_16x16x32_bf16 v[94:97], v[146:149], v[198:201], v[94:97]
	v_mfma_f32_16x16x32_bf16 v[90:93], v[158:161], v[198:201], v[90:93]
	v_mfma_f32_16x16x32_bf16 v[78:81], v[146:149], v[212:215], v[78:81]
	v_mfma_f32_16x16x32_bf16 v[74:77], v[158:161], v[212:215], v[74:77]
	s_setprio 0
	s_setprio 1
	v_mfma_f32_16x16x32_bf16 v[118:121], v[162:165], v[178:181], v[118:121]
	v_mfma_f32_16x16x32_bf16 v[114:117], v[170:173], v[178:181], v[114:117]
	v_mfma_f32_16x16x32_bf16 v[102:105], v[162:165], v[186:189], v[102:105]
	v_mfma_f32_16x16x32_bf16 v[98:101], v[170:173], v[186:189], v[98:101]
	v_mfma_f32_16x16x32_bf16 v[86:89], v[162:165], v[194:197], v[86:89]
	v_mfma_f32_16x16x32_bf16 v[82:85], v[170:173], v[194:197], v[82:85]
	v_mfma_f32_16x16x32_bf16 v[70:73], v[162:165], v[208:211], v[70:73]
	v_mfma_f32_16x16x32_bf16 v[66:69], v[170:173], v[208:211], v[66:69]
	v_mfma_f32_16x16x32_bf16 v[118:121], v[166:169], v[182:185], v[118:121]
	v_mfma_f32_16x16x32_bf16 v[114:117], v[174:177], v[182:185], v[114:117]
	v_mfma_f32_16x16x32_bf16 v[102:105], v[166:169], v[190:193], v[102:105]
	v_mfma_f32_16x16x32_bf16 v[98:101], v[174:177], v[190:193], v[98:101]
	v_mfma_f32_16x16x32_bf16 v[86:89], v[166:169], v[198:201], v[86:89]
	v_mfma_f32_16x16x32_bf16 v[82:85], v[174:177], v[198:201], v[82:85]
	v_mfma_f32_16x16x32_bf16 v[70:73], v[166:169], v[212:215], v[70:73]
	v_mfma_f32_16x16x32_bf16 v[66:69], v[174:177], v[212:215], v[66:69]
	s_barrier
	s_setprio 0
	s_add_i32 s0, s33, s34
	s_mov_b32 m0, s0
	ds_read_b128 v[178:181], v153 offset:16384
	ds_read_b128 v[182:185], v153 offset:17408
	ds_read_b128 v[186:189], v153 offset:18432
	ds_read_b128 v[190:193], v153 offset:19456
	ds_read_b128 v[194:197], v153 offset:20480
	ds_read_b128 v[198:201], v153 offset:21504
	ds_read_b128 v[208:211], v153 offset:22528
	ds_read_b128 v[212:215], v153 offset:23552
	global_load_lds_dwordx4 v132, s[26:27]
	s_add_i32 m0, s0, 0x2000
	s_add_u32 s0, s26, 0x80000
	s_addc_u32 s1, s27, 0
	s_add_i32 s33, s55, s34
	global_load_lds_dwordx4 v136, s[26:27]
	s_mov_b32 m0, s33
	s_nop 0
	global_load_lds_dwordx4 v132, s[0:1]
	s_add_i32 m0, s33, 0x2000
	s_nop 0
	global_load_lds_dwordx4 v136, s[0:1]
	s_mov_b32 m0, s9
	s_nop 0
	global_load_lds_dwordx4 v130, s[28:29]
	s_mov_b32 m0, s35
	s_nop 0
	global_load_lds_dwordx4 v134, s[28:29]
	s_waitcnt vmcnt(8)
	s_waitcnt lgkmcnt(0)
	s_setprio 1
	s_barrier
	v_mfma_f32_16x16x32_bf16 v[62:65], v[142:145], v[178:181], v[62:65]
	v_mfma_f32_16x16x32_bf16 v[58:61], v[154:157], v[178:181], v[58:61]
	v_mfma_f32_16x16x32_bf16 v[46:49], v[142:145], v[186:189], v[46:49]
	v_mfma_f32_16x16x32_bf16 v[42:45], v[154:157], v[186:189], v[42:45]
	v_mfma_f32_16x16x32_bf16 v[30:33], v[142:145], v[194:197], v[30:33]
	v_mfma_f32_16x16x32_bf16 v[26:29], v[154:157], v[194:197], v[26:29]
	v_mfma_f32_16x16x32_bf16 v[14:17], v[142:145], v[208:211], v[14:17]
	v_mfma_f32_16x16x32_bf16 v[10:13], v[154:157], v[208:211], v[10:13]
	v_mfma_f32_16x16x32_bf16 v[62:65], v[146:149], v[182:185], v[62:65]
	v_mfma_f32_16x16x32_bf16 v[58:61], v[158:161], v[182:185], v[58:61]
	v_mfma_f32_16x16x32_bf16 v[46:49], v[146:149], v[190:193], v[46:49]
	v_mfma_f32_16x16x32_bf16 v[42:45], v[158:161], v[190:193], v[42:45]
	v_mfma_f32_16x16x32_bf16 v[30:33], v[146:149], v[198:201], v[30:33]
	v_mfma_f32_16x16x32_bf16 v[26:29], v[158:161], v[198:201], v[26:29]
	v_mfma_f32_16x16x32_bf16 v[14:17], v[146:149], v[212:215], v[14:17]
	v_mfma_f32_16x16x32_bf16 v[10:13], v[158:161], v[212:215], v[10:13]
	s_setprio 0
	s_setprio 1
	v_mfma_f32_16x16x32_bf16 v[54:57], v[162:165], v[178:181], v[54:57]
	v_mfma_f32_16x16x32_bf16 v[50:53], v[170:173], v[178:181], v[50:53]
	v_mfma_f32_16x16x32_bf16 v[38:41], v[162:165], v[186:189], v[38:41]
	v_mfma_f32_16x16x32_bf16 v[34:37], v[170:173], v[186:189], v[34:37]
	v_mfma_f32_16x16x32_bf16 v[22:25], v[162:165], v[194:197], v[22:25]
	v_mfma_f32_16x16x32_bf16 v[18:21], v[170:173], v[194:197], v[18:21]
	v_mfma_f32_16x16x32_bf16 v[6:9], v[162:165], v[208:211], v[6:9]
	v_mfma_f32_16x16x32_bf16 v[2:5], v[170:173], v[208:211], v[2:5]
	v_mfma_f32_16x16x32_bf16 v[54:57], v[166:169], v[182:185], v[54:57]
	v_mfma_f32_16x16x32_bf16 v[50:53], v[174:177], v[182:185], v[50:53]
	v_mfma_f32_16x16x32_bf16 v[38:41], v[166:169], v[190:193], v[38:41]
	v_mfma_f32_16x16x32_bf16 v[34:37], v[174:177], v[190:193], v[34:37]
	v_mfma_f32_16x16x32_bf16 v[22:25], v[166:169], v[198:201], v[22:25]
	v_mfma_f32_16x16x32_bf16 v[18:21], v[174:177], v[198:201], v[18:21]
	v_mfma_f32_16x16x32_bf16 v[6:9], v[166:169], v[212:215], v[6:9]
	v_mfma_f32_16x16x32_bf16 v[2:5], v[174:177], v[212:215], v[2:5]
	s_barrier
	s_setprio 0
	s_add_i32 s33, 0, 0x18000
	s_add_i32 s55, 0, 0x1c000
	ds_read_b128 v[142:145], v151 offset:32768
	ds_read_b128 v[146:149], v151 offset:33792
	ds_read_b128 v[154:157], v151 offset:34816
	ds_read_b128 v[158:161], v151 offset:35840
	ds_read_b128 v[162:165], v151 offset:49152
	ds_read_b128 v[166:169], v151 offset:50176
	ds_read_b128 v[170:173], v151 offset:51200
	ds_read_b128 v[174:177], v151 offset:52224
	s_add_u32 s0, s28, 0x80000
	s_addc_u32 s1, s29, 0
	s_mov_b32 m0, s36
	ds_read_b128 v[178:181], v153 offset:32768
	ds_read_b128 v[182:185], v153 offset:33792
	ds_read_b128 v[186:189], v153 offset:34816
	ds_read_b128 v[190:193], v153 offset:35840
	ds_read_b128 v[194:197], v153 offset:36864
	ds_read_b128 v[198:201], v153 offset:37888
	ds_read_b128 v[208:211], v153 offset:38912
	ds_read_b128 v[212:215], v153 offset:39936
	global_load_lds_dwordx4 v130, s[0:1]
	s_mov_b32 m0, s37
	s_nop 0
	global_load_lds_dwordx4 v134, s[0:1]
	s_waitcnt vmcnt(8)
	s_waitcnt lgkmcnt(0)
	s_setprio 1
	s_barrier
	v_mfma_f32_16x16x32_bf16 v[126:129], v[142:145], v[178:181], v[126:129]
	v_mfma_f32_16x16x32_bf16 v[122:125], v[154:157], v[178:181], v[122:125]
	v_mfma_f32_16x16x32_bf16 v[110:113], v[142:145], v[186:189], v[110:113]
	v_mfma_f32_16x16x32_bf16 v[106:109], v[154:157], v[186:189], v[106:109]
	v_mfma_f32_16x16x32_bf16 v[94:97], v[142:145], v[194:197], v[94:97]
	v_mfma_f32_16x16x32_bf16 v[90:93], v[154:157], v[194:197], v[90:93]
	v_mfma_f32_16x16x32_bf16 v[78:81], v[142:145], v[208:211], v[78:81]
	v_mfma_f32_16x16x32_bf16 v[74:77], v[154:157], v[208:211], v[74:77]
	v_mfma_f32_16x16x32_bf16 v[126:129], v[146:149], v[182:185], v[126:129]
	v_mfma_f32_16x16x32_bf16 v[122:125], v[158:161], v[182:185], v[122:125]
	v_mfma_f32_16x16x32_bf16 v[110:113], v[146:149], v[190:193], v[110:113]
	v_mfma_f32_16x16x32_bf16 v[106:109], v[158:161], v[190:193], v[106:109]
	v_mfma_f32_16x16x32_bf16 v[94:97], v[146:149], v[198:201], v[94:97]
	v_mfma_f32_16x16x32_bf16 v[90:93], v[158:161], v[198:201], v[90:93]
	v_mfma_f32_16x16x32_bf16 v[78:81], v[146:149], v[212:215], v[78:81]
	v_mfma_f32_16x16x32_bf16 v[74:77], v[158:161], v[212:215], v[74:77]
	s_setprio 0
	s_setprio 1
	v_mfma_f32_16x16x32_bf16 v[118:121], v[162:165], v[178:181], v[118:121]
	v_mfma_f32_16x16x32_bf16 v[114:117], v[170:173], v[178:181], v[114:117]
	v_mfma_f32_16x16x32_bf16 v[102:105], v[162:165], v[186:189], v[102:105]
	v_mfma_f32_16x16x32_bf16 v[98:101], v[170:173], v[186:189], v[98:101]
	v_mfma_f32_16x16x32_bf16 v[86:89], v[162:165], v[194:197], v[86:89]
	v_mfma_f32_16x16x32_bf16 v[82:85], v[170:173], v[194:197], v[82:85]
	v_mfma_f32_16x16x32_bf16 v[70:73], v[162:165], v[208:211], v[70:73]
	v_mfma_f32_16x16x32_bf16 v[66:69], v[170:173], v[208:211], v[66:69]
	v_mfma_f32_16x16x32_bf16 v[118:121], v[166:169], v[182:185], v[118:121]
	v_mfma_f32_16x16x32_bf16 v[114:117], v[174:177], v[182:185], v[114:117]
	v_mfma_f32_16x16x32_bf16 v[102:105], v[166:169], v[190:193], v[102:105]
	v_mfma_f32_16x16x32_bf16 v[98:101], v[174:177], v[190:193], v[98:101]
	v_mfma_f32_16x16x32_bf16 v[86:89], v[166:169], v[198:201], v[86:89]
	v_mfma_f32_16x16x32_bf16 v[82:85], v[174:177], v[198:201], v[82:85]
	v_mfma_f32_16x16x32_bf16 v[70:73], v[166:169], v[212:215], v[70:73]
	v_mfma_f32_16x16x32_bf16 v[66:69], v[174:177], v[212:215], v[66:69]
	s_barrier
	s_setprio 0
	s_add_i32 s0, s33, s34
	s_add_u32 s100, s26, 0x80
	s_addc_u32 s101, s27, 0
	s_mov_b32 m0, s0
	ds_read_b128 v[178:181], v153 offset:49152
	ds_read_b128 v[182:185], v153 offset:50176
	ds_read_b128 v[186:189], v153 offset:51200
	ds_read_b128 v[190:193], v153 offset:52224
	ds_read_b128 v[194:197], v153 offset:53248
	ds_read_b128 v[198:201], v153 offset:54272
	ds_read_b128 v[208:211], v153 offset:55296
	ds_read_b128 v[212:215], v153 offset:56320
	global_load_lds_dwordx4 v132, s[100:101]
	s_add_i32 m0, s0, 0x2000
	s_add_u32 s100, s26, 0x80
	s_addc_u32 s101, s27, 0
	s_add_u32 s0, s26, 0x80080
	s_addc_u32 s1, s27, 0
	s_add_i32 s26, s55, s34
	global_load_lds_dwordx4 v136, s[100:101]
	s_mov_b32 m0, s26
	s_nop 0
	global_load_lds_dwordx4 v132, s[0:1]
	s_add_i32 m0, s26, 0x2000
	s_nop 0
	global_load_lds_dwordx4 v136, s[0:1]
	s_add_u32 s100, s28, 0x80
	s_addc_u32 s101, s29, 0
	s_mov_b32 m0, s39
	s_nop 0
	global_load_lds_dwordx4 v130, s[100:101]
	s_add_u32 s100, s28, 0x80
	s_addc_u32 s101, s29, 0
	s_mov_b32 m0, s40
	s_nop 0
	global_load_lds_dwordx4 v134, s[100:101]
	s_waitcnt vmcnt(8)
	s_waitcnt lgkmcnt(0)
	s_setprio 1
	s_barrier
	v_mfma_f32_16x16x32_bf16 v[62:65], v[142:145], v[178:181], v[62:65]
	v_mfma_f32_16x16x32_bf16 v[58:61], v[154:157], v[178:181], v[58:61]
	v_mfma_f32_16x16x32_bf16 v[46:49], v[142:145], v[186:189], v[46:49]
	v_mfma_f32_16x16x32_bf16 v[42:45], v[154:157], v[186:189], v[42:45]
	v_mfma_f32_16x16x32_bf16 v[30:33], v[142:145], v[194:197], v[30:33]
	v_mfma_f32_16x16x32_bf16 v[26:29], v[154:157], v[194:197], v[26:29]
	v_mfma_f32_16x16x32_bf16 v[14:17], v[142:145], v[208:211], v[14:17]
	v_mfma_f32_16x16x32_bf16 v[10:13], v[154:157], v[208:211], v[10:13]
	v_mfma_f32_16x16x32_bf16 v[62:65], v[146:149], v[182:185], v[62:65]
	v_mfma_f32_16x16x32_bf16 v[58:61], v[158:161], v[182:185], v[58:61]
	v_mfma_f32_16x16x32_bf16 v[46:49], v[146:149], v[190:193], v[46:49]
	v_mfma_f32_16x16x32_bf16 v[42:45], v[158:161], v[190:193], v[42:45]
	v_mfma_f32_16x16x32_bf16 v[30:33], v[146:149], v[198:201], v[30:33]
	v_mfma_f32_16x16x32_bf16 v[26:29], v[158:161], v[198:201], v[26:29]
	v_mfma_f32_16x16x32_bf16 v[14:17], v[146:149], v[212:215], v[14:17]
	v_mfma_f32_16x16x32_bf16 v[10:13], v[158:161], v[212:215], v[10:13]
	s_setprio 0
	s_setprio 1
	v_mfma_f32_16x16x32_bf16 v[54:57], v[162:165], v[178:181], v[54:57]
	v_mfma_f32_16x16x32_bf16 v[50:53], v[170:173], v[178:181], v[50:53]
	v_mfma_f32_16x16x32_bf16 v[38:41], v[162:165], v[186:189], v[38:41]
	v_mfma_f32_16x16x32_bf16 v[34:37], v[170:173], v[186:189], v[34:37]
	v_mfma_f32_16x16x32_bf16 v[22:25], v[162:165], v[194:197], v[22:25]
	v_mfma_f32_16x16x32_bf16 v[18:21], v[170:173], v[194:197], v[18:21]
	v_mfma_f32_16x16x32_bf16 v[6:9], v[162:165], v[208:211], v[6:9]
	v_mfma_f32_16x16x32_bf16 v[2:5], v[170:173], v[208:211], v[2:5]
	v_mfma_f32_16x16x32_bf16 v[54:57], v[166:169], v[182:185], v[54:57]
	v_mfma_f32_16x16x32_bf16 v[50:53], v[174:177], v[182:185], v[50:53]
	v_mfma_f32_16x16x32_bf16 v[38:41], v[166:169], v[190:193], v[38:41]
	v_mfma_f32_16x16x32_bf16 v[34:37], v[174:177], v[190:193], v[34:37]
	v_mfma_f32_16x16x32_bf16 v[22:25], v[166:169], v[198:201], v[22:25]
	v_mfma_f32_16x16x32_bf16 v[18:21], v[174:177], v[198:201], v[18:21]
	v_mfma_f32_16x16x32_bf16 v[6:9], v[166:169], v[212:215], v[6:9]
	v_mfma_f32_16x16x32_bf16 v[2:5], v[174:177], v[212:215], v[2:5]
	s_barrier
	s_setprio 0
	s_add_i32 s60, s60, 2
	s_add_u32 s24, s24, 0x100
	s_addc_u32 s25, s25, 0
	s_add_u32 s58, s58, 0x100
	s_addc_u32 s59, s59, 0
	s_cmp_gt_u32 s60, 29
	s_cbranch_scc0 .LBB0_394
	s_and_b64 vcc, exec, s[14:15]
	s_cbranch_vccz .LBB0_397
	s_barrier

.LBB0_682:
	s_add_u32 s31, s40, 0x4000
	v_lshrrev_b32_e32 v18, 1, v12
	v_readlane_b32 s18, v253, 46
	s_addc_u32 s34, s41, 0
	v_and_b32_e32 v18, 24, v18
	s_lshl_b32 s0, s0, 5
	v_mov_b32_e32 v213, v203
	v_readlane_b32 s19, v253, 47
	v_and_b32_e32 v13, 15, v12
	v_lshlrev_b32_e32 v19, 1, v18
	v_lshlrev_b32_e32 v12, 2, v12
	s_and_b32 s3, s0, 0x60
	s_add_i32 m0, s27, 0x18000
	v_lshl_add_u64 v[2:3], v[2:3], 0, s[80:81]
	v_lshl_add_u64 v[14:15], s[18:19], 0, v[212:213]
	v_mov_b32_e32 v211, v203
	v_lshl_or_b32 v204, s1, 6, v13
	v_lshl_or_b32 v13, v13, 6, v19
	s_lshl_b32 s1, s1, 13
	v_and_b32_e32 v12, 32, v12
	s_lshl_b32 s0, s3, 7
	s_waitcnt vmcnt(2)
	s_barrier
	global_load_lds_dwordx4 v[2:3], off
	v_lshl_add_u64 v[2:3], v[4:5], 0, s[80:81]
	s_add_i32 m0, s27, 0x1a000
	s_add_i32 s35, s27, 0x8000
	s_add_i32 s36, s27, 0xa000
	v_lshl_add_u64 v[16:17], s[18:19], 0, v[210:211]
	v_bitop3_b32 v205, v13, s0, v12 bitop3:0xde
	v_add_u32_e32 v205, 0x10000, v205
	global_load_lds_dwordx4 v[2:3], off
	v_lshl_add_u64 v[2:3], v[14:15], 0, s[80:81]
	s_mov_b32 m0, s35
	s_add_u32 s0, s20, 0x100080
	v_bitop3_b32 v19, v13, s1, v12 bitop3:0xde
	global_load_lds_dwordx4 v[2:3], off
	v_lshl_add_u64 v[2:3], v[16:17], 0, s[80:81]
	s_mov_b32 m0, s36
	s_addc_u32 s1, s21, 0
	global_load_lds_dwordx4 v[2:3], off
	s_add_i32 m0, s27, 0x1c000
	v_lshl_add_u64 v[2:3], s[0:1], 0, v[202:203]
	global_load_lds_dwordx4 v[2:3], off
	v_lshl_add_u64 v[2:3], s[0:1], 0, v[208:209]
	s_add_i32 m0, s27, 0x1e000
	s_cmpk_lt_u32 s2, 0x100
	global_load_lds_dwordx4 v[2:3], off
	v_lshlrev_b32_e32 v2, 16, v10
	v_and_b32_e32 v2, 0xfffe0000, v2
	v_lshl_add_u32 v2, v9, 13, v2
	v_and_b32_e32 v3, 1, v10
	v_lshl_or_b32 v2, v3, 6, v2
	v_lshl_add_u32 v214, v11, 1, v2
	v_lshlrev_b32_e32 v2, 16, v6
	v_and_b32_e32 v2, 0xfffe0000, v2
	s_waitcnt vmcnt(6)
	v_lshl_add_u32 v2, v7, 13, v2
	v_and_b32_e32 v3, 1, v6
	v_lshl_or_b32 v2, v3, 6, v2
	v_readlane_b32 s0, v253, 50
	s_cselect_b64 s[6:7], -1, 0
	v_or_b32_e32 v238, s3, v18
	v_mov_b32_e32 v215, v203
	v_lshl_add_u32 v216, v8, 1, v2
	v_mov_b32_e32 v217, v203
	s_mov_b32 s37, 0
	v_add_u32_e32 v239, 0, v19
	v_readlane_b32 s39, v254, 44
	s_mov_b32 s38, s0
	s_barrier
	v_readlane_b32 s1, v253, 51
	s_branch .LBB0_685

.LBB0_692:
	s_add_u32 s0, s18, 0xfff00080
	s_addc_u32 s1, s19, -1
	s_add_i32 s33, 0, 0x10000
	s_cmp_eq_u32 s61, 60
	s_cselect_b32 s23, s11, s1
	s_cselect_b32 s22, s49, s0
	s_cselect_b32 s21, s9, s60
	s_cselect_b32 s20, s58, s59
	s_add_i32 s55, 0, 0x14000
	ds_read_b128 v[78:81], v205
	ds_read_b128 v[86:89], v205 offset:1024
	ds_read_b128 v[94:97], v205 offset:2048
	ds_read_b128 v[98:101], v205 offset:3072
	ds_read_b128 v[106:109], v205 offset:16384
	ds_read_b128 v[110:113], v205 offset:17408
	ds_read_b128 v[126:129], v205 offset:18432
	ds_read_b128 v[134:137], v205 offset:19456
	s_add_i32 m0, s27, 0xc000
	ds_read_b128 v[146:149], v239
	ds_read_b128 v[158:161], v239 offset:1024
	ds_read_b128 v[166:169], v239 offset:2048
	ds_read_b128 v[174:177], v239 offset:3072
	ds_read_b128 v[178:181], v239 offset:4096
	ds_read_b128 v[182:185], v239 offset:5120
	ds_read_b128 v[186:189], v239 offset:6144
	ds_read_b128 v[190:193], v239 offset:7168
	global_load_lds_dwordx4 v214, s[18:19]
	s_add_i32 m0, s27, 0xe000
	s_nop 0
	global_load_lds_dwordx4 v216, s[18:19]
	s_waitcnt vmcnt(8)
	s_waitcnt lgkmcnt(0)
	s_setprio 1
	s_barrier
	v_mfma_f32_16x16x32_bf16 v[170:173], v[78:81], v[146:149], v[170:173]
	v_mfma_f32_16x16x32_bf16 v[162:165], v[94:97], v[146:149], v[162:165]
	v_mfma_f32_16x16x32_bf16 v[142:145], v[78:81], v[166:169], v[142:145]
	v_mfma_f32_16x16x32_bf16 v[138:141], v[94:97], v[166:169], v[138:141]
	v_mfma_f32_16x16x32_bf16 v[118:121], v[78:81], v[178:181], v[118:121]
	v_mfma_f32_16x16x32_bf16 v[114:117], v[94:97], v[178:181], v[114:117]
	v_mfma_f32_16x16x32_bf16 v[82:85], v[78:81], v[186:189], v[82:85]
	v_mfma_f32_16x16x32_bf16 v[74:77], v[94:97], v[186:189], v[74:77]
	v_mfma_f32_16x16x32_bf16 v[170:173], v[86:89], v[158:161], v[170:173]
	v_mfma_f32_16x16x32_bf16 v[162:165], v[98:101], v[158:161], v[162:165]
	v_mfma_f32_16x16x32_bf16 v[142:145], v[86:89], v[174:177], v[142:145]
	v_mfma_f32_16x16x32_bf16 v[138:141], v[98:101], v[174:177], v[138:141]
	v_mfma_f32_16x16x32_bf16 v[118:121], v[86:89], v[182:185], v[118:121]
	v_mfma_f32_16x16x32_bf16 v[114:117], v[98:101], v[182:185], v[114:117]
	v_mfma_f32_16x16x32_bf16 v[82:85], v[86:89], v[190:193], v[82:85]
	v_mfma_f32_16x16x32_bf16 v[74:77], v[98:101], v[190:193], v[74:77]
	s_setprio 0
	s_setprio 1
	v_mfma_f32_16x16x32_bf16 v[154:157], v[106:109], v[146:149], v[154:157]
	v_mfma_f32_16x16x32_bf16 v[130:133], v[106:109], v[166:169], v[130:133]
	v_mfma_f32_16x16x32_bf16 v[122:125], v[126:129], v[166:169], v[122:125]
	v_mfma_f32_16x16x32_bf16 v[102:105], v[106:109], v[178:181], v[102:105]
	v_mfma_f32_16x16x32_bf16 v[90:93], v[126:129], v[178:181], v[90:93]
	v_mfma_f32_16x16x32_bf16 v[70:73], v[106:109], v[186:189], v[70:73]
	v_mfma_f32_16x16x32_bf16 v[66:69], v[126:129], v[186:189], v[66:69]
	v_mfma_f32_16x16x32_bf16 v[154:157], v[110:113], v[158:161], v[154:157]
	v_mfma_f32_16x16x32_bf16 v[146:149], v[126:129], v[146:149], v[150:153]
	v_mfma_f32_16x16x32_bf16 v[130:133], v[110:113], v[174:177], v[130:133]
	v_mfma_f32_16x16x32_bf16 v[122:125], v[134:137], v[174:177], v[122:125]
	v_mfma_f32_16x16x32_bf16 v[102:105], v[110:113], v[182:185], v[102:105]
	v_mfma_f32_16x16x32_bf16 v[90:93], v[134:137], v[182:185], v[90:93]
	v_mfma_f32_16x16x32_bf16 v[70:73], v[110:113], v[190:193], v[70:73]
	v_mfma_f32_16x16x32_bf16 v[66:69], v[134:137], v[190:193], v[66:69]
	v_mfma_f32_16x16x32_bf16 v[146:149], v[134:137], v[158:161], v[146:149]
	s_barrier
	s_setprio 0
	s_add_i32 s0, s33, s26
	s_mov_b32 m0, s0
	ds_read_b128 v[150:153], v239 offset:16384
	ds_read_b128 v[158:161], v239 offset:17408
	ds_read_b128 v[166:169], v239 offset:18432
	ds_read_b128 v[174:177], v239 offset:19456
	ds_read_b128 v[178:181], v239 offset:20480
	ds_read_b128 v[182:185], v239 offset:21504
	ds_read_b128 v[186:189], v239 offset:22528
	ds_read_b128 v[190:193], v239 offset:23552
	global_load_lds_dwordx4 v202, s[20:21]
	s_add_i32 m0, s0, 0x2000
	s_add_u32 s0, s20, 0x100000
	s_addc_u32 s1, s21, 0
	s_add_i32 s33, s55, s26
	global_load_lds_dwordx4 v208, s[20:21]
	s_mov_b32 m0, s33
	s_nop 0
	global_load_lds_dwordx4 v202, s[0:1]
	s_add_i32 m0, s33, 0x2000
	s_nop 0
	global_load_lds_dwordx4 v208, s[0:1]
	s_mov_b32 m0, s27
	s_nop 0
	global_load_lds_dwordx4 v212, s[22:23]
	s_mov_b32 m0, s28
	s_nop 0
	global_load_lds_dwordx4 v210, s[22:23]
	s_waitcnt vmcnt(8)
	s_waitcnt lgkmcnt(0)
	s_setprio 1
	s_barrier
	v_mfma_f32_16x16x32_bf16 v[62:65], v[78:81], v[150:153], v[62:65]
	v_mfma_f32_16x16x32_bf16 v[58:61], v[94:97], v[150:153], v[58:61]
	v_mfma_f32_16x16x32_bf16 v[46:49], v[78:81], v[166:169], v[46:49]
	v_mfma_f32_16x16x32_bf16 v[42:45], v[94:97], v[166:169], v[42:45]
	v_mfma_f32_16x16x32_bf16 v[30:33], v[78:81], v[178:181], v[30:33]
	v_mfma_f32_16x16x32_bf16 v[26:29], v[94:97], v[178:181], v[26:29]
	v_mfma_f32_16x16x32_bf16 v[14:17], v[78:81], v[186:189], v[14:17]
	v_mfma_f32_16x16x32_bf16 v[10:13], v[94:97], v[186:189], v[10:13]
	v_mfma_f32_16x16x32_bf16 v[62:65], v[86:89], v[158:161], v[62:65]
	v_mfma_f32_16x16x32_bf16 v[58:61], v[98:101], v[158:161], v[58:61]
	v_mfma_f32_16x16x32_bf16 v[46:49], v[86:89], v[174:177], v[46:49]
	v_mfma_f32_16x16x32_bf16 v[42:45], v[98:101], v[174:177], v[42:45]
	v_mfma_f32_16x16x32_bf16 v[30:33], v[86:89], v[182:185], v[30:33]
	v_mfma_f32_16x16x32_bf16 v[26:29], v[98:101], v[182:185], v[26:29]
	v_mfma_f32_16x16x32_bf16 v[14:17], v[86:89], v[190:193], v[14:17]
	v_mfma_f32_16x16x32_bf16 v[10:13], v[98:101], v[190:193], v[10:13]
	s_setprio 0
	s_setprio 1
	v_mfma_f32_16x16x32_bf16 v[54:57], v[106:109], v[150:153], v[54:57]
	v_mfma_f32_16x16x32_bf16 v[50:53], v[126:129], v[150:153], v[50:53]
	v_mfma_f32_16x16x32_bf16 v[38:41], v[106:109], v[166:169], v[38:41]
	v_mfma_f32_16x16x32_bf16 v[34:37], v[126:129], v[166:169], v[34:37]
	v_mfma_f32_16x16x32_bf16 v[22:25], v[106:109], v[178:181], v[22:25]
	v_mfma_f32_16x16x32_bf16 v[18:21], v[126:129], v[178:181], v[18:21]
	v_mfma_f32_16x16x32_bf16 v[6:9], v[106:109], v[186:189], v[6:9]
	v_mfma_f32_16x16x32_bf16 v[2:5], v[126:129], v[186:189], v[2:5]
	v_mfma_f32_16x16x32_bf16 v[54:57], v[110:113], v[158:161], v[54:57]
	v_mfma_f32_16x16x32_bf16 v[50:53], v[134:137], v[158:161], v[50:53]
	v_mfma_f32_16x16x32_bf16 v[38:41], v[110:113], v[174:177], v[38:41]
	v_mfma_f32_16x16x32_bf16 v[34:37], v[134:137], v[174:177], v[34:37]
	v_mfma_f32_16x16x32_bf16 v[22:25], v[110:113], v[182:185], v[22:25]
	v_mfma_f32_16x16x32_bf16 v[18:21], v[134:137], v[182:185], v[18:21]
	v_mfma_f32_16x16x32_bf16 v[6:9], v[110:113], v[190:193], v[6:9]
	v_mfma_f32_16x16x32_bf16 v[2:5], v[134:137], v[190:193], v[2:5]
	s_barrier
	s_setprio 0
	s_add_i32 s33, 0, 0x18000
	s_add_i32 s55, 0, 0x1c000
	ds_read_b128 v[78:81], v205 offset:32768
	ds_read_b128 v[86:89], v205 offset:33792
	ds_read_b128 v[94:97], v205 offset:34816
	ds_read_b128 v[98:101], v205 offset:35840
	ds_read_b128 v[106:109], v205 offset:49152
	ds_read_b128 v[110:113], v205 offset:50176
	ds_read_b128 v[126:129], v205 offset:51200
	ds_read_b128 v[134:137], v205 offset:52224
	s_add_u32 s0, s22, 0x100000
	s_addc_u32 s1, s23, 0
	s_mov_b32 m0, s29
	ds_read_b128 v[150:153], v239 offset:32768
	ds_read_b128 v[158:161], v239 offset:33792
	ds_read_b128 v[166:169], v239 offset:34816
	ds_read_b128 v[174:177], v239 offset:35840
	ds_read_b128 v[178:181], v239 offset:36864
	ds_read_b128 v[182:185], v239 offset:37888
	ds_read_b128 v[186:189], v239 offset:38912
	ds_read_b128 v[190:193], v239 offset:39936
	global_load_lds_dwordx4 v212, s[0:1]
	s_mov_b32 m0, s30
	s_nop 0
	global_load_lds_dwordx4 v210, s[0:1]
	s_waitcnt vmcnt(8)
	s_waitcnt lgkmcnt(0)
	s_setprio 1
	s_barrier
	v_mfma_f32_16x16x32_bf16 v[170:173], v[78:81], v[150:153], v[170:173]
	v_mfma_f32_16x16x32_bf16 v[162:165], v[94:97], v[150:153], v[162:165]
	v_mfma_f32_16x16x32_bf16 v[142:145], v[78:81], v[166:169], v[142:145]
	v_mfma_f32_16x16x32_bf16 v[138:141], v[94:97], v[166:169], v[138:141]
	v_mfma_f32_16x16x32_bf16 v[118:121], v[78:81], v[178:181], v[118:121]
	v_mfma_f32_16x16x32_bf16 v[114:117], v[94:97], v[178:181], v[114:117]
	v_mfma_f32_16x16x32_bf16 v[82:85], v[78:81], v[186:189], v[82:85]
	v_mfma_f32_16x16x32_bf16 v[74:77], v[94:97], v[186:189], v[74:77]
	v_mfma_f32_16x16x32_bf16 v[170:173], v[86:89], v[158:161], v[170:173]
	v_mfma_f32_16x16x32_bf16 v[162:165], v[98:101], v[158:161], v[162:165]
	v_mfma_f32_16x16x32_bf16 v[142:145], v[86:89], v[174:177], v[142:145]
	v_mfma_f32_16x16x32_bf16 v[138:141], v[98:101], v[174:177], v[138:141]
	v_mfma_f32_16x16x32_bf16 v[118:121], v[86:89], v[182:185], v[118:121]
	v_mfma_f32_16x16x32_bf16 v[114:117], v[98:101], v[182:185], v[114:117]
	v_mfma_f32_16x16x32_bf16 v[82:85], v[86:89], v[190:193], v[82:85]
	v_mfma_f32_16x16x32_bf16 v[74:77], v[98:101], v[190:193], v[74:77]
	s_setprio 0
	s_setprio 1
	v_mfma_f32_16x16x32_bf16 v[154:157], v[106:109], v[150:153], v[154:157]
	v_mfma_f32_16x16x32_bf16 v[146:149], v[126:129], v[150:153], v[146:149]
	v_mfma_f32_16x16x32_bf16 v[130:133], v[106:109], v[166:169], v[130:133]
	v_mfma_f32_16x16x32_bf16 v[122:125], v[126:129], v[166:169], v[122:125]
	v_mfma_f32_16x16x32_bf16 v[102:105], v[106:109], v[178:181], v[102:105]
	v_mfma_f32_16x16x32_bf16 v[90:93], v[126:129], v[178:181], v[90:93]
	v_mfma_f32_16x16x32_bf16 v[70:73], v[106:109], v[186:189], v[70:73]
	v_mfma_f32_16x16x32_bf16 v[66:69], v[126:129], v[186:189], v[66:69]
	v_mfma_f32_16x16x32_bf16 v[154:157], v[110:113], v[158:161], v[154:157]
	v_mfma_f32_16x16x32_bf16 v[150:153], v[134:137], v[158:161], v[146:149]
	v_mfma_f32_16x16x32_bf16 v[130:133], v[110:113], v[174:177], v[130:133]
	v_mfma_f32_16x16x32_bf16 v[122:125], v[134:137], v[174:177], v[122:125]
	v_mfma_f32_16x16x32_bf16 v[102:105], v[110:113], v[182:185], v[102:105]
	v_mfma_f32_16x16x32_bf16 v[90:93], v[134:137], v[182:185], v[90:93]
	v_mfma_f32_16x16x32_bf16 v[70:73], v[110:113], v[190:193], v[70:73]
	v_mfma_f32_16x16x32_bf16 v[66:69], v[134:137], v[190:193], v[66:69]
	s_barrier
	s_setprio 0
	s_add_i32 s0, s33, s26
	s_add_u32 s100, s20, 0x80
	s_addc_u32 s101, s21, 0
	s_mov_b32 m0, s0
	ds_read_b128 v[146:149], v239 offset:49152
	ds_read_b128 v[158:161], v239 offset:50176
	ds_read_b128 v[166:169], v239 offset:51200
	ds_read_b128 v[174:177], v239 offset:52224
	ds_read_b128 v[178:181], v239 offset:53248
	ds_read_b128 v[182:185], v239 offset:54272
	ds_read_b128 v[186:189], v239 offset:55296
	ds_read_b128 v[190:193], v239 offset:56320
	global_load_lds_dwordx4 v202, s[100:101]
	s_add_i32 m0, s0, 0x2000
	s_add_u32 s100, s20, 0x80
	s_addc_u32 s101, s21, 0
	s_add_u32 s0, s20, 0x100080
	s_addc_u32 s1, s21, 0
	s_add_i32 s20, s55, s26
	global_load_lds_dwordx4 v208, s[100:101]
	s_mov_b32 m0, s20
	s_nop 0
	global_load_lds_dwordx4 v202, s[0:1]
	s_add_i32 m0, s20, 0x2000
	s_nop 0
	global_load_lds_dwordx4 v208, s[0:1]
	s_add_u32 s100, s22, 0x80
	s_addc_u32 s101, s23, 0
	s_mov_b32 m0, s35
	s_nop 0
	global_load_lds_dwordx4 v212, s[100:101]
	s_add_u32 s100, s22, 0x80
	s_addc_u32 s101, s23, 0
	s_mov_b32 m0, s36
	s_nop 0
	global_load_lds_dwordx4 v210, s[100:101]
	s_waitcnt vmcnt(8)
	s_waitcnt lgkmcnt(0)
	s_setprio 1
	s_barrier
	v_mfma_f32_16x16x32_bf16 v[62:65], v[78:81], v[146:149], v[62:65]
	v_mfma_f32_16x16x32_bf16 v[58:61], v[94:97], v[146:149], v[58:61]
	v_mfma_f32_16x16x32_bf16 v[46:49], v[78:81], v[166:169], v[46:49]
	v_mfma_f32_16x16x32_bf16 v[42:45], v[94:97], v[166:169], v[42:45]
	v_mfma_f32_16x16x32_bf16 v[30:33], v[78:81], v[178:181], v[30:33]
	v_mfma_f32_16x16x32_bf16 v[26:29], v[94:97], v[178:181], v[26:29]
	v_mfma_f32_16x16x32_bf16 v[14:17], v[78:81], v[186:189], v[14:17]
	v_mfma_f32_16x16x32_bf16 v[10:13], v[94:97], v[186:189], v[10:13]
	v_mfma_f32_16x16x32_bf16 v[62:65], v[86:89], v[158:161], v[62:65]
	v_mfma_f32_16x16x32_bf16 v[58:61], v[98:101], v[158:161], v[58:61]
	v_mfma_f32_16x16x32_bf16 v[46:49], v[86:89], v[174:177], v[46:49]
	v_mfma_f32_16x16x32_bf16 v[42:45], v[98:101], v[174:177], v[42:45]
	v_mfma_f32_16x16x32_bf16 v[30:33], v[86:89], v[182:185], v[30:33]
	v_mfma_f32_16x16x32_bf16 v[26:29], v[98:101], v[182:185], v[26:29]
	v_mfma_f32_16x16x32_bf16 v[14:17], v[86:89], v[190:193], v[14:17]
	v_mfma_f32_16x16x32_bf16 v[10:13], v[98:101], v[190:193], v[10:13]
	s_setprio 0
	s_setprio 1
	v_mfma_f32_16x16x32_bf16 v[54:57], v[106:109], v[146:149], v[54:57]
	v_mfma_f32_16x16x32_bf16 v[50:53], v[126:129], v[146:149], v[50:53]
	v_mfma_f32_16x16x32_bf16 v[38:41], v[106:109], v[166:169], v[38:41]
	v_mfma_f32_16x16x32_bf16 v[34:37], v[126:129], v[166:169], v[34:37]
	v_mfma_f32_16x16x32_bf16 v[22:25], v[106:109], v[178:181], v[22:25]
	v_mfma_f32_16x16x32_bf16 v[18:21], v[126:129], v[178:181], v[18:21]
	v_mfma_f32_16x16x32_bf16 v[6:9], v[106:109], v[186:189], v[6:9]
	v_mfma_f32_16x16x32_bf16 v[2:5], v[126:129], v[186:189], v[2:5]
	v_mfma_f32_16x16x32_bf16 v[54:57], v[110:113], v[158:161], v[54:57]
	v_mfma_f32_16x16x32_bf16 v[50:53], v[134:137], v[158:161], v[50:53]
	v_mfma_f32_16x16x32_bf16 v[38:41], v[110:113], v[174:177], v[38:41]
	v_mfma_f32_16x16x32_bf16 v[34:37], v[134:137], v[174:177], v[34:37]
	v_mfma_f32_16x16x32_bf16 v[22:25], v[110:113], v[182:185], v[22:25]
	v_mfma_f32_16x16x32_bf16 v[18:21], v[134:137], v[182:185], v[18:21]
	v_mfma_f32_16x16x32_bf16 v[6:9], v[110:113], v[190:193], v[6:9]
	v_mfma_f32_16x16x32_bf16 v[2:5], v[134:137], v[190:193], v[2:5]
	s_barrier
	s_setprio 0
	s_add_i32 s61, s61, 2
	s_add_u32 s18, s18, 0x100
	s_addc_u32 s19, s19, 0
	s_add_u32 s59, s59, 0x100
	s_addc_u32 s60, s60, 0
	s_cmp_gt_u32 s61, 61
	s_cbranch_scc0 .LBB0_692
	s_and_b64 vcc, exec, s[6:7]
	s_cbranch_vccz .LBB0_695
	s_barrier

.LBB0_702:
	v_bfe_u32 v18, v8, 4, 2
	s_lshl_b32 s0, s0, 5
	v_and_b32_e32 v9, 15, v8
	v_lshlrev_b32_e32 v20, 4, v18
	v_lshlrev_b32_e32 v8, 2, v8
	s_and_b32 s3, s0, 0x60
	v_lshl_or_b32 v19, s1, 6, v9
	v_lshl_or_b32 v9, v9, 6, v20
	s_lshl_b32 s1, s1, 13
	v_and_b32_e32 v8, 32, v8
	s_lshl_b32 s0, s3, 7
	v_lshl_add_u64 v[10:11], s[20:21], 0, v[202:203]
	v_mov_b32_e32 v131, v203
	v_readlane_b32 s18, v253, 7
	v_bitop3_b32 v136, v9, s0, v8 bitop3:0xde
	v_add_u32_e32 v136, 0x10000, v136
	s_add_u32 s0, s20, 0x100080
	v_lshl_add_u64 v[12:13], s[20:21], 0, v[130:131]
	v_readlane_b32 s19, v253, 8
	v_bitop3_b32 v20, v9, s1, v8 bitop3:0xde
	s_addc_u32 s1, s21, 0
	s_add_i32 m0, s27, 0x18000
	v_lshl_add_u64 v[8:9], v[10:11], 0, s[80:81]
	v_lshl_add_u64 v[14:15], s[18:19], 0, v[202:203]
	s_waitcnt vmcnt(2)
	s_barrier
	global_load_lds_dwordx4 v[8:9], off
	v_lshl_add_u64 v[8:9], v[12:13], 0, s[80:81]
	s_add_i32 m0, s27, 0x1a000
	s_add_i32 s31, s27, 0x8000
	v_lshl_add_u64 v[16:17], s[18:19], 0, v[130:131]
	global_load_lds_dwordx4 v[8:9], off
	v_lshl_add_u64 v[8:9], v[14:15], 0, s[80:81]
	s_mov_b32 m0, s31
	s_add_i32 s34, s27, 0xa000
	global_load_lds_dwordx4 v[8:9], off
	v_lshl_add_u64 v[8:9], v[16:17], 0, s[80:81]
	s_mov_b32 m0, s34
	v_add_u32_e32 v137, 0xffffc000, v19
	global_load_lds_dwordx4 v[8:9], off
	s_add_i32 m0, s27, 0x1c000
	v_lshl_add_u64 v[8:9], s[0:1], 0, v[202:203]
	global_load_lds_dwordx4 v[8:9], off
	v_lshl_add_u64 v[8:9], s[0:1], 0, v[130:131]
	s_add_i32 m0, s27, 0x1e000
	s_cmpk_lt_u32 s2, 0x100
	global_load_lds_dwordx4 v[8:9], off
	v_lshlrev_b32_e32 v8, 16, v5
	v_and_b32_e32 v8, 0xfffe0000, v8
	v_lshl_add_u32 v6, v6, 13, v8
	v_and_b32_e32 v5, 1, v5
	v_lshl_or_b32 v5, v5, 6, v6
	v_lshl_add_u32 v132, v7, 1, v5
	v_lshlrev_b32_e32 v5, 16, v2
	v_and_b32_e32 v5, 0xfffe0000, v5
	s_waitcnt vmcnt(6)
	v_lshl_add_u32 v3, v3, 13, v5
	v_and_b32_e32 v2, 1, v2
	v_lshl_or_b32 v2, v2, 6, v3
	s_cselect_b64 s[6:7], -1, 0
	v_lshl_or_b32 v138, v18, 2, s3
	v_mov_b32_e32 v133, v203
	v_lshl_add_u32 v134, v4, 1, v2
	v_mov_b32_e32 v135, v203
	s_mov_b32 s35, 0
	v_add_u32_e32 v139, 0, v20
	v_readlane_b32 s38, v253, 16
	v_readlane_b32 s39, v254, 41
	v_readlane_b32 s37, v253, 13
	s_barrier
	s_branch .LBB0_705

.LBB0_712:
	s_add_u32 s0, s18, 0xfff00080
	s_addc_u32 s1, s19, -1
	s_add_i32 s33, 0, 0x10000
	s_cmp_eq_u32 s49, 4
	s_cselect_b32 s23, s15, s1
	s_cselect_b32 s22, s14, s0
	s_cselect_b32 s21, s17, s11
	s_cselect_b32 s20, s16, s9
	s_add_i32 s55, 0, 0x14000
	ds_read_b128 v[140:143], v136
	ds_read_b128 v[144:147], v136 offset:1024
	ds_read_b128 v[148:151], v136 offset:2048
	ds_read_b128 v[152:155], v136 offset:3072
	ds_read_b128 v[156:159], v136 offset:16384
	ds_read_b128 v[160:163], v136 offset:17408
	ds_read_b128 v[164:167], v136 offset:18432
	ds_read_b128 v[168:171], v136 offset:19456
	s_add_i32 m0, s27, 0xc000
	ds_read_b128 v[172:175], v139
	ds_read_b128 v[176:179], v139 offset:1024
	ds_read_b128 v[180:183], v139 offset:2048
	ds_read_b128 v[184:187], v139 offset:3072
	ds_read_b128 v[188:191], v139 offset:4096
	ds_read_b128 v[192:195], v139 offset:5120
	ds_read_b128 v[196:199], v139 offset:6144
	ds_read_b128 v[208:211], v139 offset:7168
	global_load_lds_dwordx4 v132, s[18:19]
	s_add_i32 m0, s27, 0xe000
	s_nop 0
	global_load_lds_dwordx4 v134, s[18:19]
	s_waitcnt vmcnt(8)
	s_waitcnt lgkmcnt(0)
	s_setprio 1
	s_barrier
	v_mfma_f32_16x16x32_bf16 v[126:129], v[140:143], v[172:175], v[126:129]
	v_mfma_f32_16x16x32_bf16 v[122:125], v[148:151], v[172:175], v[122:125]
	v_mfma_f32_16x16x32_bf16 v[118:121], v[140:143], v[180:183], v[118:121]
	v_mfma_f32_16x16x32_bf16 v[114:117], v[148:151], v[180:183], v[114:117]
	v_mfma_f32_16x16x32_bf16 v[106:109], v[140:143], v[188:191], v[106:109]
	v_mfma_f32_16x16x32_bf16 v[98:101], v[148:151], v[188:191], v[98:101]
	v_mfma_f32_16x16x32_bf16 v[90:93], v[140:143], v[196:199], v[90:93]
	v_mfma_f32_16x16x32_bf16 v[82:85], v[148:151], v[196:199], v[82:85]
	v_mfma_f32_16x16x32_bf16 v[126:129], v[144:147], v[176:179], v[126:129]
	v_mfma_f32_16x16x32_bf16 v[122:125], v[152:155], v[176:179], v[122:125]
	v_mfma_f32_16x16x32_bf16 v[118:121], v[144:147], v[184:187], v[118:121]
	v_mfma_f32_16x16x32_bf16 v[114:117], v[152:155], v[184:187], v[114:117]
	v_mfma_f32_16x16x32_bf16 v[106:109], v[144:147], v[192:195], v[106:109]
	v_mfma_f32_16x16x32_bf16 v[98:101], v[152:155], v[192:195], v[98:101]
	v_mfma_f32_16x16x32_bf16 v[90:93], v[144:147], v[208:211], v[90:93]
	v_mfma_f32_16x16x32_bf16 v[82:85], v[152:155], v[208:211], v[82:85]
	s_setprio 0
	s_setprio 1
	v_mfma_f32_16x16x32_bf16 v[110:113], v[156:159], v[172:175], v[110:113]
	v_mfma_f32_16x16x32_bf16 v[102:105], v[164:167], v[172:175], v[102:105]
	v_mfma_f32_16x16x32_bf16 v[94:97], v[156:159], v[180:183], v[94:97]
	v_mfma_f32_16x16x32_bf16 v[86:89], v[164:167], v[180:183], v[86:89]
	v_mfma_f32_16x16x32_bf16 v[78:81], v[156:159], v[188:191], v[78:81]
	v_mfma_f32_16x16x32_bf16 v[74:77], v[164:167], v[188:191], v[74:77]
	v_mfma_f32_16x16x32_bf16 v[70:73], v[156:159], v[196:199], v[70:73]
	v_mfma_f32_16x16x32_bf16 v[66:69], v[164:167], v[196:199], v[66:69]
	v_mfma_f32_16x16x32_bf16 v[110:113], v[160:163], v[176:179], v[110:113]
	v_mfma_f32_16x16x32_bf16 v[102:105], v[168:171], v[176:179], v[102:105]
	v_mfma_f32_16x16x32_bf16 v[94:97], v[160:163], v[184:187], v[94:97]
	v_mfma_f32_16x16x32_bf16 v[86:89], v[168:171], v[184:187], v[86:89]
	v_mfma_f32_16x16x32_bf16 v[78:81], v[160:163], v[192:195], v[78:81]
	v_mfma_f32_16x16x32_bf16 v[74:77], v[168:171], v[192:195], v[74:77]
	v_mfma_f32_16x16x32_bf16 v[70:73], v[160:163], v[208:211], v[70:73]
	v_mfma_f32_16x16x32_bf16 v[66:69], v[168:171], v[208:211], v[66:69]
	s_barrier
	s_setprio 0
	s_add_i32 s0, s33, s26
	s_mov_b32 m0, s0
	ds_read_b128 v[172:175], v139 offset:16384
	ds_read_b128 v[176:179], v139 offset:17408
	ds_read_b128 v[180:183], v139 offset:18432
	ds_read_b128 v[184:187], v139 offset:19456
	ds_read_b128 v[188:191], v139 offset:20480
	ds_read_b128 v[192:195], v139 offset:21504
	ds_read_b128 v[196:199], v139 offset:22528
	ds_read_b128 v[208:211], v139 offset:23552
	global_load_lds_dwordx4 v202, s[20:21]
	s_add_i32 m0, s0, 0x2000
	s_add_u32 s0, s20, 0x100000
	s_addc_u32 s1, s21, 0
	s_add_i32 s33, s55, s26
	global_load_lds_dwordx4 v130, s[20:21]
	s_mov_b32 m0, s33
	s_nop 0
	global_load_lds_dwordx4 v202, s[0:1]
	s_add_i32 m0, s33, 0x2000
	s_nop 0
	global_load_lds_dwordx4 v130, s[0:1]
	s_mov_b32 m0, s27
	s_nop 0
	global_load_lds_dwordx4 v202, s[22:23]
	s_mov_b32 m0, s28
	s_nop 0
	global_load_lds_dwordx4 v130, s[22:23]
	s_waitcnt vmcnt(8)
	s_waitcnt lgkmcnt(0)
	s_setprio 1
	s_barrier
	v_mfma_f32_16x16x32_bf16 v[62:65], v[140:143], v[172:175], v[62:65]
	v_mfma_f32_16x16x32_bf16 v[58:61], v[148:151], v[172:175], v[58:61]
	v_mfma_f32_16x16x32_bf16 v[54:57], v[140:143], v[180:183], v[54:57]
	v_mfma_f32_16x16x32_bf16 v[50:53], v[148:151], v[180:183], v[50:53]
	v_mfma_f32_16x16x32_bf16 v[38:41], v[140:143], v[188:191], v[38:41]
	v_mfma_f32_16x16x32_bf16 v[34:37], v[148:151], v[188:191], v[34:37]
	v_mfma_f32_16x16x32_bf16 v[22:25], v[140:143], v[196:199], v[22:25]
	v_mfma_f32_16x16x32_bf16 v[18:21], v[148:151], v[196:199], v[18:21]
	v_mfma_f32_16x16x32_bf16 v[62:65], v[144:147], v[176:179], v[62:65]
	v_mfma_f32_16x16x32_bf16 v[58:61], v[152:155], v[176:179], v[58:61]
	v_mfma_f32_16x16x32_bf16 v[54:57], v[144:147], v[184:187], v[54:57]
	v_mfma_f32_16x16x32_bf16 v[50:53], v[152:155], v[184:187], v[50:53]
	v_mfma_f32_16x16x32_bf16 v[38:41], v[144:147], v[192:195], v[38:41]
	v_mfma_f32_16x16x32_bf16 v[34:37], v[152:155], v[192:195], v[34:37]
	v_mfma_f32_16x16x32_bf16 v[22:25], v[144:147], v[208:211], v[22:25]
	v_mfma_f32_16x16x32_bf16 v[18:21], v[152:155], v[208:211], v[18:21]
	s_setprio 0
	s_setprio 1
	v_mfma_f32_16x16x32_bf16 v[46:49], v[156:159], v[172:175], v[46:49]
	v_mfma_f32_16x16x32_bf16 v[42:45], v[164:167], v[172:175], v[42:45]
	v_mfma_f32_16x16x32_bf16 v[30:33], v[156:159], v[180:183], v[30:33]
	v_mfma_f32_16x16x32_bf16 v[26:29], v[164:167], v[180:183], v[26:29]
	v_mfma_f32_16x16x32_bf16 v[14:17], v[156:159], v[188:191], v[14:17]
	v_mfma_f32_16x16x32_bf16 v[10:13], v[164:167], v[188:191], v[10:13]
	v_mfma_f32_16x16x32_bf16 v[6:9], v[156:159], v[196:199], v[6:9]
	v_mfma_f32_16x16x32_bf16 v[2:5], v[164:167], v[196:199], v[2:5]
	v_mfma_f32_16x16x32_bf16 v[46:49], v[160:163], v[176:179], v[46:49]
	v_mfma_f32_16x16x32_bf16 v[42:45], v[168:171], v[176:179], v[42:45]
	v_mfma_f32_16x16x32_bf16 v[30:33], v[160:163], v[184:187], v[30:33]
	v_mfma_f32_16x16x32_bf16 v[26:29], v[168:171], v[184:187], v[26:29]
	v_mfma_f32_16x16x32_bf16 v[14:17], v[160:163], v[192:195], v[14:17]
	v_mfma_f32_16x16x32_bf16 v[10:13], v[168:171], v[192:195], v[10:13]
	v_mfma_f32_16x16x32_bf16 v[6:9], v[160:163], v[208:211], v[6:9]
	v_mfma_f32_16x16x32_bf16 v[2:5], v[168:171], v[208:211], v[2:5]
	s_barrier
	s_setprio 0
	s_add_i32 s33, 0, 0x18000
	s_add_i32 s55, 0, 0x1c000
	ds_read_b128 v[140:143], v136 offset:32768
	ds_read_b128 v[144:147], v136 offset:33792
	ds_read_b128 v[148:151], v136 offset:34816
	ds_read_b128 v[152:155], v136 offset:35840
	ds_read_b128 v[156:159], v136 offset:49152
	ds_read_b128 v[160:163], v136 offset:50176
	ds_read_b128 v[164:167], v136 offset:51200
	ds_read_b128 v[168:171], v136 offset:52224
	s_add_u32 s0, s22, 0x100000
	s_addc_u32 s1, s23, 0
	s_mov_b32 m0, s29
	ds_read_b128 v[172:175], v139 offset:32768
	ds_read_b128 v[176:179], v139 offset:33792
	ds_read_b128 v[180:183], v139 offset:34816
	ds_read_b128 v[184:187], v139 offset:35840
	ds_read_b128 v[188:191], v139 offset:36864
	ds_read_b128 v[192:195], v139 offset:37888
	ds_read_b128 v[196:199], v139 offset:38912
	ds_read_b128 v[208:211], v139 offset:39936
	global_load_lds_dwordx4 v202, s[0:1]
	s_mov_b32 m0, s30
	s_nop 0
	global_load_lds_dwordx4 v130, s[0:1]
	s_waitcnt vmcnt(8)
	s_waitcnt lgkmcnt(0)
	s_setprio 1
	s_barrier
	v_mfma_f32_16x16x32_bf16 v[126:129], v[140:143], v[172:175], v[126:129]
	v_mfma_f32_16x16x32_bf16 v[122:125], v[148:151], v[172:175], v[122:125]
	v_mfma_f32_16x16x32_bf16 v[118:121], v[140:143], v[180:183], v[118:121]
	v_mfma_f32_16x16x32_bf16 v[114:117], v[148:151], v[180:183], v[114:117]
	v_mfma_f32_16x16x32_bf16 v[106:109], v[140:143], v[188:191], v[106:109]
	v_mfma_f32_16x16x32_bf16 v[98:101], v[148:151], v[188:191], v[98:101]
	v_mfma_f32_16x16x32_bf16 v[90:93], v[140:143], v[196:199], v[90:93]
	v_mfma_f32_16x16x32_bf16 v[82:85], v[148:151], v[196:199], v[82:85]
	v_mfma_f32_16x16x32_bf16 v[126:129], v[144:147], v[176:179], v[126:129]
	v_mfma_f32_16x16x32_bf16 v[122:125], v[152:155], v[176:179], v[122:125]
	v_mfma_f32_16x16x32_bf16 v[118:121], v[144:147], v[184:187], v[118:121]
	v_mfma_f32_16x16x32_bf16 v[114:117], v[152:155], v[184:187], v[114:117]
	v_mfma_f32_16x16x32_bf16 v[106:109], v[144:147], v[192:195], v[106:109]
	v_mfma_f32_16x16x32_bf16 v[98:101], v[152:155], v[192:195], v[98:101]
	v_mfma_f32_16x16x32_bf16 v[90:93], v[144:147], v[208:211], v[90:93]
	v_mfma_f32_16x16x32_bf16 v[82:85], v[152:155], v[208:211], v[82:85]
	s_setprio 0
	s_setprio 1
	v_mfma_f32_16x16x32_bf16 v[110:113], v[156:159], v[172:175], v[110:113]
	v_mfma_f32_16x16x32_bf16 v[102:105], v[164:167], v[172:175], v[102:105]
	v_mfma_f32_16x16x32_bf16 v[94:97], v[156:159], v[180:183], v[94:97]
	v_mfma_f32_16x16x32_bf16 v[86:89], v[164:167], v[180:183], v[86:89]
	v_mfma_f32_16x16x32_bf16 v[78:81], v[156:159], v[188:191], v[78:81]
	v_mfma_f32_16x16x32_bf16 v[74:77], v[164:167], v[188:191], v[74:77]
	v_mfma_f32_16x16x32_bf16 v[70:73], v[156:159], v[196:199], v[70:73]
	v_mfma_f32_16x16x32_bf16 v[66:69], v[164:167], v[196:199], v[66:69]
	v_mfma_f32_16x16x32_bf16 v[110:113], v[160:163], v[176:179], v[110:113]
	v_mfma_f32_16x16x32_bf16 v[102:105], v[168:171], v[176:179], v[102:105]
	v_mfma_f32_16x16x32_bf16 v[94:97], v[160:163], v[184:187], v[94:97]
	v_mfma_f32_16x16x32_bf16 v[86:89], v[168:171], v[184:187], v[86:89]
	v_mfma_f32_16x16x32_bf16 v[78:81], v[160:163], v[192:195], v[78:81]
	v_mfma_f32_16x16x32_bf16 v[74:77], v[168:171], v[192:195], v[74:77]
	v_mfma_f32_16x16x32_bf16 v[70:73], v[160:163], v[208:211], v[70:73]
	v_mfma_f32_16x16x32_bf16 v[66:69], v[168:171], v[208:211], v[66:69]
	s_barrier
	s_setprio 0
	s_add_i32 s0, s33, s26
	s_add_u32 s100, s20, 0x80
	s_addc_u32 s101, s21, 0
	s_mov_b32 m0, s0
	ds_read_b128 v[172:175], v139 offset:49152
	ds_read_b128 v[176:179], v139 offset:50176
	ds_read_b128 v[180:183], v139 offset:51200
	ds_read_b128 v[184:187], v139 offset:52224
	ds_read_b128 v[188:191], v139 offset:53248
	ds_read_b128 v[192:195], v139 offset:54272
	ds_read_b128 v[196:199], v139 offset:55296
	ds_read_b128 v[208:211], v139 offset:56320
	global_load_lds_dwordx4 v202, s[100:101]
	s_add_i32 m0, s0, 0x2000
	s_add_u32 s100, s20, 0x80
	s_addc_u32 s101, s21, 0
	s_add_u32 s0, s20, 0x100080
	s_addc_u32 s1, s21, 0
	s_add_i32 s20, s55, s26
	global_load_lds_dwordx4 v130, s[100:101]
	s_mov_b32 m0, s20
	s_nop 0
	global_load_lds_dwordx4 v202, s[0:1]
	s_add_i32 m0, s20, 0x2000
	s_nop 0
	global_load_lds_dwordx4 v130, s[0:1]
	s_add_u32 s100, s22, 0x80
	s_addc_u32 s101, s23, 0
	s_mov_b32 m0, s31
	s_nop 0
	global_load_lds_dwordx4 v202, s[100:101]
	s_add_u32 s100, s22, 0x80
	s_addc_u32 s101, s23, 0
	s_mov_b32 m0, s34
	s_nop 0
	global_load_lds_dwordx4 v130, s[100:101]
	s_waitcnt vmcnt(8)
	s_waitcnt lgkmcnt(0)
	s_setprio 1
	s_barrier
	v_mfma_f32_16x16x32_bf16 v[62:65], v[140:143], v[172:175], v[62:65]
	v_mfma_f32_16x16x32_bf16 v[58:61], v[148:151], v[172:175], v[58:61]
	v_mfma_f32_16x16x32_bf16 v[54:57], v[140:143], v[180:183], v[54:57]
	v_mfma_f32_16x16x32_bf16 v[50:53], v[148:151], v[180:183], v[50:53]
	v_mfma_f32_16x16x32_bf16 v[38:41], v[140:143], v[188:191], v[38:41]
	v_mfma_f32_16x16x32_bf16 v[34:37], v[148:151], v[188:191], v[34:37]
	v_mfma_f32_16x16x32_bf16 v[22:25], v[140:143], v[196:199], v[22:25]
	v_mfma_f32_16x16x32_bf16 v[18:21], v[148:151], v[196:199], v[18:21]
	v_mfma_f32_16x16x32_bf16 v[62:65], v[144:147], v[176:179], v[62:65]
	v_mfma_f32_16x16x32_bf16 v[58:61], v[152:155], v[176:179], v[58:61]
	v_mfma_f32_16x16x32_bf16 v[54:57], v[144:147], v[184:187], v[54:57]
	v_mfma_f32_16x16x32_bf16 v[50:53], v[152:155], v[184:187], v[50:53]
	v_mfma_f32_16x16x32_bf16 v[38:41], v[144:147], v[192:195], v[38:41]
	v_mfma_f32_16x16x32_bf16 v[34:37], v[152:155], v[192:195], v[34:37]
	v_mfma_f32_16x16x32_bf16 v[22:25], v[144:147], v[208:211], v[22:25]
	v_mfma_f32_16x16x32_bf16 v[18:21], v[152:155], v[208:211], v[18:21]
	s_setprio 0
	s_setprio 1
	v_mfma_f32_16x16x32_bf16 v[46:49], v[156:159], v[172:175], v[46:49]
	v_mfma_f32_16x16x32_bf16 v[42:45], v[164:167], v[172:175], v[42:45]
	v_mfma_f32_16x16x32_bf16 v[30:33], v[156:159], v[180:183], v[30:33]
	v_mfma_f32_16x16x32_bf16 v[26:29], v[164:167], v[180:183], v[26:29]
	v_mfma_f32_16x16x32_bf16 v[14:17], v[156:159], v[188:191], v[14:17]
	v_mfma_f32_16x16x32_bf16 v[10:13], v[164:167], v[188:191], v[10:13]
	v_mfma_f32_16x16x32_bf16 v[6:9], v[156:159], v[196:199], v[6:9]
	v_mfma_f32_16x16x32_bf16 v[2:5], v[164:167], v[196:199], v[2:5]
	v_mfma_f32_16x16x32_bf16 v[46:49], v[160:163], v[176:179], v[46:49]
	v_mfma_f32_16x16x32_bf16 v[42:45], v[168:171], v[176:179], v[42:45]
	v_mfma_f32_16x16x32_bf16 v[30:33], v[160:163], v[184:187], v[30:33]
	v_mfma_f32_16x16x32_bf16 v[26:29], v[168:171], v[184:187], v[26:29]
	v_mfma_f32_16x16x32_bf16 v[14:17], v[160:163], v[192:195], v[14:17]
	v_mfma_f32_16x16x32_bf16 v[10:13], v[168:171], v[192:195], v[10:13]
	v_mfma_f32_16x16x32_bf16 v[6:9], v[160:163], v[208:211], v[6:9]
	v_mfma_f32_16x16x32_bf16 v[2:5], v[168:171], v[208:211], v[2:5]
	s_barrier
	s_setprio 0
	s_add_i32 s49, s49, 2
	s_add_u32 s18, s18, 0x100
	s_addc_u32 s19, s19, 0
	s_add_u32 s9, s9, 0x100
	s_addc_u32 s11, s11, 0
	s_cmp_gt_u32 s49, 5
	s_cbranch_scc0 .LBB0_712
	s_and_b64 vcc, exec, s[6:7]
	s_cbranch_vccz .LBB0_715
	s_barrier

.LBB0_831:
	v_lshrrev_b32_e32 v18, 1, v8
	v_and_b32_e32 v18, 24, v18
	s_lshl_b32 s0, s0, 5
	v_and_b32_e32 v9, 15, v8
	v_lshlrev_b32_e32 v19, 1, v18
	v_lshlrev_b32_e32 v8, 2, v8
	s_and_b32 s3, s0, 0x60
	v_lshl_add_u64 v[10:11], s[20:21], 0, v[202:203]
	v_mov_b32_e32 v131, v203
	v_readlane_b32 s18, v254, 3
	v_lshl_or_b32 v142, s1, 6, v9
	v_lshl_or_b32 v9, v9, 6, v19
	s_lshl_b32 s1, s1, 13
	v_and_b32_e32 v8, 32, v8
	s_lshl_b32 s0, s3, 7
	v_lshl_add_u64 v[12:13], s[20:21], 0, v[130:131]
	v_mov_b32_e32 v135, v203
	v_readlane_b32 s19, v254, 4
	v_bitop3_b32 v19, v9, s1, v8 bitop3:0xde
	v_bitop3_b32 v143, v9, s0, v8 bitop3:0xde
	v_add_u32_e32 v143, 0x10000, v143
	s_add_i32 m0, s27, 0x18000
	v_lshl_add_u64 v[8:9], v[10:11], 0, s[80:81]
	v_lshl_add_u64 v[14:15], s[18:19], 0, v[134:135]
	v_mov_b32_e32 v133, v203
	s_waitcnt vmcnt(2)
	s_barrier
	global_load_lds_dwordx4 v[8:9], off
	v_lshl_add_u64 v[8:9], v[12:13], 0, s[80:81]
	s_add_i32 m0, s27, 0x1a000
	s_add_i32 s31, s27, 0x8000
	s_add_i32 s34, s27, 0xa000
	v_lshl_add_u64 v[16:17], s[18:19], 0, v[132:133]
	global_load_lds_dwordx4 v[8:9], off
	v_lshl_add_u64 v[8:9], v[14:15], 0, s[80:81]
	s_mov_b32 m0, s31
	s_add_u32 s0, s20, 0x80080
	global_load_lds_dwordx4 v[8:9], off
	v_lshl_add_u64 v[8:9], v[16:17], 0, s[80:81]
	s_mov_b32 m0, s34
	s_addc_u32 s1, s21, 0
	global_load_lds_dwordx4 v[8:9], off
	s_add_i32 m0, s27, 0x1c000
	v_lshl_add_u64 v[8:9], s[0:1], 0, v[202:203]
	global_load_lds_dwordx4 v[8:9], off
	v_lshl_add_u64 v[8:9], s[0:1], 0, v[130:131]
	s_add_i32 m0, s27, 0x1e000
	s_cmpk_lt_u32 s2, 0x100
	global_load_lds_dwordx4 v[8:9], off
	v_lshlrev_b32_e32 v8, 15, v6
	v_and_b32_e32 v8, 0xffff0000, v8
	v_lshl_add_u32 v5, v5, 12, v8
	v_and_b32_e32 v6, 1, v6
	v_lshl_or_b32 v5, v6, 6, v5
	v_lshl_add_u32 v136, v7, 1, v5
	v_lshlrev_b32_e32 v5, 15, v2
	v_and_b32_e32 v5, 0xffff0000, v5
	s_waitcnt vmcnt(6)
	v_lshl_add_u32 v3, v3, 12, v5
	v_and_b32_e32 v2, 1, v2
	v_lshl_or_b32 v2, v2, 6, v3
	v_readlane_b32 s0, v254, 1
	s_cselect_b64 s[6:7], -1, 0
	v_or_b32_e32 v144, s3, v18
	v_mov_b32_e32 v137, v203
	v_lshl_add_u32 v138, v4, 1, v2
	v_mov_b32_e32 v139, v203
	s_mov_b32 s35, 0
	v_add_u32_e32 v145, 0, v19
	v_readlane_b32 s36, v254, 13
	s_mov_b32 s37, s0
	s_barrier
	v_readlane_b32 s1, v254, 2
	s_waitcnt vmcnt(0)
	s_branch .LBB0_834

.LBB0_837:
	s_add_u32 s0, s18, 0xfff80080
	s_addc_u32 s1, s19, -1
	s_add_i32 s33, 0, 0x10000
	s_cmp_eq_u32 s59, 28
	s_cselect_b32 s23, s11, s1
	s_cselect_b32 s22, s38, s0
	s_cselect_b32 s21, s9, s58
	s_cselect_b32 s20, s39, s49
	s_add_i32 s55, 0, 0x14000
	ds_read_b128 v[146:149], v143
	ds_read_b128 v[150:153], v143 offset:1024
	ds_read_b128 v[154:157], v143 offset:2048
	ds_read_b128 v[158:161], v143 offset:3072
	ds_read_b128 v[162:165], v143 offset:16384
	ds_read_b128 v[166:169], v143 offset:17408
	ds_read_b128 v[170:173], v143 offset:18432
	ds_read_b128 v[174:177], v143 offset:19456
	s_add_i32 m0, s27, 0xc000
	ds_read_b128 v[178:181], v145
	ds_read_b128 v[182:185], v145 offset:1024
	ds_read_b128 v[186:189], v145 offset:2048
	ds_read_b128 v[190:193], v145 offset:3072
	ds_read_b128 v[194:197], v145 offset:4096
	ds_read_b128 v[198:201], v145 offset:5120
	ds_read_b128 v[208:211], v145 offset:6144
	ds_read_b128 v[212:215], v145 offset:7168
	global_load_lds_dwordx4 v136, s[18:19]
	s_add_i32 m0, s27, 0xe000
	s_nop 0
	global_load_lds_dwordx4 v138, s[18:19]
	s_waitcnt vmcnt(8)
	s_waitcnt lgkmcnt(0)
	s_setprio 1
	s_barrier
	v_mfma_f32_16x16x32_bf16 v[126:129], v[146:149], v[178:181], v[126:129]
	v_mfma_f32_16x16x32_bf16 v[118:121], v[154:157], v[178:181], v[118:121]
	v_mfma_f32_16x16x32_bf16 v[110:113], v[146:149], v[186:189], v[110:113]
	v_mfma_f32_16x16x32_bf16 v[102:105], v[154:157], v[186:189], v[102:105]
	v_mfma_f32_16x16x32_bf16 v[94:97], v[146:149], v[194:197], v[94:97]
	v_mfma_f32_16x16x32_bf16 v[86:89], v[154:157], v[194:197], v[86:89]
	v_mfma_f32_16x16x32_bf16 v[78:81], v[146:149], v[208:211], v[78:81]
	v_mfma_f32_16x16x32_bf16 v[70:73], v[154:157], v[208:211], v[70:73]
	v_mfma_f32_16x16x32_bf16 v[126:129], v[150:153], v[182:185], v[126:129]
	v_mfma_f32_16x16x32_bf16 v[118:121], v[158:161], v[182:185], v[118:121]
	v_mfma_f32_16x16x32_bf16 v[110:113], v[150:153], v[190:193], v[110:113]
	v_mfma_f32_16x16x32_bf16 v[102:105], v[158:161], v[190:193], v[102:105]
	v_mfma_f32_16x16x32_bf16 v[94:97], v[150:153], v[198:201], v[94:97]
	v_mfma_f32_16x16x32_bf16 v[86:89], v[158:161], v[198:201], v[86:89]
	v_mfma_f32_16x16x32_bf16 v[78:81], v[150:153], v[212:215], v[78:81]
	v_mfma_f32_16x16x32_bf16 v[70:73], v[158:161], v[212:215], v[70:73]
	s_setprio 0
	s_setprio 1
	v_mfma_f32_16x16x32_bf16 v[122:125], v[162:165], v[178:181], v[122:125]
	v_mfma_f32_16x16x32_bf16 v[114:117], v[170:173], v[178:181], v[114:117]
	v_mfma_f32_16x16x32_bf16 v[106:109], v[162:165], v[186:189], v[106:109]
	v_mfma_f32_16x16x32_bf16 v[98:101], v[170:173], v[186:189], v[98:101]
	v_mfma_f32_16x16x32_bf16 v[90:93], v[162:165], v[194:197], v[90:93]
	v_mfma_f32_16x16x32_bf16 v[82:85], v[170:173], v[194:197], v[82:85]
	v_mfma_f32_16x16x32_bf16 v[74:77], v[162:165], v[208:211], v[74:77]
	v_mfma_f32_16x16x32_bf16 v[66:69], v[170:173], v[208:211], v[66:69]
	v_mfma_f32_16x16x32_bf16 v[122:125], v[166:169], v[182:185], v[122:125]
	v_mfma_f32_16x16x32_bf16 v[114:117], v[174:177], v[182:185], v[114:117]
	v_mfma_f32_16x16x32_bf16 v[106:109], v[166:169], v[190:193], v[106:109]
	v_mfma_f32_16x16x32_bf16 v[98:101], v[174:177], v[190:193], v[98:101]
	v_mfma_f32_16x16x32_bf16 v[90:93], v[166:169], v[198:201], v[90:93]
	v_mfma_f32_16x16x32_bf16 v[82:85], v[174:177], v[198:201], v[82:85]
	v_mfma_f32_16x16x32_bf16 v[74:77], v[166:169], v[212:215], v[74:77]
	v_mfma_f32_16x16x32_bf16 v[66:69], v[174:177], v[212:215], v[66:69]
	s_barrier
	s_setprio 0
	s_add_i32 s0, s33, s26
	s_mov_b32 m0, s0
	ds_read_b128 v[178:181], v145 offset:16384
	ds_read_b128 v[182:185], v145 offset:17408
	ds_read_b128 v[186:189], v145 offset:18432
	ds_read_b128 v[190:193], v145 offset:19456
	ds_read_b128 v[194:197], v145 offset:20480
	ds_read_b128 v[198:201], v145 offset:21504
	ds_read_b128 v[208:211], v145 offset:22528
	ds_read_b128 v[212:215], v145 offset:23552
	global_load_lds_dwordx4 v202, s[20:21]
	s_add_i32 m0, s0, 0x2000
	s_add_u32 s0, s20, 0x80000
	s_addc_u32 s1, s21, 0
	s_add_i32 s33, s55, s26
	global_load_lds_dwordx4 v130, s[20:21]
	s_mov_b32 m0, s33
	s_nop 0
	global_load_lds_dwordx4 v202, s[0:1]
	s_add_i32 m0, s33, 0x2000
	s_nop 0
	global_load_lds_dwordx4 v130, s[0:1]
	s_mov_b32 m0, s27
	s_nop 0
	global_load_lds_dwordx4 v134, s[22:23]
	s_mov_b32 m0, s28
	s_nop 0
	global_load_lds_dwordx4 v132, s[22:23]
	s_waitcnt vmcnt(8)
	s_waitcnt lgkmcnt(0)
	s_setprio 1
	s_barrier
	v_mfma_f32_16x16x32_bf16 v[62:65], v[146:149], v[178:181], v[62:65]
	v_mfma_f32_16x16x32_bf16 v[54:57], v[154:157], v[178:181], v[54:57]
	v_mfma_f32_16x16x32_bf16 v[46:49], v[146:149], v[186:189], v[46:49]
	v_mfma_f32_16x16x32_bf16 v[38:41], v[154:157], v[186:189], v[38:41]
	v_mfma_f32_16x16x32_bf16 v[30:33], v[146:149], v[194:197], v[30:33]
	v_mfma_f32_16x16x32_bf16 v[22:25], v[154:157], v[194:197], v[22:25]
	v_mfma_f32_16x16x32_bf16 v[14:17], v[146:149], v[208:211], v[14:17]
	v_mfma_f32_16x16x32_bf16 v[6:9], v[154:157], v[208:211], v[6:9]
	v_mfma_f32_16x16x32_bf16 v[62:65], v[150:153], v[182:185], v[62:65]
	v_mfma_f32_16x16x32_bf16 v[54:57], v[158:161], v[182:185], v[54:57]
	v_mfma_f32_16x16x32_bf16 v[46:49], v[150:153], v[190:193], v[46:49]
	v_mfma_f32_16x16x32_bf16 v[38:41], v[158:161], v[190:193], v[38:41]
	v_mfma_f32_16x16x32_bf16 v[30:33], v[150:153], v[198:201], v[30:33]
	v_mfma_f32_16x16x32_bf16 v[22:25], v[158:161], v[198:201], v[22:25]
	v_mfma_f32_16x16x32_bf16 v[14:17], v[150:153], v[212:215], v[14:17]
	v_mfma_f32_16x16x32_bf16 v[6:9], v[158:161], v[212:215], v[6:9]
	s_setprio 0
	s_setprio 1
	v_mfma_f32_16x16x32_bf16 v[58:61], v[162:165], v[178:181], v[58:61]
	v_mfma_f32_16x16x32_bf16 v[50:53], v[170:173], v[178:181], v[50:53]
	v_mfma_f32_16x16x32_bf16 v[42:45], v[162:165], v[186:189], v[42:45]
	v_mfma_f32_16x16x32_bf16 v[34:37], v[170:173], v[186:189], v[34:37]
	v_mfma_f32_16x16x32_bf16 v[26:29], v[162:165], v[194:197], v[26:29]
	v_mfma_f32_16x16x32_bf16 v[18:21], v[170:173], v[194:197], v[18:21]
	v_mfma_f32_16x16x32_bf16 v[10:13], v[162:165], v[208:211], v[10:13]
	v_mfma_f32_16x16x32_bf16 v[2:5], v[170:173], v[208:211], v[2:5]
	v_mfma_f32_16x16x32_bf16 v[58:61], v[166:169], v[182:185], v[58:61]
	v_mfma_f32_16x16x32_bf16 v[50:53], v[174:177], v[182:185], v[50:53]
	v_mfma_f32_16x16x32_bf16 v[42:45], v[166:169], v[190:193], v[42:45]
	v_mfma_f32_16x16x32_bf16 v[34:37], v[174:177], v[190:193], v[34:37]
	v_mfma_f32_16x16x32_bf16 v[26:29], v[166:169], v[198:201], v[26:29]
	v_mfma_f32_16x16x32_bf16 v[18:21], v[174:177], v[198:201], v[18:21]
	v_mfma_f32_16x16x32_bf16 v[10:13], v[166:169], v[212:215], v[10:13]
	v_mfma_f32_16x16x32_bf16 v[2:5], v[174:177], v[212:215], v[2:5]
	s_barrier
	s_setprio 0
	s_add_i32 s33, 0, 0x18000
	s_add_i32 s55, 0, 0x1c000
	ds_read_b128 v[146:149], v143 offset:32768
	ds_read_b128 v[150:153], v143 offset:33792
	ds_read_b128 v[154:157], v143 offset:34816
	ds_read_b128 v[158:161], v143 offset:35840
	ds_read_b128 v[162:165], v143 offset:49152
	ds_read_b128 v[166:169], v143 offset:50176
	ds_read_b128 v[170:173], v143 offset:51200
	ds_read_b128 v[174:177], v143 offset:52224
	s_add_u32 s0, s22, 0x80000
	s_addc_u32 s1, s23, 0
	s_mov_b32 m0, s29
	ds_read_b128 v[178:181], v145 offset:32768
	ds_read_b128 v[182:185], v145 offset:33792
	ds_read_b128 v[186:189], v145 offset:34816
	ds_read_b128 v[190:193], v145 offset:35840
	ds_read_b128 v[194:197], v145 offset:36864
	ds_read_b128 v[198:201], v145 offset:37888
	ds_read_b128 v[208:211], v145 offset:38912
	ds_read_b128 v[212:215], v145 offset:39936
	global_load_lds_dwordx4 v134, s[0:1]
	s_mov_b32 m0, s30
	s_nop 0
	global_load_lds_dwordx4 v132, s[0:1]
	s_waitcnt vmcnt(8)
	s_waitcnt lgkmcnt(0)
	s_setprio 1
	s_barrier
	v_mfma_f32_16x16x32_bf16 v[126:129], v[146:149], v[178:181], v[126:129]
	v_mfma_f32_16x16x32_bf16 v[118:121], v[154:157], v[178:181], v[118:121]
	v_mfma_f32_16x16x32_bf16 v[110:113], v[146:149], v[186:189], v[110:113]
	v_mfma_f32_16x16x32_bf16 v[102:105], v[154:157], v[186:189], v[102:105]
	v_mfma_f32_16x16x32_bf16 v[94:97], v[146:149], v[194:197], v[94:97]
	v_mfma_f32_16x16x32_bf16 v[86:89], v[154:157], v[194:197], v[86:89]
	v_mfma_f32_16x16x32_bf16 v[78:81], v[146:149], v[208:211], v[78:81]
	v_mfma_f32_16x16x32_bf16 v[70:73], v[154:157], v[208:211], v[70:73]
	v_mfma_f32_16x16x32_bf16 v[126:129], v[150:153], v[182:185], v[126:129]
	v_mfma_f32_16x16x32_bf16 v[118:121], v[158:161], v[182:185], v[118:121]
	v_mfma_f32_16x16x32_bf16 v[110:113], v[150:153], v[190:193], v[110:113]
	v_mfma_f32_16x16x32_bf16 v[102:105], v[158:161], v[190:193], v[102:105]
	v_mfma_f32_16x16x32_bf16 v[94:97], v[150:153], v[198:201], v[94:97]
	v_mfma_f32_16x16x32_bf16 v[86:89], v[158:161], v[198:201], v[86:89]
	v_mfma_f32_16x16x32_bf16 v[78:81], v[150:153], v[212:215], v[78:81]
	v_mfma_f32_16x16x32_bf16 v[70:73], v[158:161], v[212:215], v[70:73]
	s_setprio 0
	s_setprio 1
	v_mfma_f32_16x16x32_bf16 v[122:125], v[162:165], v[178:181], v[122:125]
	v_mfma_f32_16x16x32_bf16 v[114:117], v[170:173], v[178:181], v[114:117]
	v_mfma_f32_16x16x32_bf16 v[106:109], v[162:165], v[186:189], v[106:109]
	v_mfma_f32_16x16x32_bf16 v[98:101], v[170:173], v[186:189], v[98:101]
	v_mfma_f32_16x16x32_bf16 v[90:93], v[162:165], v[194:197], v[90:93]
	v_mfma_f32_16x16x32_bf16 v[82:85], v[170:173], v[194:197], v[82:85]
	v_mfma_f32_16x16x32_bf16 v[74:77], v[162:165], v[208:211], v[74:77]
	v_mfma_f32_16x16x32_bf16 v[66:69], v[170:173], v[208:211], v[66:69]
	v_mfma_f32_16x16x32_bf16 v[122:125], v[166:169], v[182:185], v[122:125]
	v_mfma_f32_16x16x32_bf16 v[114:117], v[174:177], v[182:185], v[114:117]
	v_mfma_f32_16x16x32_bf16 v[106:109], v[166:169], v[190:193], v[106:109]
	v_mfma_f32_16x16x32_bf16 v[98:101], v[174:177], v[190:193], v[98:101]
	v_mfma_f32_16x16x32_bf16 v[90:93], v[166:169], v[198:201], v[90:93]
	v_mfma_f32_16x16x32_bf16 v[82:85], v[174:177], v[198:201], v[82:85]
	v_mfma_f32_16x16x32_bf16 v[74:77], v[166:169], v[212:215], v[74:77]
	v_mfma_f32_16x16x32_bf16 v[66:69], v[174:177], v[212:215], v[66:69]
	s_barrier
	s_setprio 0
	s_add_i32 s0, s33, s26
	s_add_u32 s100, s20, 0x80
	s_addc_u32 s101, s21, 0
	s_mov_b32 m0, s0
	ds_read_b128 v[178:181], v145 offset:49152
	ds_read_b128 v[182:185], v145 offset:50176
	ds_read_b128 v[186:189], v145 offset:51200
	ds_read_b128 v[190:193], v145 offset:52224
	ds_read_b128 v[194:197], v145 offset:53248
	ds_read_b128 v[198:201], v145 offset:54272
	ds_read_b128 v[208:211], v145 offset:55296
	ds_read_b128 v[212:215], v145 offset:56320
	global_load_lds_dwordx4 v202, s[100:101]
	s_add_i32 m0, s0, 0x2000
	s_add_u32 s100, s20, 0x80
	s_addc_u32 s101, s21, 0
	s_add_u32 s0, s20, 0x80080
	s_addc_u32 s1, s21, 0
	s_add_i32 s20, s55, s26
	global_load_lds_dwordx4 v130, s[100:101]
	s_mov_b32 m0, s20
	s_nop 0
	global_load_lds_dwordx4 v202, s[0:1]
	s_add_i32 m0, s20, 0x2000
	s_nop 0
	global_load_lds_dwordx4 v130, s[0:1]
	s_add_u32 s100, s22, 0x80
	s_addc_u32 s101, s23, 0
	s_mov_b32 m0, s31
	s_nop 0
	global_load_lds_dwordx4 v134, s[100:101]
	s_add_u32 s100, s22, 0x80
	s_addc_u32 s101, s23, 0
	s_mov_b32 m0, s34
	s_nop 0
	global_load_lds_dwordx4 v132, s[100:101]
	s_waitcnt vmcnt(8)
	s_waitcnt lgkmcnt(0)
	s_setprio 1
	s_barrier
	v_mfma_f32_16x16x32_bf16 v[62:65], v[146:149], v[178:181], v[62:65]
	v_mfma_f32_16x16x32_bf16 v[54:57], v[154:157], v[178:181], v[54:57]
	v_mfma_f32_16x16x32_bf16 v[46:49], v[146:149], v[186:189], v[46:49]
	v_mfma_f32_16x16x32_bf16 v[38:41], v[154:157], v[186:189], v[38:41]
	v_mfma_f32_16x16x32_bf16 v[30:33], v[146:149], v[194:197], v[30:33]
	v_mfma_f32_16x16x32_bf16 v[22:25], v[154:157], v[194:197], v[22:25]
	v_mfma_f32_16x16x32_bf16 v[14:17], v[146:149], v[208:211], v[14:17]
	v_mfma_f32_16x16x32_bf16 v[6:9], v[154:157], v[208:211], v[6:9]
	v_mfma_f32_16x16x32_bf16 v[62:65], v[150:153], v[182:185], v[62:65]
	v_mfma_f32_16x16x32_bf16 v[54:57], v[158:161], v[182:185], v[54:57]
	v_mfma_f32_16x16x32_bf16 v[46:49], v[150:153], v[190:193], v[46:49]
	v_mfma_f32_16x16x32_bf16 v[38:41], v[158:161], v[190:193], v[38:41]
	v_mfma_f32_16x16x32_bf16 v[30:33], v[150:153], v[198:201], v[30:33]
	v_mfma_f32_16x16x32_bf16 v[22:25], v[158:161], v[198:201], v[22:25]
	v_mfma_f32_16x16x32_bf16 v[14:17], v[150:153], v[212:215], v[14:17]
	v_mfma_f32_16x16x32_bf16 v[6:9], v[158:161], v[212:215], v[6:9]
	s_setprio 0
	s_setprio 1
	v_mfma_f32_16x16x32_bf16 v[58:61], v[162:165], v[178:181], v[58:61]
	v_mfma_f32_16x16x32_bf16 v[50:53], v[170:173], v[178:181], v[50:53]
	v_mfma_f32_16x16x32_bf16 v[42:45], v[162:165], v[186:189], v[42:45]
	v_mfma_f32_16x16x32_bf16 v[34:37], v[170:173], v[186:189], v[34:37]
	v_mfma_f32_16x16x32_bf16 v[26:29], v[162:165], v[194:197], v[26:29]
	v_mfma_f32_16x16x32_bf16 v[18:21], v[170:173], v[194:197], v[18:21]
	v_mfma_f32_16x16x32_bf16 v[10:13], v[162:165], v[208:211], v[10:13]
	v_mfma_f32_16x16x32_bf16 v[2:5], v[170:173], v[208:211], v[2:5]
	v_mfma_f32_16x16x32_bf16 v[58:61], v[166:169], v[182:185], v[58:61]
	v_mfma_f32_16x16x32_bf16 v[50:53], v[174:177], v[182:185], v[50:53]
	v_mfma_f32_16x16x32_bf16 v[42:45], v[166:169], v[190:193], v[42:45]
	v_mfma_f32_16x16x32_bf16 v[34:37], v[174:177], v[190:193], v[34:37]
	v_mfma_f32_16x16x32_bf16 v[26:29], v[166:169], v[198:201], v[26:29]
	v_mfma_f32_16x16x32_bf16 v[18:21], v[174:177], v[198:201], v[18:21]
	v_mfma_f32_16x16x32_bf16 v[10:13], v[166:169], v[212:215], v[10:13]
	v_mfma_f32_16x16x32_bf16 v[2:5], v[174:177], v[212:215], v[2:5]
	s_barrier
	s_setprio 0
	s_add_i32 s59, s59, 2
	s_add_u32 s18, s18, 0x100
	s_addc_u32 s19, s19, 0
	s_add_u32 s49, s49, 0x100
	s_addc_u32 s58, s58, 0
	s_cmp_gt_u32 s59, 29
	s_cbranch_scc0 .LBB0_837
	s_and_b64 vcc, exec, s[6:7]
	s_cbranch_vccz .LBB0_840
	s_barrier

.LBB0_956:
	s_add_u32 s29, s40, 0xa000
	v_lshrrev_b32_e32 v20, 1, v14
	v_readlane_b32 s4, v253, 52
	s_addc_u32 s30, s41, 0
	v_and_b32_e32 v20, 24, v20
	s_lshl_b32 s0, s0, 5
	v_mov_b32_e32 v213, v203
	v_readlane_b32 s5, v253, 53
	v_and_b32_e32 v15, 15, v14
	v_lshlrev_b32_e32 v21, 1, v20
	v_lshlrev_b32_e32 v14, 2, v14
	s_and_b32 s3, s0, 0x60
	s_add_i32 m0, s25, 0x18000
	v_lshl_add_u64 v[2:3], v[2:3], 0, s[80:81]
	v_lshl_add_u64 v[16:17], s[4:5], 0, v[212:213]
	v_mov_b32_e32 v211, v203
	v_lshl_or_b32 v204, s1, 6, v15
	v_lshl_or_b32 v15, v15, 6, v21
	s_lshl_b32 s1, s1, 13
	v_and_b32_e32 v14, 32, v14
	s_lshl_b32 s0, s3, 7
	s_waitcnt vmcnt(2)
	s_barrier
	global_load_lds_dwordx4 v[2:3], off
	v_lshl_add_u64 v[2:3], v[4:5], 0, s[80:81]
	s_add_i32 m0, s25, 0x1a000
	s_add_i32 s31, s25, 0x8000
	s_add_i32 s34, s25, 0xa000
	v_lshl_add_u64 v[18:19], s[4:5], 0, v[210:211]
	v_bitop3_b32 v205, v15, s0, v14 bitop3:0xde
	v_add_u32_e32 v205, 0x10000, v205
	global_load_lds_dwordx4 v[2:3], off
	v_lshl_add_u64 v[2:3], v[16:17], 0, s[80:81]
	s_mov_b32 m0, s31
	s_add_u32 s0, s16, 0x160080
	v_bitop3_b32 v21, v15, s1, v14 bitop3:0xde
	global_load_lds_dwordx4 v[2:3], off
	v_lshl_add_u64 v[2:3], v[18:19], 0, s[80:81]
	s_mov_b32 m0, s34
	s_addc_u32 s1, s17, 0
	global_load_lds_dwordx4 v[2:3], off
	s_add_i32 m0, s25, 0x1c000
	v_lshl_add_u64 v[2:3], s[0:1], 0, v[202:203]
	global_load_lds_dwordx4 v[2:3], off
	v_lshl_add_u64 v[2:3], s[0:1], 0, v[208:209]
	s_add_i32 m0, s25, 0x1e000
	v_or_b32_e32 v238, s3, v20
	global_load_lds_dwordx4 v[2:3], off
	s_movk_i32 s3, 0x1600
	s_cmpk_lt_u32 s2, 0x100
	v_lshrrev_b32_e32 v3, 1, v11
	v_mul_lo_u32 v2, v10, s3
	s_mov_b32 s2, 0x16000
	v_mad_u64_u32 v[2:3], s[0:1], v3, s2, v[2:3]
	v_or_b32_e32 v2, v2, v12
	v_add_lshl_u32 v2, v2, v13, 1
	v_mov_b32_e32 v3, v203
	s_mov_b64 s[6:7], 0x160080
	v_lshl_add_u64 v[214:215], v[2:3], 0, s[6:7]
	v_lshrrev_b32_e32 v3, 1, v6
	v_mul_lo_u32 v2, v7, s3
	v_mad_u64_u32 v[2:3], s[0:1], v3, s2, v[2:3]
	s_waitcnt vmcnt(6)
	v_or_b32_e32 v2, v2, v8
	v_add_lshl_u32 v2, v2, v9, 1
	v_mov_b32_e32 v3, v203
	v_readlane_b32 s0, v253, 50
	s_cselect_b64 s[10:11], -1, 0
	v_lshl_add_u64 v[216:217], v[2:3], 0, s[6:7]
	s_mov_b32 s35, 0
	v_add_u32_e32 v239, 0, v21
	v_readlane_b32 s39, v254, 44
	s_mov_b32 s38, s0
	s_mov_b64 s[2:3], s[4:5]
	s_barrier
	v_readlane_b32 s1, v253, 51
	s_branch .LBB0_959

.LBB0_970:
	s_add_u32 s16, s2, 0x100
	s_addc_u32 s17, s3, 0
	s_add_i32 s0, 0, 0x10000
	s_cmpk_eq_i32 s59, 0x54
	s_cselect_b32 s21, s7, s17
	s_cselect_b32 s20, s6, s16
	s_cselect_b32 s19, s15, s58
	s_cselect_b32 s18, s14, s49
	s_add_i32 s33, 0, 0x14000
	ds_read_b128 v[78:81], v205
	ds_read_b128 v[82:85], v205 offset:1024
	ds_read_b128 v[94:97], v205 offset:2048
	ds_read_b128 v[98:101], v205 offset:3072
	ds_read_b128 v[106:109], v205 offset:16384
	ds_read_b128 v[110:113], v205 offset:17408
	ds_read_b128 v[126:129], v205 offset:18432
	ds_read_b128 v[134:137], v205 offset:19456
	s_add_i32 m0, s25, 0xc000
	ds_read_b128 v[146:149], v239
	ds_read_b128 v[158:161], v239 offset:1024
	ds_read_b128 v[166:169], v239 offset:2048
	ds_read_b128 v[174:177], v239 offset:3072
	ds_read_b128 v[178:181], v239 offset:4096
	ds_read_b128 v[182:185], v239 offset:5120
	ds_read_b128 v[186:189], v239 offset:6144
	ds_read_b128 v[190:193], v239 offset:7168
	global_load_lds_dwordx4 v214, s[2:3]
	s_add_i32 m0, s25, 0xe000
	s_nop 0
	global_load_lds_dwordx4 v216, s[2:3]
	s_waitcnt vmcnt(8)
	s_waitcnt lgkmcnt(0)
	s_setprio 1
	s_barrier
	v_mfma_f32_16x16x32_bf16 v[170:173], v[78:81], v[146:149], v[170:173]
	v_mfma_f32_16x16x32_bf16 v[162:165], v[94:97], v[146:149], v[162:165]
	v_mfma_f32_16x16x32_bf16 v[142:145], v[78:81], v[166:169], v[142:145]
	v_mfma_f32_16x16x32_bf16 v[138:141], v[94:97], v[166:169], v[138:141]
	v_mfma_f32_16x16x32_bf16 v[118:121], v[78:81], v[178:181], v[118:121]
	v_mfma_f32_16x16x32_bf16 v[114:117], v[94:97], v[178:181], v[114:117]
	v_mfma_f32_16x16x32_bf16 v[86:89], v[78:81], v[186:189], v[86:89]
	v_mfma_f32_16x16x32_bf16 v[74:77], v[94:97], v[186:189], v[74:77]
	v_mfma_f32_16x16x32_bf16 v[170:173], v[82:85], v[158:161], v[170:173]
	v_mfma_f32_16x16x32_bf16 v[162:165], v[98:101], v[158:161], v[162:165]
	v_mfma_f32_16x16x32_bf16 v[142:145], v[82:85], v[174:177], v[142:145]
	v_mfma_f32_16x16x32_bf16 v[138:141], v[98:101], v[174:177], v[138:141]
	v_mfma_f32_16x16x32_bf16 v[118:121], v[82:85], v[182:185], v[118:121]
	v_mfma_f32_16x16x32_bf16 v[114:117], v[98:101], v[182:185], v[114:117]
	v_mfma_f32_16x16x32_bf16 v[86:89], v[82:85], v[190:193], v[86:89]
	v_mfma_f32_16x16x32_bf16 v[74:77], v[98:101], v[190:193], v[74:77]
	s_setprio 0
	s_setprio 1
	v_mfma_f32_16x16x32_bf16 v[154:157], v[106:109], v[146:149], v[154:157]
	v_mfma_f32_16x16x32_bf16 v[130:133], v[106:109], v[166:169], v[130:133]
	v_mfma_f32_16x16x32_bf16 v[122:125], v[126:129], v[166:169], v[122:125]
	v_mfma_f32_16x16x32_bf16 v[102:105], v[106:109], v[178:181], v[102:105]
	v_mfma_f32_16x16x32_bf16 v[90:93], v[126:129], v[178:181], v[90:93]
	v_mfma_f32_16x16x32_bf16 v[70:73], v[106:109], v[186:189], v[70:73]
	v_mfma_f32_16x16x32_bf16 v[66:69], v[126:129], v[186:189], v[66:69]
	v_mfma_f32_16x16x32_bf16 v[154:157], v[110:113], v[158:161], v[154:157]
	v_mfma_f32_16x16x32_bf16 v[146:149], v[126:129], v[146:149], v[150:153]
	v_mfma_f32_16x16x32_bf16 v[130:133], v[110:113], v[174:177], v[130:133]
	v_mfma_f32_16x16x32_bf16 v[122:125], v[134:137], v[174:177], v[122:125]
	v_mfma_f32_16x16x32_bf16 v[102:105], v[110:113], v[182:185], v[102:105]
	v_mfma_f32_16x16x32_bf16 v[90:93], v[134:137], v[182:185], v[90:93]
	v_mfma_f32_16x16x32_bf16 v[70:73], v[110:113], v[190:193], v[70:73]
	v_mfma_f32_16x16x32_bf16 v[66:69], v[134:137], v[190:193], v[66:69]
	v_mfma_f32_16x16x32_bf16 v[146:149], v[134:137], v[158:161], v[146:149]
	s_barrier
	s_setprio 0
	s_add_i32 s0, s0, s24
	s_mov_b32 m0, s0
	ds_read_b128 v[150:153], v239 offset:16384
	ds_read_b128 v[158:161], v239 offset:17408
	ds_read_b128 v[166:169], v239 offset:18432
	ds_read_b128 v[174:177], v239 offset:19456
	ds_read_b128 v[178:181], v239 offset:20480
	ds_read_b128 v[182:185], v239 offset:21504
	ds_read_b128 v[186:189], v239 offset:22528
	ds_read_b128 v[190:193], v239 offset:23552
	global_load_lds_dwordx4 v202, s[18:19]
	s_add_i32 m0, s0, 0x2000
	s_add_u32 s0, s18, 0x160000
	s_addc_u32 s1, s19, 0
	s_add_i32 s2, s33, s24
	global_load_lds_dwordx4 v208, s[18:19]
	s_mov_b32 m0, s2
	s_nop 0
	global_load_lds_dwordx4 v202, s[0:1]
	s_add_i32 m0, s2, 0x2000
	s_nop 0
	global_load_lds_dwordx4 v208, s[0:1]
	s_mov_b32 m0, s25
	s_nop 0
	global_load_lds_dwordx4 v212, s[20:21]
	s_mov_b32 m0, s26
	s_nop 0
	global_load_lds_dwordx4 v210, s[20:21]
	s_waitcnt vmcnt(8)
	s_waitcnt lgkmcnt(0)
	s_setprio 1
	s_barrier
	v_mfma_f32_16x16x32_bf16 v[62:65], v[78:81], v[150:153], v[62:65]
	v_mfma_f32_16x16x32_bf16 v[58:61], v[94:97], v[150:153], v[58:61]
	v_mfma_f32_16x16x32_bf16 v[46:49], v[78:81], v[166:169], v[46:49]
	v_mfma_f32_16x16x32_bf16 v[42:45], v[94:97], v[166:169], v[42:45]
	v_mfma_f32_16x16x32_bf16 v[30:33], v[78:81], v[178:181], v[30:33]
	v_mfma_f32_16x16x32_bf16 v[26:29], v[94:97], v[178:181], v[26:29]
	v_mfma_f32_16x16x32_bf16 v[14:17], v[78:81], v[186:189], v[14:17]
	v_mfma_f32_16x16x32_bf16 v[10:13], v[94:97], v[186:189], v[10:13]
	v_mfma_f32_16x16x32_bf16 v[62:65], v[82:85], v[158:161], v[62:65]
	v_mfma_f32_16x16x32_bf16 v[58:61], v[98:101], v[158:161], v[58:61]
	v_mfma_f32_16x16x32_bf16 v[46:49], v[82:85], v[174:177], v[46:49]
	v_mfma_f32_16x16x32_bf16 v[42:45], v[98:101], v[174:177], v[42:45]
	v_mfma_f32_16x16x32_bf16 v[30:33], v[82:85], v[182:185], v[30:33]
	v_mfma_f32_16x16x32_bf16 v[26:29], v[98:101], v[182:185], v[26:29]
	v_mfma_f32_16x16x32_bf16 v[14:17], v[82:85], v[190:193], v[14:17]
	v_mfma_f32_16x16x32_bf16 v[10:13], v[98:101], v[190:193], v[10:13]
	s_setprio 0
	s_setprio 1
	v_mfma_f32_16x16x32_bf16 v[54:57], v[106:109], v[150:153], v[54:57]
	v_mfma_f32_16x16x32_bf16 v[50:53], v[126:129], v[150:153], v[50:53]
	v_mfma_f32_16x16x32_bf16 v[38:41], v[106:109], v[166:169], v[38:41]
	v_mfma_f32_16x16x32_bf16 v[34:37], v[126:129], v[166:169], v[34:37]
	v_mfma_f32_16x16x32_bf16 v[22:25], v[106:109], v[178:181], v[22:25]
	v_mfma_f32_16x16x32_bf16 v[18:21], v[126:129], v[178:181], v[18:21]
	v_mfma_f32_16x16x32_bf16 v[6:9], v[106:109], v[186:189], v[6:9]
	v_mfma_f32_16x16x32_bf16 v[2:5], v[126:129], v[186:189], v[2:5]
	v_mfma_f32_16x16x32_bf16 v[54:57], v[110:113], v[158:161], v[54:57]
	v_mfma_f32_16x16x32_bf16 v[50:53], v[134:137], v[158:161], v[50:53]
	v_mfma_f32_16x16x32_bf16 v[38:41], v[110:113], v[174:177], v[38:41]
	v_mfma_f32_16x16x32_bf16 v[34:37], v[134:137], v[174:177], v[34:37]
	v_mfma_f32_16x16x32_bf16 v[22:25], v[110:113], v[182:185], v[22:25]
	v_mfma_f32_16x16x32_bf16 v[18:21], v[134:137], v[182:185], v[18:21]
	v_mfma_f32_16x16x32_bf16 v[6:9], v[110:113], v[190:193], v[6:9]
	v_mfma_f32_16x16x32_bf16 v[2:5], v[134:137], v[190:193], v[2:5]
	s_barrier
	s_setprio 0
	s_add_i32 s2, 0, 0x18000
	s_add_i32 s3, 0, 0x1c000
	ds_read_b128 v[78:81], v205 offset:32768
	ds_read_b128 v[82:85], v205 offset:33792
	ds_read_b128 v[94:97], v205 offset:34816
	ds_read_b128 v[98:101], v205 offset:35840
	ds_read_b128 v[106:109], v205 offset:49152
	ds_read_b128 v[110:113], v205 offset:50176
	ds_read_b128 v[126:129], v205 offset:51200
	ds_read_b128 v[134:137], v205 offset:52224
	s_add_u32 s0, s20, 0x160000
	s_addc_u32 s1, s21, 0
	s_mov_b32 m0, s27
	ds_read_b128 v[150:153], v239 offset:32768
	ds_read_b128 v[158:161], v239 offset:33792
	ds_read_b128 v[166:169], v239 offset:34816
	ds_read_b128 v[174:177], v239 offset:35840
	ds_read_b128 v[178:181], v239 offset:36864
	ds_read_b128 v[182:185], v239 offset:37888
	ds_read_b128 v[186:189], v239 offset:38912
	ds_read_b128 v[190:193], v239 offset:39936
	global_load_lds_dwordx4 v212, s[0:1]
	s_mov_b32 m0, s28
	s_nop 0
	global_load_lds_dwordx4 v210, s[0:1]
	s_waitcnt vmcnt(8)
	s_waitcnt lgkmcnt(0)
	s_setprio 1
	s_barrier
	v_mfma_f32_16x16x32_bf16 v[170:173], v[78:81], v[150:153], v[170:173]
	v_mfma_f32_16x16x32_bf16 v[162:165], v[94:97], v[150:153], v[162:165]
	v_mfma_f32_16x16x32_bf16 v[142:145], v[78:81], v[166:169], v[142:145]
	v_mfma_f32_16x16x32_bf16 v[138:141], v[94:97], v[166:169], v[138:141]
	v_mfma_f32_16x16x32_bf16 v[118:121], v[78:81], v[178:181], v[118:121]
	v_mfma_f32_16x16x32_bf16 v[114:117], v[94:97], v[178:181], v[114:117]
	v_mfma_f32_16x16x32_bf16 v[86:89], v[78:81], v[186:189], v[86:89]
	v_mfma_f32_16x16x32_bf16 v[74:77], v[94:97], v[186:189], v[74:77]
	v_mfma_f32_16x16x32_bf16 v[170:173], v[82:85], v[158:161], v[170:173]
	v_mfma_f32_16x16x32_bf16 v[162:165], v[98:101], v[158:161], v[162:165]
	v_mfma_f32_16x16x32_bf16 v[142:145], v[82:85], v[174:177], v[142:145]
	v_mfma_f32_16x16x32_bf16 v[138:141], v[98:101], v[174:177], v[138:141]
	v_mfma_f32_16x16x32_bf16 v[118:121], v[82:85], v[182:185], v[118:121]
	v_mfma_f32_16x16x32_bf16 v[114:117], v[98:101], v[182:185], v[114:117]
	v_mfma_f32_16x16x32_bf16 v[86:89], v[82:85], v[190:193], v[86:89]
	v_mfma_f32_16x16x32_bf16 v[74:77], v[98:101], v[190:193], v[74:77]
	s_setprio 0
	s_setprio 1
	v_mfma_f32_16x16x32_bf16 v[154:157], v[106:109], v[150:153], v[154:157]
	v_mfma_f32_16x16x32_bf16 v[146:149], v[126:129], v[150:153], v[146:149]
	v_mfma_f32_16x16x32_bf16 v[130:133], v[106:109], v[166:169], v[130:133]
	v_mfma_f32_16x16x32_bf16 v[122:125], v[126:129], v[166:169], v[122:125]
	v_mfma_f32_16x16x32_bf16 v[102:105], v[106:109], v[178:181], v[102:105]
	v_mfma_f32_16x16x32_bf16 v[90:93], v[126:129], v[178:181], v[90:93]
	v_mfma_f32_16x16x32_bf16 v[70:73], v[106:109], v[186:189], v[70:73]
	v_mfma_f32_16x16x32_bf16 v[66:69], v[126:129], v[186:189], v[66:69]
	v_mfma_f32_16x16x32_bf16 v[154:157], v[110:113], v[158:161], v[154:157]
	v_mfma_f32_16x16x32_bf16 v[150:153], v[134:137], v[158:161], v[146:149]
	v_mfma_f32_16x16x32_bf16 v[130:133], v[110:113], v[174:177], v[130:133]
	v_mfma_f32_16x16x32_bf16 v[122:125], v[134:137], v[174:177], v[122:125]
	v_mfma_f32_16x16x32_bf16 v[102:105], v[110:113], v[182:185], v[102:105]
	v_mfma_f32_16x16x32_bf16 v[90:93], v[134:137], v[182:185], v[90:93]
	v_mfma_f32_16x16x32_bf16 v[70:73], v[110:113], v[190:193], v[70:73]
	v_mfma_f32_16x16x32_bf16 v[66:69], v[134:137], v[190:193], v[66:69]
	s_barrier
	s_setprio 0
	s_add_i32 s0, s2, s24
	s_add_u32 s100, s18, 0x80
	s_addc_u32 s101, s19, 0
	s_mov_b32 m0, s0
	ds_read_b128 v[146:149], v239 offset:49152
	ds_read_b128 v[158:161], v239 offset:50176
	ds_read_b128 v[166:169], v239 offset:51200
	ds_read_b128 v[174:177], v239 offset:52224
	ds_read_b128 v[178:181], v239 offset:53248
	ds_read_b128 v[182:185], v239 offset:54272
	ds_read_b128 v[186:189], v239 offset:55296
	ds_read_b128 v[190:193], v239 offset:56320
	global_load_lds_dwordx4 v202, s[100:101]
	s_add_i32 m0, s0, 0x2000
	s_add_u32 s100, s18, 0x80
	s_addc_u32 s101, s19, 0
	s_add_u32 s0, s18, 0x160080
	s_addc_u32 s1, s19, 0
	s_add_i32 s2, s3, s24
	global_load_lds_dwordx4 v208, s[100:101]
	s_mov_b32 m0, s2
	s_nop 0
	global_load_lds_dwordx4 v202, s[0:1]
	s_add_i32 m0, s2, 0x2000
	s_nop 0
	global_load_lds_dwordx4 v208, s[0:1]
	s_add_u32 s100, s20, 0x80
	s_addc_u32 s101, s21, 0
	s_mov_b32 m0, s31
	s_nop 0
	global_load_lds_dwordx4 v212, s[100:101]
	s_add_u32 s100, s20, 0x80
	s_addc_u32 s101, s21, 0
	s_mov_b32 m0, s34
	s_nop 0
	global_load_lds_dwordx4 v210, s[100:101]
	s_waitcnt vmcnt(8)
	s_waitcnt lgkmcnt(0)
	s_setprio 1
	s_barrier
	v_mfma_f32_16x16x32_bf16 v[62:65], v[78:81], v[146:149], v[62:65]
	v_mfma_f32_16x16x32_bf16 v[58:61], v[94:97], v[146:149], v[58:61]
	v_mfma_f32_16x16x32_bf16 v[46:49], v[78:81], v[166:169], v[46:49]
	v_mfma_f32_16x16x32_bf16 v[42:45], v[94:97], v[166:169], v[42:45]
	v_mfma_f32_16x16x32_bf16 v[30:33], v[78:81], v[178:181], v[30:33]
	v_mfma_f32_16x16x32_bf16 v[26:29], v[94:97], v[178:181], v[26:29]
	v_mfma_f32_16x16x32_bf16 v[14:17], v[78:81], v[186:189], v[14:17]
	v_mfma_f32_16x16x32_bf16 v[10:13], v[94:97], v[186:189], v[10:13]
	v_mfma_f32_16x16x32_bf16 v[62:65], v[82:85], v[158:161], v[62:65]
	v_mfma_f32_16x16x32_bf16 v[58:61], v[98:101], v[158:161], v[58:61]
	v_mfma_f32_16x16x32_bf16 v[46:49], v[82:85], v[174:177], v[46:49]
	v_mfma_f32_16x16x32_bf16 v[42:45], v[98:101], v[174:177], v[42:45]
	v_mfma_f32_16x16x32_bf16 v[30:33], v[82:85], v[182:185], v[30:33]
	v_mfma_f32_16x16x32_bf16 v[26:29], v[98:101], v[182:185], v[26:29]
	v_mfma_f32_16x16x32_bf16 v[14:17], v[82:85], v[190:193], v[14:17]
	v_mfma_f32_16x16x32_bf16 v[10:13], v[98:101], v[190:193], v[10:13]
	s_setprio 0
	s_setprio 1
	v_mfma_f32_16x16x32_bf16 v[54:57], v[106:109], v[146:149], v[54:57]
	v_mfma_f32_16x16x32_bf16 v[50:53], v[126:129], v[146:149], v[50:53]
	v_mfma_f32_16x16x32_bf16 v[38:41], v[106:109], v[166:169], v[38:41]
	v_mfma_f32_16x16x32_bf16 v[34:37], v[126:129], v[166:169], v[34:37]
	v_mfma_f32_16x16x32_bf16 v[22:25], v[106:109], v[178:181], v[22:25]
	v_mfma_f32_16x16x32_bf16 v[18:21], v[126:129], v[178:181], v[18:21]
	v_mfma_f32_16x16x32_bf16 v[6:9], v[106:109], v[186:189], v[6:9]
	v_mfma_f32_16x16x32_bf16 v[2:5], v[126:129], v[186:189], v[2:5]
	v_mfma_f32_16x16x32_bf16 v[54:57], v[110:113], v[158:161], v[54:57]
	v_mfma_f32_16x16x32_bf16 v[50:53], v[134:137], v[158:161], v[50:53]
	v_mfma_f32_16x16x32_bf16 v[38:41], v[110:113], v[174:177], v[38:41]
	v_mfma_f32_16x16x32_bf16 v[34:37], v[134:137], v[174:177], v[34:37]
	v_mfma_f32_16x16x32_bf16 v[22:25], v[110:113], v[182:185], v[22:25]
	v_mfma_f32_16x16x32_bf16 v[18:21], v[134:137], v[182:185], v[18:21]
	v_mfma_f32_16x16x32_bf16 v[6:9], v[110:113], v[190:193], v[6:9]
	v_mfma_f32_16x16x32_bf16 v[2:5], v[134:137], v[190:193], v[2:5]
	s_barrier
	s_setprio 0
	s_add_i32 s59, s59, 2
	s_add_u32 s49, s49, 0x100
	s_addc_u32 s58, s58, 0
	s_cmpk_gt_u32 s59, 0x55
	s_mov_b64 s[2:3], s[16:17]
	s_cbranch_scc0 .LBB0_970
	s_and_b64 vcc, exec, s[10:11]
	s_cbranch_vccz .LBB0_973
	s_barrier

.LBB0_980:
	v_bfe_u32 v20, v14, 4, 2
	s_lshl_b32 s0, s0, 5
	v_and_b32_e32 v15, 15, v14
	v_lshlrev_b32_e32 v22, 4, v20
	v_lshlrev_b32_e32 v14, 2, v14
	s_and_b32 s3, s0, 0x60
	v_lshl_or_b32 v21, s1, 6, v15
	v_lshl_or_b32 v15, v15, 6, v22
	s_lshl_b32 s1, s1, 13
	v_and_b32_e32 v14, 32, v14
	s_lshl_b32 s0, s3, 7
	v_readlane_b32 s6, v253, 18
	v_bitop3_b32 v136, v15, s0, v14 bitop3:0xde
	v_add_u32_e32 v136, 0x10000, v136
	s_add_u32 s0, s4, 0x160080
	v_readlane_b32 s7, v253, 19
	v_bitop3_b32 v22, v15, s1, v14 bitop3:0xde
	s_addc_u32 s1, s5, 0
	s_add_i32 m0, s25, 0x18000
	v_lshl_add_u64 v[2:3], v[2:3], 0, s[80:81]
	v_lshl_add_u64 v[16:17], s[6:7], 0, v[202:203]
	s_waitcnt vmcnt(2)
	s_barrier
	global_load_lds_dwordx4 v[2:3], off
	v_lshl_add_u64 v[2:3], v[4:5], 0, s[80:81]
	s_add_i32 m0, s25, 0x1a000
	s_add_i32 s29, s25, 0x8000
	v_lshl_add_u64 v[18:19], s[6:7], 0, v[130:131]
	global_load_lds_dwordx4 v[2:3], off
	v_lshl_add_u64 v[2:3], v[16:17], 0, s[80:81]
	s_mov_b32 m0, s29
	s_add_i32 s30, s25, 0xa000
	global_load_lds_dwordx4 v[2:3], off
	v_lshl_add_u64 v[2:3], v[18:19], 0, s[80:81]
	s_mov_b32 m0, s30
	v_lshl_or_b32 v138, v20, 2, s3
	global_load_lds_dwordx4 v[2:3], off
	s_add_i32 m0, s25, 0x1c000
	v_lshl_add_u64 v[2:3], s[0:1], 0, v[202:203]
	global_load_lds_dwordx4 v[2:3], off
	v_lshl_add_u64 v[2:3], s[0:1], 0, v[130:131]
	s_add_i32 m0, s25, 0x1e000
	s_movk_i32 s3, 0x1600
	global_load_lds_dwordx4 v[2:3], off
	s_cmpk_lt_u32 s2, 0x100
	v_lshrrev_b32_e32 v3, 1, v11
	v_mul_lo_u32 v2, v13, s3
	s_mov_b32 s2, 0x16000
	v_mad_u64_u32 v[2:3], s[0:1], v3, s2, v[2:3]
	v_or_b32_e32 v2, v2, v10
	v_add_lshl_u32 v2, v2, v12, 1
	v_mov_b32_e32 v3, v203
	s_mov_b64 s[14:15], 0x160080
	v_lshl_add_u64 v[132:133], v[2:3], 0, s[14:15]
	v_lshrrev_b32_e32 v3, 1, v7
	v_mul_lo_u32 v2, v9, s3
	v_mad_u64_u32 v[2:3], s[0:1], v3, s2, v[2:3]
	s_waitcnt vmcnt(6)
	v_or_b32_e32 v2, v2, v6
	v_add_lshl_u32 v2, v2, v8, 1
	v_mov_b32_e32 v3, v203
	s_cselect_b64 s[10:11], -1, 0
	v_add_u32_e32 v137, 0xffffc000, v21
	v_lshl_add_u64 v[134:135], v[2:3], 0, s[14:15]
	s_mov_b32 s31, 0
	v_add_u32_e32 v139, 0, v22
	v_readlane_b32 s38, v253, 16
	v_readlane_b32 s39, v254, 41
	v_readlane_b32 s37, v253, 13
	s_mov_b64 s[2:3], s[6:7]
	s_barrier
	s_branch .LBB0_983

.LBB0_990:
	s_add_u32 s4, s2, 0x100
	s_addc_u32 s5, s3, 0
	s_add_i32 s0, 0, 0x10000
	s_cmp_eq_u32 s59, 4
	s_cselect_b32 s21, s15, s5
	s_cselect_b32 s20, s14, s4
	s_cselect_b32 s19, s17, s58
	s_cselect_b32 s18, s16, s49
	s_add_i32 s33, 0, 0x14000
	ds_read_b128 v[140:143], v136
	ds_read_b128 v[144:147], v136 offset:1024
	ds_read_b128 v[148:151], v136 offset:2048
	ds_read_b128 v[152:155], v136 offset:3072
	ds_read_b128 v[156:159], v136 offset:16384
	ds_read_b128 v[160:163], v136 offset:17408
	ds_read_b128 v[164:167], v136 offset:18432
	ds_read_b128 v[168:171], v136 offset:19456
	s_add_i32 m0, s25, 0xc000
	ds_read_b128 v[172:175], v139
	ds_read_b128 v[176:179], v139 offset:1024
	ds_read_b128 v[180:183], v139 offset:2048
	ds_read_b128 v[184:187], v139 offset:3072
	ds_read_b128 v[188:191], v139 offset:4096
	ds_read_b128 v[192:195], v139 offset:5120
	ds_read_b128 v[196:199], v139 offset:6144
	ds_read_b128 v[208:211], v139 offset:7168
	global_load_lds_dwordx4 v132, s[2:3]
	s_add_i32 m0, s25, 0xe000
	s_nop 0
	global_load_lds_dwordx4 v134, s[2:3]
	s_waitcnt vmcnt(8)
	s_waitcnt lgkmcnt(0)
	s_setprio 1
	s_barrier
	v_mfma_f32_16x16x32_bf16 v[126:129], v[140:143], v[172:175], v[126:129]
	v_mfma_f32_16x16x32_bf16 v[122:125], v[148:151], v[172:175], v[122:125]
	v_mfma_f32_16x16x32_bf16 v[118:121], v[140:143], v[180:183], v[118:121]
	v_mfma_f32_16x16x32_bf16 v[114:117], v[148:151], v[180:183], v[114:117]
	v_mfma_f32_16x16x32_bf16 v[106:109], v[140:143], v[188:191], v[106:109]
	v_mfma_f32_16x16x32_bf16 v[98:101], v[148:151], v[188:191], v[98:101]
	v_mfma_f32_16x16x32_bf16 v[90:93], v[140:143], v[196:199], v[90:93]
	v_mfma_f32_16x16x32_bf16 v[82:85], v[148:151], v[196:199], v[82:85]
	v_mfma_f32_16x16x32_bf16 v[126:129], v[144:147], v[176:179], v[126:129]
	v_mfma_f32_16x16x32_bf16 v[122:125], v[152:155], v[176:179], v[122:125]
	v_mfma_f32_16x16x32_bf16 v[118:121], v[144:147], v[184:187], v[118:121]
	v_mfma_f32_16x16x32_bf16 v[114:117], v[152:155], v[184:187], v[114:117]
	v_mfma_f32_16x16x32_bf16 v[106:109], v[144:147], v[192:195], v[106:109]
	v_mfma_f32_16x16x32_bf16 v[98:101], v[152:155], v[192:195], v[98:101]
	v_mfma_f32_16x16x32_bf16 v[90:93], v[144:147], v[208:211], v[90:93]
	v_mfma_f32_16x16x32_bf16 v[82:85], v[152:155], v[208:211], v[82:85]
	s_setprio 0
	s_setprio 1
	v_mfma_f32_16x16x32_bf16 v[110:113], v[156:159], v[172:175], v[110:113]
	v_mfma_f32_16x16x32_bf16 v[102:105], v[164:167], v[172:175], v[102:105]
	v_mfma_f32_16x16x32_bf16 v[94:97], v[156:159], v[180:183], v[94:97]
	v_mfma_f32_16x16x32_bf16 v[86:89], v[164:167], v[180:183], v[86:89]
	v_mfma_f32_16x16x32_bf16 v[78:81], v[156:159], v[188:191], v[78:81]
	v_mfma_f32_16x16x32_bf16 v[74:77], v[164:167], v[188:191], v[74:77]
	v_mfma_f32_16x16x32_bf16 v[70:73], v[156:159], v[196:199], v[70:73]
	v_mfma_f32_16x16x32_bf16 v[66:69], v[164:167], v[196:199], v[66:69]
	v_mfma_f32_16x16x32_bf16 v[110:113], v[160:163], v[176:179], v[110:113]
	v_mfma_f32_16x16x32_bf16 v[102:105], v[168:171], v[176:179], v[102:105]
	v_mfma_f32_16x16x32_bf16 v[94:97], v[160:163], v[184:187], v[94:97]
	v_mfma_f32_16x16x32_bf16 v[86:89], v[168:171], v[184:187], v[86:89]
	v_mfma_f32_16x16x32_bf16 v[78:81], v[160:163], v[192:195], v[78:81]
	v_mfma_f32_16x16x32_bf16 v[74:77], v[168:171], v[192:195], v[74:77]
	v_mfma_f32_16x16x32_bf16 v[70:73], v[160:163], v[208:211], v[70:73]
	v_mfma_f32_16x16x32_bf16 v[66:69], v[168:171], v[208:211], v[66:69]
	s_barrier
	s_setprio 0
	s_add_i32 s0, s0, s24
	s_mov_b32 m0, s0
	ds_read_b128 v[172:175], v139 offset:16384
	ds_read_b128 v[176:179], v139 offset:17408
	ds_read_b128 v[180:183], v139 offset:18432
	ds_read_b128 v[184:187], v139 offset:19456
	ds_read_b128 v[188:191], v139 offset:20480
	ds_read_b128 v[192:195], v139 offset:21504
	ds_read_b128 v[196:199], v139 offset:22528
	ds_read_b128 v[208:211], v139 offset:23552
	global_load_lds_dwordx4 v202, s[18:19]
	s_add_i32 m0, s0, 0x2000
	s_add_u32 s0, s18, 0x160000
	s_addc_u32 s1, s19, 0
	s_add_i32 s2, s33, s24
	global_load_lds_dwordx4 v130, s[18:19]
	s_mov_b32 m0, s2
	s_nop 0
	global_load_lds_dwordx4 v202, s[0:1]
	s_add_i32 m0, s2, 0x2000
	s_nop 0
	global_load_lds_dwordx4 v130, s[0:1]
	s_mov_b32 m0, s25
	s_nop 0
	global_load_lds_dwordx4 v202, s[20:21]
	s_mov_b32 m0, s26
	s_nop 0
	global_load_lds_dwordx4 v130, s[20:21]
	s_waitcnt vmcnt(8)
	s_waitcnt lgkmcnt(0)
	s_setprio 1
	s_barrier
	v_mfma_f32_16x16x32_bf16 v[62:65], v[140:143], v[172:175], v[62:65]
	v_mfma_f32_16x16x32_bf16 v[58:61], v[148:151], v[172:175], v[58:61]
	v_mfma_f32_16x16x32_bf16 v[54:57], v[140:143], v[180:183], v[54:57]
	v_mfma_f32_16x16x32_bf16 v[50:53], v[148:151], v[180:183], v[50:53]
	v_mfma_f32_16x16x32_bf16 v[38:41], v[140:143], v[188:191], v[38:41]
	v_mfma_f32_16x16x32_bf16 v[34:37], v[148:151], v[188:191], v[34:37]
	v_mfma_f32_16x16x32_bf16 v[22:25], v[140:143], v[196:199], v[22:25]
	v_mfma_f32_16x16x32_bf16 v[18:21], v[148:151], v[196:199], v[18:21]
	v_mfma_f32_16x16x32_bf16 v[62:65], v[144:147], v[176:179], v[62:65]
	v_mfma_f32_16x16x32_bf16 v[58:61], v[152:155], v[176:179], v[58:61]
	v_mfma_f32_16x16x32_bf16 v[54:57], v[144:147], v[184:187], v[54:57]
	v_mfma_f32_16x16x32_bf16 v[50:53], v[152:155], v[184:187], v[50:53]
	v_mfma_f32_16x16x32_bf16 v[38:41], v[144:147], v[192:195], v[38:41]
	v_mfma_f32_16x16x32_bf16 v[34:37], v[152:155], v[192:195], v[34:37]
	v_mfma_f32_16x16x32_bf16 v[22:25], v[144:147], v[208:211], v[22:25]
	v_mfma_f32_16x16x32_bf16 v[18:21], v[152:155], v[208:211], v[18:21]
	s_setprio 0
	s_setprio 1
	v_mfma_f32_16x16x32_bf16 v[46:49], v[156:159], v[172:175], v[46:49]
	v_mfma_f32_16x16x32_bf16 v[42:45], v[164:167], v[172:175], v[42:45]
	v_mfma_f32_16x16x32_bf16 v[30:33], v[156:159], v[180:183], v[30:33]
	v_mfma_f32_16x16x32_bf16 v[26:29], v[164:167], v[180:183], v[26:29]
	v_mfma_f32_16x16x32_bf16 v[14:17], v[156:159], v[188:191], v[14:17]
	v_mfma_f32_16x16x32_bf16 v[10:13], v[164:167], v[188:191], v[10:13]
	v_mfma_f32_16x16x32_bf16 v[6:9], v[156:159], v[196:199], v[6:9]
	v_mfma_f32_16x16x32_bf16 v[2:5], v[164:167], v[196:199], v[2:5]
	v_mfma_f32_16x16x32_bf16 v[46:49], v[160:163], v[176:179], v[46:49]
	v_mfma_f32_16x16x32_bf16 v[42:45], v[168:171], v[176:179], v[42:45]
	v_mfma_f32_16x16x32_bf16 v[30:33], v[160:163], v[184:187], v[30:33]
	v_mfma_f32_16x16x32_bf16 v[26:29], v[168:171], v[184:187], v[26:29]
	v_mfma_f32_16x16x32_bf16 v[14:17], v[160:163], v[192:195], v[14:17]
	v_mfma_f32_16x16x32_bf16 v[10:13], v[168:171], v[192:195], v[10:13]
	v_mfma_f32_16x16x32_bf16 v[6:9], v[160:163], v[208:211], v[6:9]
	v_mfma_f32_16x16x32_bf16 v[2:5], v[168:171], v[208:211], v[2:5]
	s_barrier
	s_setprio 0
	s_add_i32 s2, 0, 0x18000
	s_add_i32 s3, 0, 0x1c000
	ds_read_b128 v[140:143], v136 offset:32768
	ds_read_b128 v[144:147], v136 offset:33792
	ds_read_b128 v[148:151], v136 offset:34816
	ds_read_b128 v[152:155], v136 offset:35840
	ds_read_b128 v[156:159], v136 offset:49152
	ds_read_b128 v[160:163], v136 offset:50176
	ds_read_b128 v[164:167], v136 offset:51200
	ds_read_b128 v[168:171], v136 offset:52224
	s_add_u32 s0, s20, 0x160000
	s_addc_u32 s1, s21, 0
	s_mov_b32 m0, s27
	ds_read_b128 v[172:175], v139 offset:32768
	ds_read_b128 v[176:179], v139 offset:33792
	ds_read_b128 v[180:183], v139 offset:34816
	ds_read_b128 v[184:187], v139 offset:35840
	ds_read_b128 v[188:191], v139 offset:36864
	ds_read_b128 v[192:195], v139 offset:37888
	ds_read_b128 v[196:199], v139 offset:38912
	ds_read_b128 v[208:211], v139 offset:39936
	global_load_lds_dwordx4 v202, s[0:1]
	s_mov_b32 m0, s28
	s_nop 0
	global_load_lds_dwordx4 v130, s[0:1]
	s_waitcnt vmcnt(8)
	s_waitcnt lgkmcnt(0)
	s_setprio 1
	s_barrier
	v_mfma_f32_16x16x32_bf16 v[126:129], v[140:143], v[172:175], v[126:129]
	v_mfma_f32_16x16x32_bf16 v[122:125], v[148:151], v[172:175], v[122:125]
	v_mfma_f32_16x16x32_bf16 v[118:121], v[140:143], v[180:183], v[118:121]
	v_mfma_f32_16x16x32_bf16 v[114:117], v[148:151], v[180:183], v[114:117]
	v_mfma_f32_16x16x32_bf16 v[106:109], v[140:143], v[188:191], v[106:109]
	v_mfma_f32_16x16x32_bf16 v[98:101], v[148:151], v[188:191], v[98:101]
	v_mfma_f32_16x16x32_bf16 v[90:93], v[140:143], v[196:199], v[90:93]
	v_mfma_f32_16x16x32_bf16 v[82:85], v[148:151], v[196:199], v[82:85]
	v_mfma_f32_16x16x32_bf16 v[126:129], v[144:147], v[176:179], v[126:129]
	v_mfma_f32_16x16x32_bf16 v[122:125], v[152:155], v[176:179], v[122:125]
	v_mfma_f32_16x16x32_bf16 v[118:121], v[144:147], v[184:187], v[118:121]
	v_mfma_f32_16x16x32_bf16 v[114:117], v[152:155], v[184:187], v[114:117]
	v_mfma_f32_16x16x32_bf16 v[106:109], v[144:147], v[192:195], v[106:109]
	v_mfma_f32_16x16x32_bf16 v[98:101], v[152:155], v[192:195], v[98:101]
	v_mfma_f32_16x16x32_bf16 v[90:93], v[144:147], v[208:211], v[90:93]
	v_mfma_f32_16x16x32_bf16 v[82:85], v[152:155], v[208:211], v[82:85]
	s_setprio 0
	s_setprio 1
	v_mfma_f32_16x16x32_bf16 v[110:113], v[156:159], v[172:175], v[110:113]
	v_mfma_f32_16x16x32_bf16 v[102:105], v[164:167], v[172:175], v[102:105]
	v_mfma_f32_16x16x32_bf16 v[94:97], v[156:159], v[180:183], v[94:97]
	v_mfma_f32_16x16x32_bf16 v[86:89], v[164:167], v[180:183], v[86:89]
	v_mfma_f32_16x16x32_bf16 v[78:81], v[156:159], v[188:191], v[78:81]
	v_mfma_f32_16x16x32_bf16 v[74:77], v[164:167], v[188:191], v[74:77]
	v_mfma_f32_16x16x32_bf16 v[70:73], v[156:159], v[196:199], v[70:73]
	v_mfma_f32_16x16x32_bf16 v[66:69], v[164:167], v[196:199], v[66:69]
	v_mfma_f32_16x16x32_bf16 v[110:113], v[160:163], v[176:179], v[110:113]
	v_mfma_f32_16x16x32_bf16 v[102:105], v[168:171], v[176:179], v[102:105]
	v_mfma_f32_16x16x32_bf16 v[94:97], v[160:163], v[184:187], v[94:97]
	v_mfma_f32_16x16x32_bf16 v[86:89], v[168:171], v[184:187], v[86:89]
	v_mfma_f32_16x16x32_bf16 v[78:81], v[160:163], v[192:195], v[78:81]
	v_mfma_f32_16x16x32_bf16 v[74:77], v[168:171], v[192:195], v[74:77]
	v_mfma_f32_16x16x32_bf16 v[70:73], v[160:163], v[208:211], v[70:73]
	v_mfma_f32_16x16x32_bf16 v[66:69], v[168:171], v[208:211], v[66:69]
	s_barrier
	s_setprio 0
	s_add_i32 s0, s2, s24
	s_add_u32 s100, s18, 0x80
	s_addc_u32 s101, s19, 0
	s_mov_b32 m0, s0
	ds_read_b128 v[172:175], v139 offset:49152
	ds_read_b128 v[176:179], v139 offset:50176
	ds_read_b128 v[180:183], v139 offset:51200
	ds_read_b128 v[184:187], v139 offset:52224
	ds_read_b128 v[188:191], v139 offset:53248
	ds_read_b128 v[192:195], v139 offset:54272
	ds_read_b128 v[196:199], v139 offset:55296
	ds_read_b128 v[208:211], v139 offset:56320
	global_load_lds_dwordx4 v202, s[100:101]
	s_add_i32 m0, s0, 0x2000
	s_add_u32 s100, s18, 0x80
	s_addc_u32 s101, s19, 0
	s_add_u32 s0, s18, 0x160080
	s_addc_u32 s1, s19, 0
	s_add_i32 s2, s3, s24
	global_load_lds_dwordx4 v130, s[100:101]
	s_mov_b32 m0, s2
	s_nop 0
	global_load_lds_dwordx4 v202, s[0:1]
	s_add_i32 m0, s2, 0x2000
	s_nop 0
	global_load_lds_dwordx4 v130, s[0:1]
	s_add_u32 s100, s20, 0x80
	s_addc_u32 s101, s21, 0
	s_mov_b32 m0, s29
	s_nop 0
	global_load_lds_dwordx4 v202, s[100:101]
	s_add_u32 s100, s20, 0x80
	s_addc_u32 s101, s21, 0
	s_mov_b32 m0, s30
	s_nop 0
	global_load_lds_dwordx4 v130, s[100:101]
	s_waitcnt vmcnt(8)
	s_waitcnt lgkmcnt(0)
	s_setprio 1
	s_barrier
	v_mfma_f32_16x16x32_bf16 v[62:65], v[140:143], v[172:175], v[62:65]
	v_mfma_f32_16x16x32_bf16 v[58:61], v[148:151], v[172:175], v[58:61]
	v_mfma_f32_16x16x32_bf16 v[54:57], v[140:143], v[180:183], v[54:57]
	v_mfma_f32_16x16x32_bf16 v[50:53], v[148:151], v[180:183], v[50:53]
	v_mfma_f32_16x16x32_bf16 v[38:41], v[140:143], v[188:191], v[38:41]
	v_mfma_f32_16x16x32_bf16 v[34:37], v[148:151], v[188:191], v[34:37]
	v_mfma_f32_16x16x32_bf16 v[22:25], v[140:143], v[196:199], v[22:25]
	v_mfma_f32_16x16x32_bf16 v[18:21], v[148:151], v[196:199], v[18:21]
	v_mfma_f32_16x16x32_bf16 v[62:65], v[144:147], v[176:179], v[62:65]
	v_mfma_f32_16x16x32_bf16 v[58:61], v[152:155], v[176:179], v[58:61]
	v_mfma_f32_16x16x32_bf16 v[54:57], v[144:147], v[184:187], v[54:57]
	v_mfma_f32_16x16x32_bf16 v[50:53], v[152:155], v[184:187], v[50:53]
	v_mfma_f32_16x16x32_bf16 v[38:41], v[144:147], v[192:195], v[38:41]
	v_mfma_f32_16x16x32_bf16 v[34:37], v[152:155], v[192:195], v[34:37]
	v_mfma_f32_16x16x32_bf16 v[22:25], v[144:147], v[208:211], v[22:25]
	v_mfma_f32_16x16x32_bf16 v[18:21], v[152:155], v[208:211], v[18:21]
	s_setprio 0
	s_setprio 1
	v_mfma_f32_16x16x32_bf16 v[46:49], v[156:159], v[172:175], v[46:49]
	v_mfma_f32_16x16x32_bf16 v[42:45], v[164:167], v[172:175], v[42:45]
	v_mfma_f32_16x16x32_bf16 v[30:33], v[156:159], v[180:183], v[30:33]
	v_mfma_f32_16x16x32_bf16 v[26:29], v[164:167], v[180:183], v[26:29]
	v_mfma_f32_16x16x32_bf16 v[14:17], v[156:159], v[188:191], v[14:17]
	v_mfma_f32_16x16x32_bf16 v[10:13], v[164:167], v[188:191], v[10:13]
	v_mfma_f32_16x16x32_bf16 v[6:9], v[156:159], v[196:199], v[6:9]
	v_mfma_f32_16x16x32_bf16 v[2:5], v[164:167], v[196:199], v[2:5]
	v_mfma_f32_16x16x32_bf16 v[46:49], v[160:163], v[176:179], v[46:49]
	v_mfma_f32_16x16x32_bf16 v[42:45], v[168:171], v[176:179], v[42:45]
	v_mfma_f32_16x16x32_bf16 v[30:33], v[160:163], v[184:187], v[30:33]
	v_mfma_f32_16x16x32_bf16 v[26:29], v[168:171], v[184:187], v[26:29]
	v_mfma_f32_16x16x32_bf16 v[14:17], v[160:163], v[192:195], v[14:17]
	v_mfma_f32_16x16x32_bf16 v[10:13], v[168:171], v[192:195], v[10:13]
	v_mfma_f32_16x16x32_bf16 v[6:9], v[160:163], v[208:211], v[6:9]
	v_mfma_f32_16x16x32_bf16 v[2:5], v[168:171], v[208:211], v[2:5]
	s_barrier
	s_setprio 0
	s_add_i32 s59, s59, 2
	s_add_u32 s49, s49, 0x100
	s_addc_u32 s58, s58, 0
	s_cmp_gt_u32 s59, 5
	s_mov_b64 s[2:3], s[4:5]
	s_cbranch_scc0 .LBB0_990
	s_and_b64 vcc, exec, s[10:11]
	s_cbranch_vccz .LBB0_993
	s_barrier

.LBB0_1109:
	v_lshrrev_b32_e32 v13, 1, v12
	v_readlane_b32 s6, v254, 15
	v_and_b32_e32 v18, 24, v13
	s_lshl_b32 s0, s0, 5
	v_mov_b32_e32 v137, v203
	v_readlane_b32 s7, v254, 16
	v_and_b32_e32 v144, 15, v12
	v_lshlrev_b32_e32 v19, 1, v18
	v_lshlrev_b32_e32 v12, 2, v12
	s_and_b32 s5, s0, 0x60
	s_add_i32 m0, s27, 0x18000
	v_lshl_add_u64 v[2:3], v[2:3], 0, s[80:81]
	v_lshl_add_u64 v[14:15], s[6:7], 0, v[136:137]
	v_mov_b32_e32 v133, v203
	s_lshl_b32 s31, s1, 6
	v_lshl_or_b32 v19, v144, 6, v19
	s_lshl_b32 s1, s1, 13
	v_and_b32_e32 v12, 32, v12
	s_lshl_b32 s0, s5, 7
	s_waitcnt vmcnt(2)
	s_barrier
	global_load_lds_dwordx4 v[2:3], off
	v_lshl_add_u64 v[2:3], v[4:5], 0, s[80:81]
	s_add_i32 m0, s27, 0x1a000
	s_add_i32 s34, s27, 0x8000
	s_add_i32 s35, s27, 0xa000
	v_lshl_add_u64 v[16:17], s[6:7], 0, v[132:133]
	v_bitop3_b32 v145, v19, s0, v12 bitop3:0xde
	v_add_u32_e32 v145, 0x10000, v145
	global_load_lds_dwordx4 v[2:3], off
	v_lshl_add_u64 v[2:3], v[14:15], 0, s[80:81]
	s_mov_b32 m0, s34
	s_add_u32 s0, s2, 0x80080
	v_bitop3_b32 v20, v19, s1, v12 bitop3:0xde
	global_load_lds_dwordx4 v[2:3], off
	v_lshl_add_u64 v[2:3], v[16:17], 0, s[80:81]
	s_mov_b32 m0, s35
	s_addc_u32 s1, s3, 0
	global_load_lds_dwordx4 v[2:3], off
	s_add_i32 m0, s27, 0x1c000
	v_lshl_add_u64 v[2:3], s[0:1], 0, v[134:135]
	global_load_lds_dwordx4 v[2:3], off
	v_lshl_add_u64 v[2:3], s[0:1], 0, v[130:131]
	s_add_i32 m0, s27, 0x1e000
	v_and_b32_e32 v5, 1, v10
	global_load_lds_dwordx4 v[2:3], off
	v_lshlrev_b32_e32 v3, 15, v10
	v_and_b32_e32 v3, 0xffff0000, v3
	v_lshl_add_u32 v3, v9, 12, v3
	v_lshl_or_b32 v3, v5, 6, v3
	v_lshl_add_u32 v138, v11, 1, v3
	v_lshlrev_b32_e32 v3, 15, v6
	v_and_b32_e32 v3, 0xffff0000, v3
	s_waitcnt vmcnt(6)
	v_lshl_add_u32 v3, v7, 12, v3
	v_and_b32_e32 v5, 1, v6
	s_cmpk_lt_u32 s4, 0x100
	v_and_b32_e32 v2, 8, v13
	v_lshlrev_b32_e32 v4, 4, v144
	v_lshl_or_b32 v3, v5, 6, v3
	v_readlane_b32 s0, v254, 11
	s_cselect_b64 s[10:11], -1, 0
	v_or_b32_e32 v146, s5, v18
	v_mov_b32_e32 v139, v203
	v_lshl_add_u32 v140, v8, 1, v3
	v_mov_b32_e32 v141, v203
	s_mov_b32 s36, 0
	v_add_u32_e32 v147, 0, v20
	v_lshlrev_b32_e32 v202, 1, v4
	v_lshlrev_b32_e32 v142, 1, v2
	v_readlane_b32 s37, v254, 14
	s_mov_b32 s38, s0
	s_mov_b64 s[4:5], s[6:7]
	s_barrier
	v_readlane_b32 s1, v254, 12
	s_waitcnt vmcnt(0)
	s_branch .LBB0_1112

.LBB0_1115:
	s_add_u32 s0, s22, 0xfff80080
	s_addc_u32 s1, s23, -1
	s_add_i32 s33, 0, 0x10000
	s_cmp_eq_u32 s58, 28
	s_cselect_b32 s5, s17, s1
	s_cselect_b32 s4, s39, s0
	s_cselect_b32 s3, s15, s49
	s_cselect_b32 s2, s40, s41
	s_add_i32 s55, 0, 0x14000
	ds_read_b128 v[148:151], v145
	ds_read_b128 v[152:155], v145 offset:1024
	ds_read_b128 v[156:159], v145 offset:2048
	ds_read_b128 v[160:163], v145 offset:3072
	ds_read_b128 v[164:167], v145 offset:16384
	ds_read_b128 v[168:171], v145 offset:17408
	ds_read_b128 v[172:175], v145 offset:18432
	ds_read_b128 v[176:179], v145 offset:19456
	s_add_i32 m0, s27, 0xc000
	ds_read_b128 v[180:183], v147
	ds_read_b128 v[184:187], v147 offset:1024
	ds_read_b128 v[188:191], v147 offset:2048
	ds_read_b128 v[192:195], v147 offset:3072
	ds_read_b128 v[196:199], v147 offset:4096
	ds_read_b128 v[208:211], v147 offset:5120
	ds_read_b128 v[212:215], v147 offset:6144
	ds_read_b128 v[216:219], v147 offset:7168
	global_load_lds_dwordx4 v138, s[22:23]
	s_add_i32 m0, s27, 0xe000
	s_nop 0
	global_load_lds_dwordx4 v140, s[22:23]
	s_waitcnt vmcnt(8)
	s_waitcnt lgkmcnt(0)
	s_setprio 1
	s_barrier
	v_mfma_f32_16x16x32_bf16 v[126:129], v[148:151], v[180:183], v[126:129]
	v_mfma_f32_16x16x32_bf16 v[122:125], v[156:159], v[180:183], v[122:125]
	v_mfma_f32_16x16x32_bf16 v[110:113], v[148:151], v[188:191], v[110:113]
	v_mfma_f32_16x16x32_bf16 v[106:109], v[156:159], v[188:191], v[106:109]
	v_mfma_f32_16x16x32_bf16 v[94:97], v[148:151], v[196:199], v[94:97]
	v_mfma_f32_16x16x32_bf16 v[90:93], v[156:159], v[196:199], v[90:93]
	v_mfma_f32_16x16x32_bf16 v[78:81], v[148:151], v[212:215], v[78:81]
	v_mfma_f32_16x16x32_bf16 v[74:77], v[156:159], v[212:215], v[74:77]
	v_mfma_f32_16x16x32_bf16 v[126:129], v[152:155], v[184:187], v[126:129]
	v_mfma_f32_16x16x32_bf16 v[122:125], v[160:163], v[184:187], v[122:125]
	v_mfma_f32_16x16x32_bf16 v[110:113], v[152:155], v[192:195], v[110:113]
	v_mfma_f32_16x16x32_bf16 v[106:109], v[160:163], v[192:195], v[106:109]
	v_mfma_f32_16x16x32_bf16 v[94:97], v[152:155], v[208:211], v[94:97]
	v_mfma_f32_16x16x32_bf16 v[90:93], v[160:163], v[208:211], v[90:93]
	v_mfma_f32_16x16x32_bf16 v[78:81], v[152:155], v[216:219], v[78:81]
	v_mfma_f32_16x16x32_bf16 v[74:77], v[160:163], v[216:219], v[74:77]
	s_setprio 0
	s_setprio 1
	v_mfma_f32_16x16x32_bf16 v[118:121], v[164:167], v[180:183], v[118:121]
	v_mfma_f32_16x16x32_bf16 v[114:117], v[172:175], v[180:183], v[114:117]
	v_mfma_f32_16x16x32_bf16 v[102:105], v[164:167], v[188:191], v[102:105]
	v_mfma_f32_16x16x32_bf16 v[98:101], v[172:175], v[188:191], v[98:101]
	v_mfma_f32_16x16x32_bf16 v[86:89], v[164:167], v[196:199], v[86:89]
	v_mfma_f32_16x16x32_bf16 v[82:85], v[172:175], v[196:199], v[82:85]
	v_mfma_f32_16x16x32_bf16 v[70:73], v[164:167], v[212:215], v[70:73]
	v_mfma_f32_16x16x32_bf16 v[66:69], v[172:175], v[212:215], v[66:69]
	v_mfma_f32_16x16x32_bf16 v[118:121], v[168:171], v[184:187], v[118:121]
	v_mfma_f32_16x16x32_bf16 v[114:117], v[176:179], v[184:187], v[114:117]
	v_mfma_f32_16x16x32_bf16 v[102:105], v[168:171], v[192:195], v[102:105]
	v_mfma_f32_16x16x32_bf16 v[98:101], v[176:179], v[192:195], v[98:101]
	v_mfma_f32_16x16x32_bf16 v[86:89], v[168:171], v[208:211], v[86:89]
	v_mfma_f32_16x16x32_bf16 v[82:85], v[176:179], v[208:211], v[82:85]
	v_mfma_f32_16x16x32_bf16 v[70:73], v[168:171], v[216:219], v[70:73]
	v_mfma_f32_16x16x32_bf16 v[66:69], v[176:179], v[216:219], v[66:69]
	s_barrier
	s_setprio 0
	s_add_i32 s0, s33, s26
	s_mov_b32 m0, s0
	ds_read_b128 v[180:183], v147 offset:16384
	ds_read_b128 v[184:187], v147 offset:17408
	ds_read_b128 v[188:191], v147 offset:18432
	ds_read_b128 v[192:195], v147 offset:19456
	ds_read_b128 v[196:199], v147 offset:20480
	ds_read_b128 v[208:211], v147 offset:21504
	ds_read_b128 v[212:215], v147 offset:22528
	ds_read_b128 v[216:219], v147 offset:23552
	global_load_lds_dwordx4 v134, s[2:3]
	s_add_i32 m0, s0, 0x2000
	s_add_u32 s0, s2, 0x80000
	s_addc_u32 s1, s3, 0
	s_add_i32 s33, s55, s26
	global_load_lds_dwordx4 v130, s[2:3]
	s_mov_b32 m0, s33
	s_nop 0
	global_load_lds_dwordx4 v134, s[0:1]
	s_add_i32 m0, s33, 0x2000
	s_nop 0
	global_load_lds_dwordx4 v130, s[0:1]
	s_mov_b32 m0, s27
	s_nop 0
	global_load_lds_dwordx4 v136, s[4:5]
	s_mov_b32 m0, s28
	s_nop 0
	global_load_lds_dwordx4 v132, s[4:5]
	s_waitcnt vmcnt(8)
	s_waitcnt lgkmcnt(0)
	s_setprio 1
	s_barrier
	v_mfma_f32_16x16x32_bf16 v[62:65], v[148:151], v[180:183], v[62:65]
	v_mfma_f32_16x16x32_bf16 v[58:61], v[156:159], v[180:183], v[58:61]
	v_mfma_f32_16x16x32_bf16 v[46:49], v[148:151], v[188:191], v[46:49]
	v_mfma_f32_16x16x32_bf16 v[42:45], v[156:159], v[188:191], v[42:45]
	v_mfma_f32_16x16x32_bf16 v[30:33], v[148:151], v[196:199], v[30:33]
	v_mfma_f32_16x16x32_bf16 v[26:29], v[156:159], v[196:199], v[26:29]
	v_mfma_f32_16x16x32_bf16 v[14:17], v[148:151], v[212:215], v[14:17]
	v_mfma_f32_16x16x32_bf16 v[10:13], v[156:159], v[212:215], v[10:13]
	v_mfma_f32_16x16x32_bf16 v[62:65], v[152:155], v[184:187], v[62:65]
	v_mfma_f32_16x16x32_bf16 v[58:61], v[160:163], v[184:187], v[58:61]
	v_mfma_f32_16x16x32_bf16 v[46:49], v[152:155], v[192:195], v[46:49]
	v_mfma_f32_16x16x32_bf16 v[42:45], v[160:163], v[192:195], v[42:45]
	v_mfma_f32_16x16x32_bf16 v[30:33], v[152:155], v[208:211], v[30:33]
	v_mfma_f32_16x16x32_bf16 v[26:29], v[160:163], v[208:211], v[26:29]
	v_mfma_f32_16x16x32_bf16 v[14:17], v[152:155], v[216:219], v[14:17]
	v_mfma_f32_16x16x32_bf16 v[10:13], v[160:163], v[216:219], v[10:13]
	s_setprio 0
	s_setprio 1
	v_mfma_f32_16x16x32_bf16 v[54:57], v[164:167], v[180:183], v[54:57]
	v_mfma_f32_16x16x32_bf16 v[50:53], v[172:175], v[180:183], v[50:53]
	v_mfma_f32_16x16x32_bf16 v[38:41], v[164:167], v[188:191], v[38:41]
	v_mfma_f32_16x16x32_bf16 v[34:37], v[172:175], v[188:191], v[34:37]
	v_mfma_f32_16x16x32_bf16 v[22:25], v[164:167], v[196:199], v[22:25]
	v_mfma_f32_16x16x32_bf16 v[18:21], v[172:175], v[196:199], v[18:21]
	v_mfma_f32_16x16x32_bf16 v[6:9], v[164:167], v[212:215], v[6:9]
	v_mfma_f32_16x16x32_bf16 v[2:5], v[172:175], v[212:215], v[2:5]
	v_mfma_f32_16x16x32_bf16 v[54:57], v[168:171], v[184:187], v[54:57]
	v_mfma_f32_16x16x32_bf16 v[50:53], v[176:179], v[184:187], v[50:53]
	v_mfma_f32_16x16x32_bf16 v[38:41], v[168:171], v[192:195], v[38:41]
	v_mfma_f32_16x16x32_bf16 v[34:37], v[176:179], v[192:195], v[34:37]
	v_mfma_f32_16x16x32_bf16 v[22:25], v[168:171], v[208:211], v[22:25]
	v_mfma_f32_16x16x32_bf16 v[18:21], v[176:179], v[208:211], v[18:21]
	v_mfma_f32_16x16x32_bf16 v[6:9], v[168:171], v[216:219], v[6:9]
	v_mfma_f32_16x16x32_bf16 v[2:5], v[176:179], v[216:219], v[2:5]
	s_barrier
	s_setprio 0
	s_add_i32 s33, 0, 0x18000
	s_add_i32 s55, 0, 0x1c000
	ds_read_b128 v[148:151], v145 offset:32768
	ds_read_b128 v[152:155], v145 offset:33792
	ds_read_b128 v[156:159], v145 offset:34816
	ds_read_b128 v[160:163], v145 offset:35840
	ds_read_b128 v[164:167], v145 offset:49152
	ds_read_b128 v[168:171], v145 offset:50176
	ds_read_b128 v[172:175], v145 offset:51200
	ds_read_b128 v[176:179], v145 offset:52224
	s_add_u32 s0, s4, 0x80000
	s_addc_u32 s1, s5, 0
	s_mov_b32 m0, s29
	ds_read_b128 v[180:183], v147 offset:32768
	ds_read_b128 v[184:187], v147 offset:33792
	ds_read_b128 v[188:191], v147 offset:34816
	ds_read_b128 v[192:195], v147 offset:35840
	ds_read_b128 v[196:199], v147 offset:36864
	ds_read_b128 v[208:211], v147 offset:37888
	ds_read_b128 v[212:215], v147 offset:38912
	ds_read_b128 v[216:219], v147 offset:39936
	global_load_lds_dwordx4 v136, s[0:1]
	s_mov_b32 m0, s30
	s_nop 0
	global_load_lds_dwordx4 v132, s[0:1]
	s_waitcnt vmcnt(8)
	s_waitcnt lgkmcnt(0)
	s_setprio 1
	s_barrier
	v_mfma_f32_16x16x32_bf16 v[126:129], v[148:151], v[180:183], v[126:129]
	v_mfma_f32_16x16x32_bf16 v[122:125], v[156:159], v[180:183], v[122:125]
	v_mfma_f32_16x16x32_bf16 v[110:113], v[148:151], v[188:191], v[110:113]
	v_mfma_f32_16x16x32_bf16 v[106:109], v[156:159], v[188:191], v[106:109]
	v_mfma_f32_16x16x32_bf16 v[94:97], v[148:151], v[196:199], v[94:97]
	v_mfma_f32_16x16x32_bf16 v[90:93], v[156:159], v[196:199], v[90:93]
	v_mfma_f32_16x16x32_bf16 v[78:81], v[148:151], v[212:215], v[78:81]
	v_mfma_f32_16x16x32_bf16 v[74:77], v[156:159], v[212:215], v[74:77]
	v_mfma_f32_16x16x32_bf16 v[126:129], v[152:155], v[184:187], v[126:129]
	v_mfma_f32_16x16x32_bf16 v[122:125], v[160:163], v[184:187], v[122:125]
	v_mfma_f32_16x16x32_bf16 v[110:113], v[152:155], v[192:195], v[110:113]
	v_mfma_f32_16x16x32_bf16 v[106:109], v[160:163], v[192:195], v[106:109]
	v_mfma_f32_16x16x32_bf16 v[94:97], v[152:155], v[208:211], v[94:97]
	v_mfma_f32_16x16x32_bf16 v[90:93], v[160:163], v[208:211], v[90:93]
	v_mfma_f32_16x16x32_bf16 v[78:81], v[152:155], v[216:219], v[78:81]
	v_mfma_f32_16x16x32_bf16 v[74:77], v[160:163], v[216:219], v[74:77]
	s_setprio 0
	s_setprio 1
	v_mfma_f32_16x16x32_bf16 v[118:121], v[164:167], v[180:183], v[118:121]
	v_mfma_f32_16x16x32_bf16 v[114:117], v[172:175], v[180:183], v[114:117]
	v_mfma_f32_16x16x32_bf16 v[102:105], v[164:167], v[188:191], v[102:105]
	v_mfma_f32_16x16x32_bf16 v[98:101], v[172:175], v[188:191], v[98:101]
	v_mfma_f32_16x16x32_bf16 v[86:89], v[164:167], v[196:199], v[86:89]
	v_mfma_f32_16x16x32_bf16 v[82:85], v[172:175], v[196:199], v[82:85]
	v_mfma_f32_16x16x32_bf16 v[70:73], v[164:167], v[212:215], v[70:73]
	v_mfma_f32_16x16x32_bf16 v[66:69], v[172:175], v[212:215], v[66:69]
	v_mfma_f32_16x16x32_bf16 v[118:121], v[168:171], v[184:187], v[118:121]
	v_mfma_f32_16x16x32_bf16 v[114:117], v[176:179], v[184:187], v[114:117]
	v_mfma_f32_16x16x32_bf16 v[102:105], v[168:171], v[192:195], v[102:105]
	v_mfma_f32_16x16x32_bf16 v[98:101], v[176:179], v[192:195], v[98:101]
	v_mfma_f32_16x16x32_bf16 v[86:89], v[168:171], v[208:211], v[86:89]
	v_mfma_f32_16x16x32_bf16 v[82:85], v[176:179], v[208:211], v[82:85]
	v_mfma_f32_16x16x32_bf16 v[70:73], v[168:171], v[216:219], v[70:73]
	v_mfma_f32_16x16x32_bf16 v[66:69], v[176:179], v[216:219], v[66:69]
	s_barrier
	s_setprio 0
	s_add_i32 s0, s33, s26
	s_add_u32 s100, s2, 0x80
	s_addc_u32 s101, s3, 0
	s_mov_b32 m0, s0
	ds_read_b128 v[180:183], v147 offset:49152
	ds_read_b128 v[184:187], v147 offset:50176
	ds_read_b128 v[188:191], v147 offset:51200
	ds_read_b128 v[192:195], v147 offset:52224
	ds_read_b128 v[196:199], v147 offset:53248
	ds_read_b128 v[208:211], v147 offset:54272
	ds_read_b128 v[212:215], v147 offset:55296
	ds_read_b128 v[216:219], v147 offset:56320
	global_load_lds_dwordx4 v134, s[100:101]
	s_add_i32 m0, s0, 0x2000
	s_add_u32 s100, s2, 0x80
	s_addc_u32 s101, s3, 0
	s_add_u32 s0, s2, 0x80080
	s_addc_u32 s1, s3, 0
	s_add_i32 s2, s55, s26
	global_load_lds_dwordx4 v130, s[100:101]
	s_mov_b32 m0, s2
	s_nop 0
	global_load_lds_dwordx4 v134, s[0:1]
	s_add_i32 m0, s2, 0x2000
	s_nop 0
	global_load_lds_dwordx4 v130, s[0:1]
	s_add_u32 s100, s4, 0x80
	s_addc_u32 s101, s5, 0
	s_mov_b32 m0, s34
	s_nop 0
	global_load_lds_dwordx4 v136, s[100:101]
	s_add_u32 s100, s4, 0x80
	s_addc_u32 s101, s5, 0
	s_mov_b32 m0, s35
	s_nop 0
	global_load_lds_dwordx4 v132, s[100:101]
	s_waitcnt vmcnt(8)
	s_waitcnt lgkmcnt(0)
	s_setprio 1
	s_barrier
	v_mfma_f32_16x16x32_bf16 v[62:65], v[148:151], v[180:183], v[62:65]
	v_mfma_f32_16x16x32_bf16 v[58:61], v[156:159], v[180:183], v[58:61]
	v_mfma_f32_16x16x32_bf16 v[46:49], v[148:151], v[188:191], v[46:49]
	v_mfma_f32_16x16x32_bf16 v[42:45], v[156:159], v[188:191], v[42:45]
	v_mfma_f32_16x16x32_bf16 v[30:33], v[148:151], v[196:199], v[30:33]
	v_mfma_f32_16x16x32_bf16 v[26:29], v[156:159], v[196:199], v[26:29]
	v_mfma_f32_16x16x32_bf16 v[14:17], v[148:151], v[212:215], v[14:17]
	v_mfma_f32_16x16x32_bf16 v[10:13], v[156:159], v[212:215], v[10:13]
	v_mfma_f32_16x16x32_bf16 v[62:65], v[152:155], v[184:187], v[62:65]
	v_mfma_f32_16x16x32_bf16 v[58:61], v[160:163], v[184:187], v[58:61]
	v_mfma_f32_16x16x32_bf16 v[46:49], v[152:155], v[192:195], v[46:49]
	v_mfma_f32_16x16x32_bf16 v[42:45], v[160:163], v[192:195], v[42:45]
	v_mfma_f32_16x16x32_bf16 v[30:33], v[152:155], v[208:211], v[30:33]
	v_mfma_f32_16x16x32_bf16 v[26:29], v[160:163], v[208:211], v[26:29]
	v_mfma_f32_16x16x32_bf16 v[14:17], v[152:155], v[216:219], v[14:17]
	v_mfma_f32_16x16x32_bf16 v[10:13], v[160:163], v[216:219], v[10:13]
	s_setprio 0
	s_setprio 1
	v_mfma_f32_16x16x32_bf16 v[54:57], v[164:167], v[180:183], v[54:57]
	v_mfma_f32_16x16x32_bf16 v[50:53], v[172:175], v[180:183], v[50:53]
	v_mfma_f32_16x16x32_bf16 v[38:41], v[164:167], v[188:191], v[38:41]
	v_mfma_f32_16x16x32_bf16 v[34:37], v[172:175], v[188:191], v[34:37]
	v_mfma_f32_16x16x32_bf16 v[22:25], v[164:167], v[196:199], v[22:25]
	v_mfma_f32_16x16x32_bf16 v[18:21], v[172:175], v[196:199], v[18:21]
	v_mfma_f32_16x16x32_bf16 v[6:9], v[164:167], v[212:215], v[6:9]
	v_mfma_f32_16x16x32_bf16 v[2:5], v[172:175], v[212:215], v[2:5]
	v_mfma_f32_16x16x32_bf16 v[54:57], v[168:171], v[184:187], v[54:57]
	v_mfma_f32_16x16x32_bf16 v[50:53], v[176:179], v[184:187], v[50:53]
	v_mfma_f32_16x16x32_bf16 v[38:41], v[168:171], v[192:195], v[38:41]
	v_mfma_f32_16x16x32_bf16 v[34:37], v[176:179], v[192:195], v[34:37]
	v_mfma_f32_16x16x32_bf16 v[22:25], v[168:171], v[208:211], v[22:25]
	v_mfma_f32_16x16x32_bf16 v[18:21], v[176:179], v[208:211], v[18:21]
	v_mfma_f32_16x16x32_bf16 v[6:9], v[168:171], v[216:219], v[6:9]
	v_mfma_f32_16x16x32_bf16 v[2:5], v[176:179], v[216:219], v[2:5]
	s_barrier
	s_setprio 0
	s_add_i32 s58, s58, 2
	s_add_u32 s22, s22, 0x100
	s_addc_u32 s23, s23, 0
	s_add_u32 s41, s41, 0x100
	s_addc_u32 s49, s49, 0
	s_cmp_gt_u32 s58, 29
	s_cbranch_scc0 .LBB0_1115
	s_and_b64 vcc, exec, s[10:11]
	s_cbranch_vccz .LBB0_1118
	s_barrier

.LBB0_1359:
	v_readlane_b32 s16, v253, 28
	s_add_u32 s4, s8, 0x20080
	v_mov_b32_e32 v137, v203
	v_readlane_b32 s17, v253, 29
	s_addc_u32 s5, s9, 0
	s_add_i32 m0, s25, 0x18000
	v_lshl_add_u64 v[2:3], v[2:3], 0, s[80:81]
	v_lshl_add_u64 v[14:15], s[16:17], 0, v[136:137]
	v_mov_b32_e32 v133, v203
	s_waitcnt vmcnt(2)
	s_barrier
	global_load_lds_dwordx4 v[2:3], off
	v_lshl_add_u64 v[2:3], v[4:5], 0, s[80:81]
	s_add_i32 m0, s25, 0x1a000
	s_add_i32 s29, s25, 0x8000
	v_lshl_add_u64 v[16:17], s[16:17], 0, v[132:133]
	global_load_lds_dwordx4 v[2:3], off
	v_lshl_add_u64 v[2:3], v[14:15], 0, s[80:81]
	s_mov_b32 m0, s29
	s_add_i32 s30, s25, 0xa000
	global_load_lds_dwordx4 v[2:3], off
	v_lshl_add_u64 v[2:3], v[16:17], 0, s[80:81]
	s_mov_b32 m0, s30
	v_lshrrev_b32_e32 v18, 1, v12
	global_load_lds_dwordx4 v[2:3], off
	s_add_i32 m0, s25, 0x1c000
	v_lshl_add_u64 v[2:3], s[4:5], 0, v[134:135]
	global_load_lds_dwordx4 v[2:3], off
	v_lshl_add_u64 v[2:3], s[4:5], 0, v[130:131]
	s_add_i32 m0, s25, 0x1e000
	s_lshl_b32 s0, s0, 5
	global_load_lds_dwordx4 v[2:3], off
	v_and_b32_e32 v19, 24, v18
	s_and_b32 s0, s0, 0x60
	v_or_b32_e32 v3, s0, v19
	v_lshrrev_b32_e32 v144, 4, v3
	v_lshlrev_b32_e32 v3, 13, v10
	v_and_b32_e32 v3, 0xffffc000, v3
	v_lshl_add_u32 v3, v9, 10, v3
	v_and_b32_e32 v4, 1, v10
	v_lshl_or_b32 v3, v4, 6, v3
	v_and_b32_e32 v13, 15, v12
	v_lshlrev_b32_e32 v20, 1, v19
	v_lshlrev_b32_e32 v12, 2, v12
	v_lshl_add_u32 v138, v11, 1, v3
	v_lshlrev_b32_e32 v3, 13, v6
	v_lshl_or_b32 v142, s1, 6, v13
	v_lshl_or_b32 v13, v13, 6, v20
	s_lshl_b32 s1, s1, 13
	v_and_b32_e32 v12, 32, v12
	v_and_b32_e32 v3, 0xffffc000, v3
	v_bitop3_b32 v20, v13, s1, v12 bitop3:0xde
	s_lshl_b32 s1, s0, 7
	s_waitcnt vmcnt(6)
	v_lshl_add_u32 v3, v7, 10, v3
	v_and_b32_e32 v4, 1, v6
	v_bitop3_b32 v143, v13, s1, v12 bitop3:0xde
	v_add_u32_e32 v143, 0x10000, v143
	s_cmpk_lt_u32 s2, 0x100
	v_and_b32_e32 v2, 8, v18
	v_lshl_or_b32 v3, v4, 6, v3
	v_readlane_b32 s0, v253, 36
	s_cselect_b64 s[14:15], -1, 0
	v_or_b32_e32 v145, 8, v144
	v_mov_b32_e32 v139, v203
	v_lshl_add_u32 v140, v8, 1, v3
	v_mov_b32_e32 v141, v203
	s_mov_b32 s31, 0
	v_add_u32_e32 v146, 0, v20
	v_lshlrev_b32_e32 v202, 1, v2
	s_mov_b32 s35, s0
	s_mov_b32 s34, s56
	s_barrier
	v_readlane_b32 s1, v253, 37
	s_branch .LBB0_1362

.LBB0_1363:
	s_add_u32 s0, s20, 0xfffe0080
	s_addc_u32 s1, s21, -1
	s_add_i32 s33, 0, 0x10000
	s_cmp_eq_u32 s59, 4
	s_cselect_b32 s5, s38, s1
	s_cselect_b32 s4, s39, s0
	s_cselect_b32 s3, s40, s58
	s_cselect_b32 s2, s41, s49
	s_add_i32 s55, 0, 0x14000
	ds_read_b128 v[148:151], v143
	ds_read_b128 v[152:155], v143 offset:1024
	ds_read_b128 v[156:159], v143 offset:2048
	ds_read_b128 v[160:163], v143 offset:3072
	ds_read_b128 v[164:167], v143 offset:16384
	ds_read_b128 v[168:171], v143 offset:17408
	ds_read_b128 v[172:175], v143 offset:18432
	ds_read_b128 v[176:179], v143 offset:19456
	s_add_i32 m0, s25, 0xc000
	ds_read_b128 v[180:183], v146
	ds_read_b128 v[184:187], v146 offset:1024
	ds_read_b128 v[188:191], v146 offset:2048
	ds_read_b128 v[192:195], v146 offset:3072
	ds_read_b128 v[196:199], v146 offset:4096
	ds_read_b128 v[208:211], v146 offset:5120
	ds_read_b128 v[212:215], v146 offset:6144
	ds_read_b128 v[216:219], v146 offset:7168
	global_load_lds_dwordx4 v138, s[20:21]
	s_add_i32 m0, s25, 0xe000
	s_nop 0
	global_load_lds_dwordx4 v140, s[20:21]
	s_waitcnt vmcnt(8)
	s_waitcnt lgkmcnt(0)
	s_setprio 1
	s_barrier
	v_mfma_f32_16x16x32_bf16 v[126:129], v[148:151], v[180:183], v[126:129]
	v_mfma_f32_16x16x32_bf16 v[122:125], v[156:159], v[180:183], v[122:125]
	v_mfma_f32_16x16x32_bf16 v[110:113], v[148:151], v[188:191], v[110:113]
	v_mfma_f32_16x16x32_bf16 v[106:109], v[156:159], v[188:191], v[106:109]
	v_mfma_f32_16x16x32_bf16 v[94:97], v[148:151], v[196:199], v[94:97]
	v_mfma_f32_16x16x32_bf16 v[90:93], v[156:159], v[196:199], v[90:93]
	v_mfma_f32_16x16x32_bf16 v[78:81], v[148:151], v[212:215], v[78:81]
	v_mfma_f32_16x16x32_bf16 v[74:77], v[156:159], v[212:215], v[74:77]
	v_mfma_f32_16x16x32_bf16 v[126:129], v[152:155], v[184:187], v[126:129]
	v_mfma_f32_16x16x32_bf16 v[122:125], v[160:163], v[184:187], v[122:125]
	v_mfma_f32_16x16x32_bf16 v[110:113], v[152:155], v[192:195], v[110:113]
	v_mfma_f32_16x16x32_bf16 v[106:109], v[160:163], v[192:195], v[106:109]
	v_mfma_f32_16x16x32_bf16 v[94:97], v[152:155], v[208:211], v[94:97]
	v_mfma_f32_16x16x32_bf16 v[90:93], v[160:163], v[208:211], v[90:93]
	v_mfma_f32_16x16x32_bf16 v[78:81], v[152:155], v[216:219], v[78:81]
	v_mfma_f32_16x16x32_bf16 v[74:77], v[160:163], v[216:219], v[74:77]
	s_setprio 0
	s_setprio 1
	v_mfma_f32_16x16x32_bf16 v[118:121], v[164:167], v[180:183], v[118:121]
	v_mfma_f32_16x16x32_bf16 v[114:117], v[172:175], v[180:183], v[114:117]
	v_mfma_f32_16x16x32_bf16 v[102:105], v[164:167], v[188:191], v[102:105]
	v_mfma_f32_16x16x32_bf16 v[98:101], v[172:175], v[188:191], v[98:101]
	v_mfma_f32_16x16x32_bf16 v[86:89], v[164:167], v[196:199], v[86:89]
	v_mfma_f32_16x16x32_bf16 v[82:85], v[172:175], v[196:199], v[82:85]
	v_mfma_f32_16x16x32_bf16 v[70:73], v[164:167], v[212:215], v[70:73]
	v_mfma_f32_16x16x32_bf16 v[66:69], v[172:175], v[212:215], v[66:69]
	v_mfma_f32_16x16x32_bf16 v[118:121], v[168:171], v[184:187], v[118:121]
	v_mfma_f32_16x16x32_bf16 v[114:117], v[176:179], v[184:187], v[114:117]
	v_mfma_f32_16x16x32_bf16 v[102:105], v[168:171], v[192:195], v[102:105]
	v_mfma_f32_16x16x32_bf16 v[98:101], v[176:179], v[192:195], v[98:101]
	v_mfma_f32_16x16x32_bf16 v[86:89], v[168:171], v[208:211], v[86:89]
	v_mfma_f32_16x16x32_bf16 v[82:85], v[176:179], v[208:211], v[82:85]
	v_mfma_f32_16x16x32_bf16 v[70:73], v[168:171], v[216:219], v[70:73]
	v_mfma_f32_16x16x32_bf16 v[66:69], v[176:179], v[216:219], v[66:69]
	s_barrier
	s_setprio 0
	s_add_i32 s0, s33, s24
	s_mov_b32 m0, s0
	ds_read_b128 v[180:183], v146 offset:16384
	ds_read_b128 v[184:187], v146 offset:17408
	ds_read_b128 v[188:191], v146 offset:18432
	ds_read_b128 v[192:195], v146 offset:19456
	ds_read_b128 v[196:199], v146 offset:20480
	ds_read_b128 v[208:211], v146 offset:21504
	ds_read_b128 v[212:215], v146 offset:22528
	ds_read_b128 v[216:219], v146 offset:23552
	global_load_lds_dwordx4 v134, s[2:3]
	s_add_i32 m0, s0, 0x2000
	s_add_u32 s0, s2, 0x20000
	s_addc_u32 s1, s3, 0
	s_add_i32 s33, s55, s24
	global_load_lds_dwordx4 v130, s[2:3]
	s_mov_b32 m0, s33
	s_nop 0
	global_load_lds_dwordx4 v134, s[0:1]
	s_add_i32 m0, s33, 0x2000
	s_nop 0
	global_load_lds_dwordx4 v130, s[0:1]
	s_mov_b32 m0, s25
	s_nop 0
	global_load_lds_dwordx4 v136, s[4:5]
	s_mov_b32 m0, s26
	s_nop 0
	global_load_lds_dwordx4 v132, s[4:5]
	s_waitcnt vmcnt(8)
	s_waitcnt lgkmcnt(0)
	s_setprio 1
	s_barrier
	v_mfma_f32_16x16x32_bf16 v[62:65], v[148:151], v[180:183], v[62:65]
	v_mfma_f32_16x16x32_bf16 v[58:61], v[156:159], v[180:183], v[58:61]
	v_mfma_f32_16x16x32_bf16 v[46:49], v[148:151], v[188:191], v[46:49]
	v_mfma_f32_16x16x32_bf16 v[42:45], v[156:159], v[188:191], v[42:45]
	v_mfma_f32_16x16x32_bf16 v[30:33], v[148:151], v[196:199], v[30:33]
	v_mfma_f32_16x16x32_bf16 v[26:29], v[156:159], v[196:199], v[26:29]
	v_mfma_f32_16x16x32_bf16 v[14:17], v[148:151], v[212:215], v[14:17]
	v_mfma_f32_16x16x32_bf16 v[10:13], v[156:159], v[212:215], v[10:13]
	v_mfma_f32_16x16x32_bf16 v[62:65], v[152:155], v[184:187], v[62:65]
	v_mfma_f32_16x16x32_bf16 v[58:61], v[160:163], v[184:187], v[58:61]
	v_mfma_f32_16x16x32_bf16 v[46:49], v[152:155], v[192:195], v[46:49]
	v_mfma_f32_16x16x32_bf16 v[42:45], v[160:163], v[192:195], v[42:45]
	v_mfma_f32_16x16x32_bf16 v[30:33], v[152:155], v[208:211], v[30:33]
	v_mfma_f32_16x16x32_bf16 v[26:29], v[160:163], v[208:211], v[26:29]
	v_mfma_f32_16x16x32_bf16 v[14:17], v[152:155], v[216:219], v[14:17]
	v_mfma_f32_16x16x32_bf16 v[10:13], v[160:163], v[216:219], v[10:13]
	s_setprio 0
	s_setprio 1
	v_mfma_f32_16x16x32_bf16 v[54:57], v[164:167], v[180:183], v[54:57]
	v_mfma_f32_16x16x32_bf16 v[50:53], v[172:175], v[180:183], v[50:53]
	v_mfma_f32_16x16x32_bf16 v[38:41], v[164:167], v[188:191], v[38:41]
	v_mfma_f32_16x16x32_bf16 v[34:37], v[172:175], v[188:191], v[34:37]
	v_mfma_f32_16x16x32_bf16 v[22:25], v[164:167], v[196:199], v[22:25]
	v_mfma_f32_16x16x32_bf16 v[18:21], v[172:175], v[196:199], v[18:21]
	v_mfma_f32_16x16x32_bf16 v[6:9], v[164:167], v[212:215], v[6:9]
	v_mfma_f32_16x16x32_bf16 v[2:5], v[172:175], v[212:215], v[2:5]
	v_mfma_f32_16x16x32_bf16 v[54:57], v[168:171], v[184:187], v[54:57]
	v_mfma_f32_16x16x32_bf16 v[50:53], v[176:179], v[184:187], v[50:53]
	v_mfma_f32_16x16x32_bf16 v[38:41], v[168:171], v[192:195], v[38:41]
	v_mfma_f32_16x16x32_bf16 v[34:37], v[176:179], v[192:195], v[34:37]
	v_mfma_f32_16x16x32_bf16 v[22:25], v[168:171], v[208:211], v[22:25]
	v_mfma_f32_16x16x32_bf16 v[18:21], v[176:179], v[208:211], v[18:21]
	v_mfma_f32_16x16x32_bf16 v[6:9], v[168:171], v[216:219], v[6:9]
	v_mfma_f32_16x16x32_bf16 v[2:5], v[176:179], v[216:219], v[2:5]
	s_barrier
	s_setprio 0
	s_add_i32 s33, 0, 0x18000
	s_add_i32 s55, 0, 0x1c000
	ds_read_b128 v[148:151], v143 offset:32768
	ds_read_b128 v[152:155], v143 offset:33792
	ds_read_b128 v[156:159], v143 offset:34816
	ds_read_b128 v[160:163], v143 offset:35840
	ds_read_b128 v[164:167], v143 offset:49152
	ds_read_b128 v[168:171], v143 offset:50176
	ds_read_b128 v[172:175], v143 offset:51200
	ds_read_b128 v[176:179], v143 offset:52224
	s_add_u32 s0, s4, 0x20000
	s_addc_u32 s1, s5, 0
	s_mov_b32 m0, s27
	ds_read_b128 v[180:183], v146 offset:32768
	ds_read_b128 v[184:187], v146 offset:33792
	ds_read_b128 v[188:191], v146 offset:34816
	ds_read_b128 v[192:195], v146 offset:35840
	ds_read_b128 v[196:199], v146 offset:36864
	ds_read_b128 v[208:211], v146 offset:37888
	ds_read_b128 v[212:215], v146 offset:38912
	ds_read_b128 v[216:219], v146 offset:39936
	global_load_lds_dwordx4 v136, s[0:1]
	s_mov_b32 m0, s28
	s_nop 0
	global_load_lds_dwordx4 v132, s[0:1]
	s_waitcnt vmcnt(8)
	s_waitcnt lgkmcnt(0)
	s_setprio 1
	s_barrier
	v_mfma_f32_16x16x32_bf16 v[126:129], v[148:151], v[180:183], v[126:129]
	v_mfma_f32_16x16x32_bf16 v[122:125], v[156:159], v[180:183], v[122:125]
	v_mfma_f32_16x16x32_bf16 v[110:113], v[148:151], v[188:191], v[110:113]
	v_mfma_f32_16x16x32_bf16 v[106:109], v[156:159], v[188:191], v[106:109]
	v_mfma_f32_16x16x32_bf16 v[94:97], v[148:151], v[196:199], v[94:97]
	v_mfma_f32_16x16x32_bf16 v[90:93], v[156:159], v[196:199], v[90:93]
	v_mfma_f32_16x16x32_bf16 v[78:81], v[148:151], v[212:215], v[78:81]
	v_mfma_f32_16x16x32_bf16 v[74:77], v[156:159], v[212:215], v[74:77]
	v_mfma_f32_16x16x32_bf16 v[126:129], v[152:155], v[184:187], v[126:129]
	v_mfma_f32_16x16x32_bf16 v[122:125], v[160:163], v[184:187], v[122:125]
	v_mfma_f32_16x16x32_bf16 v[110:113], v[152:155], v[192:195], v[110:113]
	v_mfma_f32_16x16x32_bf16 v[106:109], v[160:163], v[192:195], v[106:109]
	v_mfma_f32_16x16x32_bf16 v[94:97], v[152:155], v[208:211], v[94:97]
	v_mfma_f32_16x16x32_bf16 v[90:93], v[160:163], v[208:211], v[90:93]
	v_mfma_f32_16x16x32_bf16 v[78:81], v[152:155], v[216:219], v[78:81]
	v_mfma_f32_16x16x32_bf16 v[74:77], v[160:163], v[216:219], v[74:77]
	s_setprio 0
	s_setprio 1
	v_mfma_f32_16x16x32_bf16 v[118:121], v[164:167], v[180:183], v[118:121]
	v_mfma_f32_16x16x32_bf16 v[114:117], v[172:175], v[180:183], v[114:117]
	v_mfma_f32_16x16x32_bf16 v[102:105], v[164:167], v[188:191], v[102:105]
	v_mfma_f32_16x16x32_bf16 v[98:101], v[172:175], v[188:191], v[98:101]
	v_mfma_f32_16x16x32_bf16 v[86:89], v[164:167], v[196:199], v[86:89]
	v_mfma_f32_16x16x32_bf16 v[82:85], v[172:175], v[196:199], v[82:85]
	v_mfma_f32_16x16x32_bf16 v[70:73], v[164:167], v[212:215], v[70:73]
	v_mfma_f32_16x16x32_bf16 v[66:69], v[172:175], v[212:215], v[66:69]
	v_mfma_f32_16x16x32_bf16 v[118:121], v[168:171], v[184:187], v[118:121]
	v_mfma_f32_16x16x32_bf16 v[114:117], v[176:179], v[184:187], v[114:117]
	v_mfma_f32_16x16x32_bf16 v[102:105], v[168:171], v[192:195], v[102:105]
	v_mfma_f32_16x16x32_bf16 v[98:101], v[176:179], v[192:195], v[98:101]
	v_mfma_f32_16x16x32_bf16 v[86:89], v[168:171], v[208:211], v[86:89]
	v_mfma_f32_16x16x32_bf16 v[82:85], v[176:179], v[208:211], v[82:85]
	v_mfma_f32_16x16x32_bf16 v[70:73], v[168:171], v[216:219], v[70:73]
	v_mfma_f32_16x16x32_bf16 v[66:69], v[176:179], v[216:219], v[66:69]
	s_barrier
	s_setprio 0
	s_add_i32 s0, s33, s24
	s_add_u32 s100, s2, 0x80
	s_addc_u32 s101, s3, 0
	s_mov_b32 m0, s0
	ds_read_b128 v[180:183], v146 offset:49152
	ds_read_b128 v[184:187], v146 offset:50176
	ds_read_b128 v[188:191], v146 offset:51200
	ds_read_b128 v[192:195], v146 offset:52224
	ds_read_b128 v[196:199], v146 offset:53248
	ds_read_b128 v[208:211], v146 offset:54272
	ds_read_b128 v[212:215], v146 offset:55296
	ds_read_b128 v[216:219], v146 offset:56320
	global_load_lds_dwordx4 v134, s[100:101]
	s_add_i32 m0, s0, 0x2000
	s_add_u32 s100, s2, 0x80
	s_addc_u32 s101, s3, 0
	s_add_u32 s0, s2, 0x20080
	s_addc_u32 s1, s3, 0
	s_add_i32 s2, s55, s24
	global_load_lds_dwordx4 v130, s[100:101]
	s_mov_b32 m0, s2
	s_nop 0
	global_load_lds_dwordx4 v134, s[0:1]
	s_add_i32 m0, s2, 0x2000
	s_nop 0
	global_load_lds_dwordx4 v130, s[0:1]
	s_add_u32 s100, s4, 0x80
	s_addc_u32 s101, s5, 0
	s_mov_b32 m0, s29
	s_nop 0
	global_load_lds_dwordx4 v136, s[100:101]
	s_add_u32 s100, s4, 0x80
	s_addc_u32 s101, s5, 0
	s_mov_b32 m0, s30
	s_nop 0
	global_load_lds_dwordx4 v132, s[100:101]
	s_waitcnt vmcnt(8)
	s_waitcnt lgkmcnt(0)
	s_setprio 1
	s_barrier
	v_mfma_f32_16x16x32_bf16 v[62:65], v[148:151], v[180:183], v[62:65]
	v_mfma_f32_16x16x32_bf16 v[58:61], v[156:159], v[180:183], v[58:61]
	v_mfma_f32_16x16x32_bf16 v[46:49], v[148:151], v[188:191], v[46:49]
	v_mfma_f32_16x16x32_bf16 v[42:45], v[156:159], v[188:191], v[42:45]
	v_mfma_f32_16x16x32_bf16 v[30:33], v[148:151], v[196:199], v[30:33]
	v_mfma_f32_16x16x32_bf16 v[26:29], v[156:159], v[196:199], v[26:29]
	v_mfma_f32_16x16x32_bf16 v[14:17], v[148:151], v[212:215], v[14:17]
	v_mfma_f32_16x16x32_bf16 v[10:13], v[156:159], v[212:215], v[10:13]
	v_mfma_f32_16x16x32_bf16 v[62:65], v[152:155], v[184:187], v[62:65]
	v_mfma_f32_16x16x32_bf16 v[58:61], v[160:163], v[184:187], v[58:61]
	v_mfma_f32_16x16x32_bf16 v[46:49], v[152:155], v[192:195], v[46:49]
	v_mfma_f32_16x16x32_bf16 v[42:45], v[160:163], v[192:195], v[42:45]
	v_mfma_f32_16x16x32_bf16 v[30:33], v[152:155], v[208:211], v[30:33]
	v_mfma_f32_16x16x32_bf16 v[26:29], v[160:163], v[208:211], v[26:29]
	v_mfma_f32_16x16x32_bf16 v[14:17], v[152:155], v[216:219], v[14:17]
	v_mfma_f32_16x16x32_bf16 v[10:13], v[160:163], v[216:219], v[10:13]
	s_setprio 0
	s_setprio 1
	v_mfma_f32_16x16x32_bf16 v[54:57], v[164:167], v[180:183], v[54:57]
	v_mfma_f32_16x16x32_bf16 v[50:53], v[172:175], v[180:183], v[50:53]
	v_mfma_f32_16x16x32_bf16 v[38:41], v[164:167], v[188:191], v[38:41]
	v_mfma_f32_16x16x32_bf16 v[34:37], v[172:175], v[188:191], v[34:37]
	v_mfma_f32_16x16x32_bf16 v[22:25], v[164:167], v[196:199], v[22:25]
	v_mfma_f32_16x16x32_bf16 v[18:21], v[172:175], v[196:199], v[18:21]
	v_mfma_f32_16x16x32_bf16 v[6:9], v[164:167], v[212:215], v[6:9]
	v_mfma_f32_16x16x32_bf16 v[2:5], v[172:175], v[212:215], v[2:5]
	v_mfma_f32_16x16x32_bf16 v[54:57], v[168:171], v[184:187], v[54:57]
	v_mfma_f32_16x16x32_bf16 v[50:53], v[176:179], v[184:187], v[50:53]
	v_mfma_f32_16x16x32_bf16 v[38:41], v[168:171], v[192:195], v[38:41]
	v_mfma_f32_16x16x32_bf16 v[34:37], v[176:179], v[192:195], v[34:37]
	v_mfma_f32_16x16x32_bf16 v[22:25], v[168:171], v[208:211], v[22:25]
	v_mfma_f32_16x16x32_bf16 v[18:21], v[176:179], v[208:211], v[18:21]
	v_mfma_f32_16x16x32_bf16 v[6:9], v[168:171], v[216:219], v[6:9]
	v_mfma_f32_16x16x32_bf16 v[2:5], v[176:179], v[216:219], v[2:5]
	s_barrier
	s_setprio 0
	s_add_i32 s59, s59, 2
	s_add_u32 s20, s20, 0x100
	s_addc_u32 s21, s21, 0
	s_add_u32 s49, s49, 0x100
	s_addc_u32 s58, s58, 0
	s_cmp_gt_u32 s59, 5
	s_cbranch_scc0 .LBB0_1363
	s_and_b64 vcc, exec, s[14:15]
	s_cbranch_vccz .LBB0_1366
	s_barrier

.LBB0_1422:
	v_lshrrev_b32_e32 v18, 1, v16
	v_readlane_b32 s0, v254, 58
	v_and_b32_e32 v18, 24, v18
	v_readlane_b32 s1, v254, 59
	s_add_u32 s37, s0, 0x4000
	v_and_b32_e32 v17, 15, v16
	v_lshlrev_b32_e32 v19, 1, v18
	v_lshlrev_b32_e32 v16, 2, v16
	s_addc_u32 s38, s1, 0
	v_lshl_or_b32 v186, s10, 6, v17
	v_lshl_or_b32 v17, v17, 6, v19
	s_lshl_b32 s0, s10, 13
	v_and_b32_e32 v16, 32, v16
	v_bitop3_b32 v19, v17, s0, v16 bitop3:0xde
	s_lshl_b32 s0, s7, 5
	s_and_b32 s7, s0, 0x60
	s_add_i32 m0, s23, 0x18000
	v_lshl_add_u64 v[8:9], v[8:9], 0, s[80:81]
	s_lshl_b32 s0, s7, 7
	s_waitcnt vmcnt(2)
	s_barrier
	global_load_lds_dwordx4 v[8:9], off
	v_lshl_add_u64 v[6:7], v[6:7], 0, s[80:81]
	s_add_i32 m0, s23, 0x1a000
	s_add_i32 s39, s23, 0x8000
	s_add_i32 s40, s23, 0xa000
	v_bitop3_b32 v187, v17, s0, v16 bitop3:0xde
	v_add_u32_e32 v187, 0x10000, v187
	global_load_lds_dwordx4 v[6:7], off
	v_lshl_add_u64 v[2:3], v[2:3], 0, s[80:81]
	s_mov_b32 m0, s39
	s_add_u32 s0, s2, 0x80080
	global_load_lds_dwordx4 v[2:3], off
	v_lshl_add_u64 v[2:3], v[4:5], 0, s[80:81]
	s_mov_b32 m0, s40
	s_addc_u32 s1, s3, 0
	global_load_lds_dwordx4 v[2:3], off
	s_add_i32 m0, s23, 0x1c000
	v_lshl_add_u64 v[2:3], s[0:1], 0, v[202:203]
	global_load_lds_dwordx4 v[2:3], off
	v_lshl_add_u64 v[2:3], s[0:1], 0, v[162:163]
	s_add_i32 m0, s23, 0x1e000
	s_cmpk_lt_u32 s6, 0x100
	global_load_lds_dwordx4 v[2:3], off
	v_lshlrev_b32_e32 v2, 15, v14
	v_and_b32_e32 v2, 0xffff0000, v2
	v_lshl_add_u32 v2, v13, 12, v2
	v_and_b32_e32 v3, 1, v14
	v_lshl_or_b32 v2, v3, 6, v2
	v_lshl_add_u32 v168, v15, 1, v2
	v_lshlrev_b32_e32 v2, 15, v10
	v_and_b32_e32 v2, 0xffff0000, v2
	s_waitcnt vmcnt(6)
	v_lshl_add_u32 v2, v11, 12, v2
	v_and_b32_e32 v3, 1, v10
	v_lshl_or_b32 v2, v3, 6, v2
	s_cselect_b64 s[10:11], -1, 0
	v_or_b32_e32 v188, s7, v18
	v_mov_b32_e32 v169, v203
	v_lshl_add_u32 v170, v12, 1, v2
	v_mov_b32_e32 v171, v203
	s_mov_b32 s41, 0
	v_add_u32_e32 v189, 0, v19
	s_barrier
	s_branch .LBB0_1425

.LBB0_1428:
	s_add_u32 s0, s26, 0xfff80080
	s_addc_u32 s1, s27, -1
	s_add_i32 s33, 0, 0x10000
	s_cmp_eq_u32 s61, 28
	s_cselect_b32 s5, s17, s1
	s_cselect_b32 s4, s49, s0
	s_cselect_b32 s3, s15, s60
	s_cselect_b32 s2, s58, s59
	s_add_i32 s55, 0, 0x14000
	ds_read_b128 v[126:129], v187
	ds_read_b128 v[134:137], v187 offset:1024
	ds_read_b128 v[138:141], v187 offset:2048
	ds_read_b128 v[142:145], v187 offset:3072
	ds_read_b128 v[146:149], v187 offset:16384
	ds_read_b128 v[150:153], v187 offset:17408
	ds_read_b128 v[154:157], v187 offset:18432
	ds_read_b128 v[158:161], v187 offset:19456
	s_add_i32 m0, s23, 0xc000
	ds_read_b128 v[172:175], v189
	ds_read_b128 v[176:179], v189 offset:1024
	ds_read_b128 v[180:183], v189 offset:2048
	ds_read_b128 v[190:193], v189 offset:3072
	ds_read_b128 v[194:197], v189 offset:4096
	ds_read_b128 v[198:201], v189 offset:5120
	ds_read_b128 v[208:211], v189 offset:6144
	ds_read_b128 v[212:215], v189 offset:7168
	global_load_lds_dwordx4 v168, s[26:27]
	s_add_i32 m0, s23, 0xe000
	s_nop 0
	global_load_lds_dwordx4 v170, s[26:27]
	s_waitcnt vmcnt(8)
	s_waitcnt lgkmcnt(0)
	s_setprio 1
	s_barrier
	v_mfma_f32_16x16x32_bf16 v[130:133], v[126:129], v[172:175], v[130:133]
	v_mfma_f32_16x16x32_bf16 v[118:121], v[138:141], v[172:175], v[118:121]
	v_mfma_f32_16x16x32_bf16 v[110:113], v[126:129], v[180:183], v[110:113]
	v_mfma_f32_16x16x32_bf16 v[102:105], v[138:141], v[180:183], v[102:105]
	v_mfma_f32_16x16x32_bf16 v[94:97], v[126:129], v[194:197], v[94:97]
	v_mfma_f32_16x16x32_bf16 v[86:89], v[138:141], v[194:197], v[86:89]
	v_mfma_f32_16x16x32_bf16 v[78:81], v[126:129], v[208:211], v[78:81]
	v_mfma_f32_16x16x32_bf16 v[70:73], v[138:141], v[208:211], v[70:73]
	v_mfma_f32_16x16x32_bf16 v[130:133], v[134:137], v[176:179], v[130:133]
	v_mfma_f32_16x16x32_bf16 v[118:121], v[142:145], v[176:179], v[118:121]
	v_mfma_f32_16x16x32_bf16 v[110:113], v[134:137], v[190:193], v[110:113]
	v_mfma_f32_16x16x32_bf16 v[102:105], v[142:145], v[190:193], v[102:105]
	v_mfma_f32_16x16x32_bf16 v[94:97], v[134:137], v[198:201], v[94:97]
	v_mfma_f32_16x16x32_bf16 v[86:89], v[142:145], v[198:201], v[86:89]
	v_mfma_f32_16x16x32_bf16 v[78:81], v[134:137], v[212:215], v[78:81]
	v_mfma_f32_16x16x32_bf16 v[70:73], v[142:145], v[212:215], v[70:73]
	s_setprio 0
	s_setprio 1
	v_mfma_f32_16x16x32_bf16 v[122:125], v[146:149], v[172:175], v[122:125]
	v_mfma_f32_16x16x32_bf16 v[114:117], v[154:157], v[172:175], v[114:117]
	v_mfma_f32_16x16x32_bf16 v[106:109], v[146:149], v[180:183], v[106:109]
	v_mfma_f32_16x16x32_bf16 v[98:101], v[154:157], v[180:183], v[98:101]
	v_mfma_f32_16x16x32_bf16 v[90:93], v[146:149], v[194:197], v[90:93]
	v_mfma_f32_16x16x32_bf16 v[82:85], v[154:157], v[194:197], v[82:85]
	v_mfma_f32_16x16x32_bf16 v[74:77], v[146:149], v[208:211], v[74:77]
	v_mfma_f32_16x16x32_bf16 v[66:69], v[154:157], v[208:211], v[66:69]
	v_mfma_f32_16x16x32_bf16 v[122:125], v[150:153], v[176:179], v[122:125]
	v_mfma_f32_16x16x32_bf16 v[114:117], v[158:161], v[176:179], v[114:117]
	v_mfma_f32_16x16x32_bf16 v[106:109], v[150:153], v[190:193], v[106:109]
	v_mfma_f32_16x16x32_bf16 v[98:101], v[158:161], v[190:193], v[98:101]
	v_mfma_f32_16x16x32_bf16 v[90:93], v[150:153], v[198:201], v[90:93]
	v_mfma_f32_16x16x32_bf16 v[82:85], v[158:161], v[198:201], v[82:85]
	v_mfma_f32_16x16x32_bf16 v[74:77], v[150:153], v[212:215], v[74:77]
	v_mfma_f32_16x16x32_bf16 v[66:69], v[158:161], v[212:215], v[66:69]
	s_barrier
	s_setprio 0
	s_add_i32 s0, s33, s34
	s_mov_b32 m0, s0
	ds_read_b128 v[172:175], v189 offset:16384
	ds_read_b128 v[176:179], v189 offset:17408
	ds_read_b128 v[180:183], v189 offset:18432
	ds_read_b128 v[190:193], v189 offset:19456
	ds_read_b128 v[194:197], v189 offset:20480
	ds_read_b128 v[198:201], v189 offset:21504
	ds_read_b128 v[208:211], v189 offset:22528
	ds_read_b128 v[212:215], v189 offset:23552
	global_load_lds_dwordx4 v202, s[2:3]
	s_add_i32 m0, s0, 0x2000
	s_add_u32 s0, s2, 0x80000
	s_addc_u32 s1, s3, 0
	s_add_i32 s33, s55, s34
	global_load_lds_dwordx4 v162, s[2:3]
	s_mov_b32 m0, s33
	s_nop 0
	global_load_lds_dwordx4 v202, s[0:1]
	s_add_i32 m0, s33, 0x2000
	s_nop 0
	global_load_lds_dwordx4 v162, s[0:1]
	s_mov_b32 m0, s23
	s_nop 0
	global_load_lds_dwordx4 v166, s[4:5]
	s_mov_b32 m0, s25
	s_nop 0
	global_load_lds_dwordx4 v164, s[4:5]
	s_waitcnt vmcnt(8)
	s_waitcnt lgkmcnt(0)
	s_setprio 1
	s_barrier
	v_mfma_f32_16x16x32_bf16 v[62:65], v[126:129], v[172:175], v[62:65]
	v_mfma_f32_16x16x32_bf16 v[54:57], v[138:141], v[172:175], v[54:57]
	v_mfma_f32_16x16x32_bf16 v[46:49], v[126:129], v[180:183], v[46:49]
	v_mfma_f32_16x16x32_bf16 v[38:41], v[138:141], v[180:183], v[38:41]
	v_mfma_f32_16x16x32_bf16 v[30:33], v[126:129], v[194:197], v[30:33]
	v_mfma_f32_16x16x32_bf16 v[22:25], v[138:141], v[194:197], v[22:25]
	v_mfma_f32_16x16x32_bf16 v[14:17], v[126:129], v[208:211], v[14:17]
	v_mfma_f32_16x16x32_bf16 v[6:9], v[138:141], v[208:211], v[6:9]
	v_mfma_f32_16x16x32_bf16 v[62:65], v[134:137], v[176:179], v[62:65]
	v_mfma_f32_16x16x32_bf16 v[54:57], v[142:145], v[176:179], v[54:57]
	v_mfma_f32_16x16x32_bf16 v[46:49], v[134:137], v[190:193], v[46:49]
	v_mfma_f32_16x16x32_bf16 v[38:41], v[142:145], v[190:193], v[38:41]
	v_mfma_f32_16x16x32_bf16 v[30:33], v[134:137], v[198:201], v[30:33]
	v_mfma_f32_16x16x32_bf16 v[22:25], v[142:145], v[198:201], v[22:25]
	v_mfma_f32_16x16x32_bf16 v[14:17], v[134:137], v[212:215], v[14:17]
	v_mfma_f32_16x16x32_bf16 v[6:9], v[142:145], v[212:215], v[6:9]
	s_setprio 0
	s_setprio 1
	v_mfma_f32_16x16x32_bf16 v[58:61], v[146:149], v[172:175], v[58:61]
	v_mfma_f32_16x16x32_bf16 v[50:53], v[154:157], v[172:175], v[50:53]
	v_mfma_f32_16x16x32_bf16 v[42:45], v[146:149], v[180:183], v[42:45]
	v_mfma_f32_16x16x32_bf16 v[34:37], v[154:157], v[180:183], v[34:37]
	v_mfma_f32_16x16x32_bf16 v[26:29], v[146:149], v[194:197], v[26:29]
	v_mfma_f32_16x16x32_bf16 v[18:21], v[154:157], v[194:197], v[18:21]
	v_mfma_f32_16x16x32_bf16 v[10:13], v[146:149], v[208:211], v[10:13]
	v_mfma_f32_16x16x32_bf16 v[2:5], v[154:157], v[208:211], v[2:5]
	v_mfma_f32_16x16x32_bf16 v[58:61], v[150:153], v[176:179], v[58:61]
	v_mfma_f32_16x16x32_bf16 v[50:53], v[158:161], v[176:179], v[50:53]
	v_mfma_f32_16x16x32_bf16 v[42:45], v[150:153], v[190:193], v[42:45]
	v_mfma_f32_16x16x32_bf16 v[34:37], v[158:161], v[190:193], v[34:37]
	v_mfma_f32_16x16x32_bf16 v[26:29], v[150:153], v[198:201], v[26:29]
	v_mfma_f32_16x16x32_bf16 v[18:21], v[158:161], v[198:201], v[18:21]
	v_mfma_f32_16x16x32_bf16 v[10:13], v[150:153], v[212:215], v[10:13]
	v_mfma_f32_16x16x32_bf16 v[2:5], v[158:161], v[212:215], v[2:5]
	s_barrier
	s_setprio 0
	s_add_i32 s33, 0, 0x18000
	s_add_i32 s55, 0, 0x1c000
	ds_read_b128 v[126:129], v187 offset:32768
	ds_read_b128 v[134:137], v187 offset:33792
	ds_read_b128 v[138:141], v187 offset:34816
	ds_read_b128 v[142:145], v187 offset:35840
	ds_read_b128 v[146:149], v187 offset:49152
	ds_read_b128 v[150:153], v187 offset:50176
	ds_read_b128 v[154:157], v187 offset:51200
	ds_read_b128 v[158:161], v187 offset:52224
	s_add_u32 s0, s4, 0x80000
	s_addc_u32 s1, s5, 0
	s_mov_b32 m0, s35
	ds_read_b128 v[172:175], v189 offset:32768
	ds_read_b128 v[176:179], v189 offset:33792
	ds_read_b128 v[180:183], v189 offset:34816
	ds_read_b128 v[190:193], v189 offset:35840
	ds_read_b128 v[194:197], v189 offset:36864
	ds_read_b128 v[198:201], v189 offset:37888
	ds_read_b128 v[208:211], v189 offset:38912
	ds_read_b128 v[212:215], v189 offset:39936
	global_load_lds_dwordx4 v166, s[0:1]
	s_mov_b32 m0, s36
	s_nop 0
	global_load_lds_dwordx4 v164, s[0:1]
	s_waitcnt vmcnt(8)
	s_waitcnt lgkmcnt(0)
	s_setprio 1
	s_barrier
	v_mfma_f32_16x16x32_bf16 v[130:133], v[126:129], v[172:175], v[130:133]
	v_mfma_f32_16x16x32_bf16 v[118:121], v[138:141], v[172:175], v[118:121]
	v_mfma_f32_16x16x32_bf16 v[110:113], v[126:129], v[180:183], v[110:113]
	v_mfma_f32_16x16x32_bf16 v[102:105], v[138:141], v[180:183], v[102:105]
	v_mfma_f32_16x16x32_bf16 v[94:97], v[126:129], v[194:197], v[94:97]
	v_mfma_f32_16x16x32_bf16 v[86:89], v[138:141], v[194:197], v[86:89]
	v_mfma_f32_16x16x32_bf16 v[78:81], v[126:129], v[208:211], v[78:81]
	v_mfma_f32_16x16x32_bf16 v[70:73], v[138:141], v[208:211], v[70:73]
	v_mfma_f32_16x16x32_bf16 v[130:133], v[134:137], v[176:179], v[130:133]
	v_mfma_f32_16x16x32_bf16 v[118:121], v[142:145], v[176:179], v[118:121]
	v_mfma_f32_16x16x32_bf16 v[110:113], v[134:137], v[190:193], v[110:113]
	v_mfma_f32_16x16x32_bf16 v[102:105], v[142:145], v[190:193], v[102:105]
	v_mfma_f32_16x16x32_bf16 v[94:97], v[134:137], v[198:201], v[94:97]
	v_mfma_f32_16x16x32_bf16 v[86:89], v[142:145], v[198:201], v[86:89]
	v_mfma_f32_16x16x32_bf16 v[78:81], v[134:137], v[212:215], v[78:81]
	v_mfma_f32_16x16x32_bf16 v[70:73], v[142:145], v[212:215], v[70:73]
	s_setprio 0
	s_setprio 1
	v_mfma_f32_16x16x32_bf16 v[122:125], v[146:149], v[172:175], v[122:125]
	v_mfma_f32_16x16x32_bf16 v[114:117], v[154:157], v[172:175], v[114:117]
	v_mfma_f32_16x16x32_bf16 v[106:109], v[146:149], v[180:183], v[106:109]
	v_mfma_f32_16x16x32_bf16 v[98:101], v[154:157], v[180:183], v[98:101]
	v_mfma_f32_16x16x32_bf16 v[90:93], v[146:149], v[194:197], v[90:93]
	v_mfma_f32_16x16x32_bf16 v[82:85], v[154:157], v[194:197], v[82:85]
	v_mfma_f32_16x16x32_bf16 v[74:77], v[146:149], v[208:211], v[74:77]
	v_mfma_f32_16x16x32_bf16 v[66:69], v[154:157], v[208:211], v[66:69]
	v_mfma_f32_16x16x32_bf16 v[122:125], v[150:153], v[176:179], v[122:125]
	v_mfma_f32_16x16x32_bf16 v[114:117], v[158:161], v[176:179], v[114:117]
	v_mfma_f32_16x16x32_bf16 v[106:109], v[150:153], v[190:193], v[106:109]
	v_mfma_f32_16x16x32_bf16 v[98:101], v[158:161], v[190:193], v[98:101]
	v_mfma_f32_16x16x32_bf16 v[90:93], v[150:153], v[198:201], v[90:93]
	v_mfma_f32_16x16x32_bf16 v[82:85], v[158:161], v[198:201], v[82:85]
	v_mfma_f32_16x16x32_bf16 v[74:77], v[150:153], v[212:215], v[74:77]
	v_mfma_f32_16x16x32_bf16 v[66:69], v[158:161], v[212:215], v[66:69]
	s_barrier
	s_setprio 0
	s_add_i32 s0, s33, s34
	s_add_u32 s100, s2, 0x80
	s_addc_u32 s101, s3, 0
	s_mov_b32 m0, s0
	ds_read_b128 v[172:175], v189 offset:49152
	ds_read_b128 v[176:179], v189 offset:50176
	ds_read_b128 v[180:183], v189 offset:51200
	ds_read_b128 v[190:193], v189 offset:52224
	ds_read_b128 v[194:197], v189 offset:53248
	ds_read_b128 v[198:201], v189 offset:54272
	ds_read_b128 v[208:211], v189 offset:55296
	ds_read_b128 v[212:215], v189 offset:56320
	global_load_lds_dwordx4 v202, s[100:101]
	s_add_i32 m0, s0, 0x2000
	s_add_u32 s100, s2, 0x80
	s_addc_u32 s101, s3, 0
	s_add_u32 s0, s2, 0x80080
	s_addc_u32 s1, s3, 0
	s_add_i32 s2, s55, s34
	global_load_lds_dwordx4 v162, s[100:101]
	s_mov_b32 m0, s2
	s_nop 0
	global_load_lds_dwordx4 v202, s[0:1]
	s_add_i32 m0, s2, 0x2000
	s_nop 0
	global_load_lds_dwordx4 v162, s[0:1]
	s_add_u32 s100, s4, 0x80
	s_addc_u32 s101, s5, 0
	s_mov_b32 m0, s39
	s_nop 0
	global_load_lds_dwordx4 v166, s[100:101]
	s_add_u32 s100, s4, 0x80
	s_addc_u32 s101, s5, 0
	s_mov_b32 m0, s40
	s_nop 0
	global_load_lds_dwordx4 v164, s[100:101]
	s_waitcnt vmcnt(8)
	s_waitcnt lgkmcnt(0)
	s_setprio 1
	s_barrier
	v_mfma_f32_16x16x32_bf16 v[62:65], v[126:129], v[172:175], v[62:65]
	v_mfma_f32_16x16x32_bf16 v[54:57], v[138:141], v[172:175], v[54:57]
	v_mfma_f32_16x16x32_bf16 v[46:49], v[126:129], v[180:183], v[46:49]
	v_mfma_f32_16x16x32_bf16 v[38:41], v[138:141], v[180:183], v[38:41]
	v_mfma_f32_16x16x32_bf16 v[30:33], v[126:129], v[194:197], v[30:33]
	v_mfma_f32_16x16x32_bf16 v[22:25], v[138:141], v[194:197], v[22:25]
	v_mfma_f32_16x16x32_bf16 v[14:17], v[126:129], v[208:211], v[14:17]
	v_mfma_f32_16x16x32_bf16 v[6:9], v[138:141], v[208:211], v[6:9]
	v_mfma_f32_16x16x32_bf16 v[62:65], v[134:137], v[176:179], v[62:65]
	v_mfma_f32_16x16x32_bf16 v[54:57], v[142:145], v[176:179], v[54:57]
	v_mfma_f32_16x16x32_bf16 v[46:49], v[134:137], v[190:193], v[46:49]
	v_mfma_f32_16x16x32_bf16 v[38:41], v[142:145], v[190:193], v[38:41]
	v_mfma_f32_16x16x32_bf16 v[30:33], v[134:137], v[198:201], v[30:33]
	v_mfma_f32_16x16x32_bf16 v[22:25], v[142:145], v[198:201], v[22:25]
	v_mfma_f32_16x16x32_bf16 v[14:17], v[134:137], v[212:215], v[14:17]
	v_mfma_f32_16x16x32_bf16 v[6:9], v[142:145], v[212:215], v[6:9]
	s_setprio 0
	s_setprio 1
	v_mfma_f32_16x16x32_bf16 v[58:61], v[146:149], v[172:175], v[58:61]
	v_mfma_f32_16x16x32_bf16 v[50:53], v[154:157], v[172:175], v[50:53]
	v_mfma_f32_16x16x32_bf16 v[42:45], v[146:149], v[180:183], v[42:45]
	v_mfma_f32_16x16x32_bf16 v[34:37], v[154:157], v[180:183], v[34:37]
	v_mfma_f32_16x16x32_bf16 v[26:29], v[146:149], v[194:197], v[26:29]
	v_mfma_f32_16x16x32_bf16 v[18:21], v[154:157], v[194:197], v[18:21]
	v_mfma_f32_16x16x32_bf16 v[10:13], v[146:149], v[208:211], v[10:13]
	v_mfma_f32_16x16x32_bf16 v[2:5], v[154:157], v[208:211], v[2:5]
	v_mfma_f32_16x16x32_bf16 v[58:61], v[150:153], v[176:179], v[58:61]
	v_mfma_f32_16x16x32_bf16 v[50:53], v[158:161], v[176:179], v[50:53]
	v_mfma_f32_16x16x32_bf16 v[42:45], v[150:153], v[190:193], v[42:45]
	v_mfma_f32_16x16x32_bf16 v[34:37], v[158:161], v[190:193], v[34:37]
	v_mfma_f32_16x16x32_bf16 v[26:29], v[150:153], v[198:201], v[26:29]
	v_mfma_f32_16x16x32_bf16 v[18:21], v[158:161], v[198:201], v[18:21]
	v_mfma_f32_16x16x32_bf16 v[10:13], v[150:153], v[212:215], v[10:13]
	v_mfma_f32_16x16x32_bf16 v[2:5], v[158:161], v[212:215], v[2:5]
	s_barrier
	s_setprio 0
	s_add_i32 s61, s61, 2
	s_add_u32 s26, s26, 0x100
	s_addc_u32 s27, s27, 0
	s_add_u32 s59, s59, 0x100
	s_addc_u32 s60, s60, 0
	s_cmp_gt_u32 s61, 29
	s_cbranch_scc0 .LBB0_1428
	s_and_b64 vcc, exec, s[10:11]
	s_cbranch_vccz .LBB0_1431
	s_barrier

.LBB0_1588:
	v_lshrrev_b32_e32 v18, 1, v16
	v_and_b32_e32 v18, 24, v18
	v_and_b32_e32 v17, 15, v16
	v_lshlrev_b32_e32 v19, 1, v18
	v_lshlrev_b32_e32 v16, 2, v16
	v_lshl_or_b32 v142, s14, 6, v17
	v_lshl_or_b32 v17, v17, 6, v19
	s_lshl_b32 s0, s14, 13
	v_and_b32_e32 v16, 32, v16
	v_bitop3_b32 v19, v17, s0, v16 bitop3:0xde
	s_lshl_b32 s0, s9, 5
	s_and_b32 s9, s0, 0x60
	s_add_i32 m0, s25, 0x18000
	v_lshl_add_u64 v[8:9], v[8:9], 0, s[80:81]
	s_lshl_b32 s0, s9, 7
	s_waitcnt vmcnt(2)
	s_barrier
	global_load_lds_dwordx4 v[8:9], off
	v_lshl_add_u64 v[6:7], v[6:7], 0, s[80:81]
	s_add_i32 m0, s25, 0x1a000
	s_add_i32 s39, s25, 0x8000
	s_add_i32 s40, s25, 0xa000
	v_bitop3_b32 v143, v17, s0, v16 bitop3:0xde
	v_add_u32_e32 v143, 0x10000, v143
	global_load_lds_dwordx4 v[6:7], off
	v_lshl_add_u64 v[2:3], v[2:3], 0, s[80:81]
	s_mov_b32 m0, s39
	s_add_u32 s0, s2, 0x80080
	global_load_lds_dwordx4 v[2:3], off
	v_lshl_add_u64 v[2:3], v[4:5], 0, s[80:81]
	s_mov_b32 m0, s40
	s_addc_u32 s1, s3, 0
	global_load_lds_dwordx4 v[2:3], off
	s_add_i32 m0, s25, 0x1c000
	v_lshl_add_u64 v[2:3], s[0:1], 0, v[202:203]
	global_load_lds_dwordx4 v[2:3], off
	v_lshl_add_u64 v[2:3], s[0:1], 0, v[130:131]
	s_add_i32 m0, s25, 0x1e000
	s_cmpk_lt_u32 s8, 0x100
	global_load_lds_dwordx4 v[2:3], off
	v_lshlrev_b32_e32 v2, 15, v14
	v_and_b32_e32 v2, 0xffff0000, v2
	v_lshl_add_u32 v2, v13, 12, v2
	v_and_b32_e32 v3, 1, v14
	v_lshl_or_b32 v2, v3, 6, v2
	v_lshl_add_u32 v136, v15, 1, v2
	v_lshlrev_b32_e32 v2, 15, v10
	v_and_b32_e32 v2, 0xffff0000, v2
	s_waitcnt vmcnt(6)
	v_lshl_add_u32 v2, v11, 12, v2
	v_and_b32_e32 v3, 1, v10
	v_lshl_or_b32 v2, v3, 6, v2
	s_cselect_b64 s[14:15], -1, 0
	v_or_b32_e32 v144, s9, v18
	v_mov_b32_e32 v137, v203
	v_lshl_add_u32 v138, v12, 1, v2
	v_mov_b32_e32 v139, v203
	s_mov_b32 s41, 0
	v_add_u32_e32 v145, 0, v19
	s_barrier
	s_waitcnt vmcnt(0)
	s_branch .LBB0_1591

.LBB0_1594:
	s_add_u32 s0, s28, 0xfff80080
	s_addc_u32 s1, s29, -1
	s_add_i32 s33, 0, 0x10000
	s_cmp_eq_u32 s61, 28
	s_cselect_b32 s5, s19, s1
	s_cselect_b32 s4, s49, s0
	s_cselect_b32 s3, s17, s60
	s_cselect_b32 s2, s58, s59
	s_add_i32 s55, 0, 0x14000
	ds_read_b128 v[146:149], v143
	ds_read_b128 v[150:153], v143 offset:1024
	ds_read_b128 v[154:157], v143 offset:2048
	ds_read_b128 v[158:161], v143 offset:3072
	ds_read_b128 v[162:165], v143 offset:16384
	ds_read_b128 v[166:169], v143 offset:17408
	ds_read_b128 v[170:173], v143 offset:18432
	ds_read_b128 v[174:177], v143 offset:19456
	s_add_i32 m0, s25, 0xc000
	ds_read_b128 v[178:181], v145
	ds_read_b128 v[182:185], v145 offset:1024
	ds_read_b128 v[186:189], v145 offset:2048
	ds_read_b128 v[190:193], v145 offset:3072
	ds_read_b128 v[194:197], v145 offset:4096
	ds_read_b128 v[198:201], v145 offset:5120
	ds_read_b128 v[208:211], v145 offset:6144
	ds_read_b128 v[212:215], v145 offset:7168
	global_load_lds_dwordx4 v136, s[28:29]
	s_add_i32 m0, s25, 0xe000
	s_nop 0
	global_load_lds_dwordx4 v138, s[28:29]
	s_waitcnt vmcnt(8)
	s_waitcnt lgkmcnt(0)
	s_setprio 1
	s_barrier
	v_mfma_f32_16x16x32_bf16 v[126:129], v[146:149], v[178:181], v[126:129]
	v_mfma_f32_16x16x32_bf16 v[118:121], v[154:157], v[178:181], v[118:121]
	v_mfma_f32_16x16x32_bf16 v[110:113], v[146:149], v[186:189], v[110:113]
	v_mfma_f32_16x16x32_bf16 v[102:105], v[154:157], v[186:189], v[102:105]
	v_mfma_f32_16x16x32_bf16 v[94:97], v[146:149], v[194:197], v[94:97]
	v_mfma_f32_16x16x32_bf16 v[86:89], v[154:157], v[194:197], v[86:89]
	v_mfma_f32_16x16x32_bf16 v[78:81], v[146:149], v[208:211], v[78:81]
	v_mfma_f32_16x16x32_bf16 v[70:73], v[154:157], v[208:211], v[70:73]
	v_mfma_f32_16x16x32_bf16 v[126:129], v[150:153], v[182:185], v[126:129]
	v_mfma_f32_16x16x32_bf16 v[118:121], v[158:161], v[182:185], v[118:121]
	v_mfma_f32_16x16x32_bf16 v[110:113], v[150:153], v[190:193], v[110:113]
	v_mfma_f32_16x16x32_bf16 v[102:105], v[158:161], v[190:193], v[102:105]
	v_mfma_f32_16x16x32_bf16 v[94:97], v[150:153], v[198:201], v[94:97]
	v_mfma_f32_16x16x32_bf16 v[86:89], v[158:161], v[198:201], v[86:89]
	v_mfma_f32_16x16x32_bf16 v[78:81], v[150:153], v[212:215], v[78:81]
	v_mfma_f32_16x16x32_bf16 v[70:73], v[158:161], v[212:215], v[70:73]
	s_setprio 0
	s_setprio 1
	v_mfma_f32_16x16x32_bf16 v[122:125], v[162:165], v[178:181], v[122:125]
	v_mfma_f32_16x16x32_bf16 v[114:117], v[170:173], v[178:181], v[114:117]
	v_mfma_f32_16x16x32_bf16 v[106:109], v[162:165], v[186:189], v[106:109]
	v_mfma_f32_16x16x32_bf16 v[98:101], v[170:173], v[186:189], v[98:101]
	v_mfma_f32_16x16x32_bf16 v[90:93], v[162:165], v[194:197], v[90:93]
	v_mfma_f32_16x16x32_bf16 v[82:85], v[170:173], v[194:197], v[82:85]
	v_mfma_f32_16x16x32_bf16 v[74:77], v[162:165], v[208:211], v[74:77]
	v_mfma_f32_16x16x32_bf16 v[66:69], v[170:173], v[208:211], v[66:69]
	v_mfma_f32_16x16x32_bf16 v[122:125], v[166:169], v[182:185], v[122:125]
	v_mfma_f32_16x16x32_bf16 v[114:117], v[174:177], v[182:185], v[114:117]
	v_mfma_f32_16x16x32_bf16 v[106:109], v[166:169], v[190:193], v[106:109]
	v_mfma_f32_16x16x32_bf16 v[98:101], v[174:177], v[190:193], v[98:101]
	v_mfma_f32_16x16x32_bf16 v[90:93], v[166:169], v[198:201], v[90:93]
	v_mfma_f32_16x16x32_bf16 v[82:85], v[174:177], v[198:201], v[82:85]
	v_mfma_f32_16x16x32_bf16 v[74:77], v[166:169], v[212:215], v[74:77]
	v_mfma_f32_16x16x32_bf16 v[66:69], v[174:177], v[212:215], v[66:69]
	s_barrier
	s_setprio 0
	s_add_i32 s0, s33, s36
	s_mov_b32 m0, s0
	ds_read_b128 v[178:181], v145 offset:16384
	ds_read_b128 v[182:185], v145 offset:17408
	ds_read_b128 v[186:189], v145 offset:18432
	ds_read_b128 v[190:193], v145 offset:19456
	ds_read_b128 v[194:197], v145 offset:20480
	ds_read_b128 v[198:201], v145 offset:21504
	ds_read_b128 v[208:211], v145 offset:22528
	ds_read_b128 v[212:215], v145 offset:23552
	global_load_lds_dwordx4 v202, s[2:3]
	s_add_i32 m0, s0, 0x2000
	s_add_u32 s0, s2, 0x80000
	s_addc_u32 s1, s3, 0
	s_add_i32 s33, s55, s36
	global_load_lds_dwordx4 v130, s[2:3]
	s_mov_b32 m0, s33
	s_nop 0
	global_load_lds_dwordx4 v202, s[0:1]
	s_add_i32 m0, s33, 0x2000
	s_nop 0
	global_load_lds_dwordx4 v130, s[0:1]
	s_mov_b32 m0, s25
	s_nop 0
	global_load_lds_dwordx4 v134, s[4:5]
	s_mov_b32 m0, s27
	s_nop 0
	global_load_lds_dwordx4 v132, s[4:5]
	s_waitcnt vmcnt(8)
	s_waitcnt lgkmcnt(0)
	s_setprio 1
	s_barrier
	v_mfma_f32_16x16x32_bf16 v[62:65], v[146:149], v[178:181], v[62:65]
	v_mfma_f32_16x16x32_bf16 v[54:57], v[154:157], v[178:181], v[54:57]
	v_mfma_f32_16x16x32_bf16 v[46:49], v[146:149], v[186:189], v[46:49]
	v_mfma_f32_16x16x32_bf16 v[38:41], v[154:157], v[186:189], v[38:41]
	v_mfma_f32_16x16x32_bf16 v[30:33], v[146:149], v[194:197], v[30:33]
	v_mfma_f32_16x16x32_bf16 v[22:25], v[154:157], v[194:197], v[22:25]
	v_mfma_f32_16x16x32_bf16 v[14:17], v[146:149], v[208:211], v[14:17]
	v_mfma_f32_16x16x32_bf16 v[6:9], v[154:157], v[208:211], v[6:9]
	v_mfma_f32_16x16x32_bf16 v[62:65], v[150:153], v[182:185], v[62:65]
	v_mfma_f32_16x16x32_bf16 v[54:57], v[158:161], v[182:185], v[54:57]
	v_mfma_f32_16x16x32_bf16 v[46:49], v[150:153], v[190:193], v[46:49]
	v_mfma_f32_16x16x32_bf16 v[38:41], v[158:161], v[190:193], v[38:41]
	v_mfma_f32_16x16x32_bf16 v[30:33], v[150:153], v[198:201], v[30:33]
	v_mfma_f32_16x16x32_bf16 v[22:25], v[158:161], v[198:201], v[22:25]
	v_mfma_f32_16x16x32_bf16 v[14:17], v[150:153], v[212:215], v[14:17]
	v_mfma_f32_16x16x32_bf16 v[6:9], v[158:161], v[212:215], v[6:9]
	s_setprio 0
	s_setprio 1
	v_mfma_f32_16x16x32_bf16 v[58:61], v[162:165], v[178:181], v[58:61]
	v_mfma_f32_16x16x32_bf16 v[50:53], v[170:173], v[178:181], v[50:53]
	v_mfma_f32_16x16x32_bf16 v[42:45], v[162:165], v[186:189], v[42:45]
	v_mfma_f32_16x16x32_bf16 v[34:37], v[170:173], v[186:189], v[34:37]
	v_mfma_f32_16x16x32_bf16 v[26:29], v[162:165], v[194:197], v[26:29]
	v_mfma_f32_16x16x32_bf16 v[18:21], v[170:173], v[194:197], v[18:21]
	v_mfma_f32_16x16x32_bf16 v[10:13], v[162:165], v[208:211], v[10:13]
	v_mfma_f32_16x16x32_bf16 v[2:5], v[170:173], v[208:211], v[2:5]
	v_mfma_f32_16x16x32_bf16 v[58:61], v[166:169], v[182:185], v[58:61]
	v_mfma_f32_16x16x32_bf16 v[50:53], v[174:177], v[182:185], v[50:53]
	v_mfma_f32_16x16x32_bf16 v[42:45], v[166:169], v[190:193], v[42:45]
	v_mfma_f32_16x16x32_bf16 v[34:37], v[174:177], v[190:193], v[34:37]
	v_mfma_f32_16x16x32_bf16 v[26:29], v[166:169], v[198:201], v[26:29]
	v_mfma_f32_16x16x32_bf16 v[18:21], v[174:177], v[198:201], v[18:21]
	v_mfma_f32_16x16x32_bf16 v[10:13], v[166:169], v[212:215], v[10:13]
	v_mfma_f32_16x16x32_bf16 v[2:5], v[174:177], v[212:215], v[2:5]
	s_barrier
	s_setprio 0
	s_add_i32 s33, 0, 0x18000
	s_add_i32 s55, 0, 0x1c000
	ds_read_b128 v[146:149], v143 offset:32768
	ds_read_b128 v[150:153], v143 offset:33792
	ds_read_b128 v[154:157], v143 offset:34816
	ds_read_b128 v[158:161], v143 offset:35840
	ds_read_b128 v[162:165], v143 offset:49152
	ds_read_b128 v[166:169], v143 offset:50176
	ds_read_b128 v[170:173], v143 offset:51200
	ds_read_b128 v[174:177], v143 offset:52224
	s_add_u32 s0, s4, 0x80000
	s_addc_u32 s1, s5, 0
	s_mov_b32 m0, s37
	ds_read_b128 v[178:181], v145 offset:32768
	ds_read_b128 v[182:185], v145 offset:33792
	ds_read_b128 v[186:189], v145 offset:34816
	ds_read_b128 v[190:193], v145 offset:35840
	ds_read_b128 v[194:197], v145 offset:36864
	ds_read_b128 v[198:201], v145 offset:37888
	ds_read_b128 v[208:211], v145 offset:38912
	ds_read_b128 v[212:215], v145 offset:39936
	global_load_lds_dwordx4 v134, s[0:1]
	s_mov_b32 m0, s38
	s_nop 0
	global_load_lds_dwordx4 v132, s[0:1]
	s_waitcnt vmcnt(8)
	s_waitcnt lgkmcnt(0)
	s_setprio 1
	s_barrier
	v_mfma_f32_16x16x32_bf16 v[126:129], v[146:149], v[178:181], v[126:129]
	v_mfma_f32_16x16x32_bf16 v[118:121], v[154:157], v[178:181], v[118:121]
	v_mfma_f32_16x16x32_bf16 v[110:113], v[146:149], v[186:189], v[110:113]
	v_mfma_f32_16x16x32_bf16 v[102:105], v[154:157], v[186:189], v[102:105]
	v_mfma_f32_16x16x32_bf16 v[94:97], v[146:149], v[194:197], v[94:97]
	v_mfma_f32_16x16x32_bf16 v[86:89], v[154:157], v[194:197], v[86:89]
	v_mfma_f32_16x16x32_bf16 v[78:81], v[146:149], v[208:211], v[78:81]
	v_mfma_f32_16x16x32_bf16 v[70:73], v[154:157], v[208:211], v[70:73]
	v_mfma_f32_16x16x32_bf16 v[126:129], v[150:153], v[182:185], v[126:129]
	v_mfma_f32_16x16x32_bf16 v[118:121], v[158:161], v[182:185], v[118:121]
	v_mfma_f32_16x16x32_bf16 v[110:113], v[150:153], v[190:193], v[110:113]
	v_mfma_f32_16x16x32_bf16 v[102:105], v[158:161], v[190:193], v[102:105]
	v_mfma_f32_16x16x32_bf16 v[94:97], v[150:153], v[198:201], v[94:97]
	v_mfma_f32_16x16x32_bf16 v[86:89], v[158:161], v[198:201], v[86:89]
	v_mfma_f32_16x16x32_bf16 v[78:81], v[150:153], v[212:215], v[78:81]
	v_mfma_f32_16x16x32_bf16 v[70:73], v[158:161], v[212:215], v[70:73]
	s_setprio 0
	s_setprio 1
	v_mfma_f32_16x16x32_bf16 v[122:125], v[162:165], v[178:181], v[122:125]
	v_mfma_f32_16x16x32_bf16 v[114:117], v[170:173], v[178:181], v[114:117]
	v_mfma_f32_16x16x32_bf16 v[106:109], v[162:165], v[186:189], v[106:109]
	v_mfma_f32_16x16x32_bf16 v[98:101], v[170:173], v[186:189], v[98:101]
	v_mfma_f32_16x16x32_bf16 v[90:93], v[162:165], v[194:197], v[90:93]
	v_mfma_f32_16x16x32_bf16 v[82:85], v[170:173], v[194:197], v[82:85]
	v_mfma_f32_16x16x32_bf16 v[74:77], v[162:165], v[208:211], v[74:77]
	v_mfma_f32_16x16x32_bf16 v[66:69], v[170:173], v[208:211], v[66:69]
	v_mfma_f32_16x16x32_bf16 v[122:125], v[166:169], v[182:185], v[122:125]
	v_mfma_f32_16x16x32_bf16 v[114:117], v[174:177], v[182:185], v[114:117]
	v_mfma_f32_16x16x32_bf16 v[106:109], v[166:169], v[190:193], v[106:109]
	v_mfma_f32_16x16x32_bf16 v[98:101], v[174:177], v[190:193], v[98:101]
	v_mfma_f32_16x16x32_bf16 v[90:93], v[166:169], v[198:201], v[90:93]
	v_mfma_f32_16x16x32_bf16 v[82:85], v[174:177], v[198:201], v[82:85]
	v_mfma_f32_16x16x32_bf16 v[74:77], v[166:169], v[212:215], v[74:77]
	v_mfma_f32_16x16x32_bf16 v[66:69], v[174:177], v[212:215], v[66:69]
	s_barrier
	s_setprio 0
	s_add_i32 s0, s33, s36
	s_add_u32 s100, s2, 0x80
	s_addc_u32 s101, s3, 0
	s_mov_b32 m0, s0
	ds_read_b128 v[178:181], v145 offset:49152
	ds_read_b128 v[182:185], v145 offset:50176
	ds_read_b128 v[186:189], v145 offset:51200
	ds_read_b128 v[190:193], v145 offset:52224
	ds_read_b128 v[194:197], v145 offset:53248
	ds_read_b128 v[198:201], v145 offset:54272
	ds_read_b128 v[208:211], v145 offset:55296
	ds_read_b128 v[212:215], v145 offset:56320
	global_load_lds_dwordx4 v202, s[100:101]
	s_add_i32 m0, s0, 0x2000
	s_add_u32 s100, s2, 0x80
	s_addc_u32 s101, s3, 0
	s_add_u32 s0, s2, 0x80080
	s_addc_u32 s1, s3, 0
	s_add_i32 s2, s55, s36
	global_load_lds_dwordx4 v130, s[100:101]
	s_mov_b32 m0, s2
	s_nop 0
	global_load_lds_dwordx4 v202, s[0:1]
	s_add_i32 m0, s2, 0x2000
	s_nop 0
	global_load_lds_dwordx4 v130, s[0:1]
	s_add_u32 s100, s4, 0x80
	s_addc_u32 s101, s5, 0
	s_mov_b32 m0, s39
	s_nop 0
	global_load_lds_dwordx4 v134, s[100:101]
	s_add_u32 s100, s4, 0x80
	s_addc_u32 s101, s5, 0
	s_mov_b32 m0, s40
	s_nop 0
	global_load_lds_dwordx4 v132, s[100:101]
	s_waitcnt vmcnt(8)
	s_waitcnt lgkmcnt(0)
	s_setprio 1
	s_barrier
	v_mfma_f32_16x16x32_bf16 v[62:65], v[146:149], v[178:181], v[62:65]
	v_mfma_f32_16x16x32_bf16 v[54:57], v[154:157], v[178:181], v[54:57]
	v_mfma_f32_16x16x32_bf16 v[46:49], v[146:149], v[186:189], v[46:49]
	v_mfma_f32_16x16x32_bf16 v[38:41], v[154:157], v[186:189], v[38:41]
	v_mfma_f32_16x16x32_bf16 v[30:33], v[146:149], v[194:197], v[30:33]
	v_mfma_f32_16x16x32_bf16 v[22:25], v[154:157], v[194:197], v[22:25]
	v_mfma_f32_16x16x32_bf16 v[14:17], v[146:149], v[208:211], v[14:17]
	v_mfma_f32_16x16x32_bf16 v[6:9], v[154:157], v[208:211], v[6:9]
	v_mfma_f32_16x16x32_bf16 v[62:65], v[150:153], v[182:185], v[62:65]
	v_mfma_f32_16x16x32_bf16 v[54:57], v[158:161], v[182:185], v[54:57]
	v_mfma_f32_16x16x32_bf16 v[46:49], v[150:153], v[190:193], v[46:49]
	v_mfma_f32_16x16x32_bf16 v[38:41], v[158:161], v[190:193], v[38:41]
	v_mfma_f32_16x16x32_bf16 v[30:33], v[150:153], v[198:201], v[30:33]
	v_mfma_f32_16x16x32_bf16 v[22:25], v[158:161], v[198:201], v[22:25]
	v_mfma_f32_16x16x32_bf16 v[14:17], v[150:153], v[212:215], v[14:17]
	v_mfma_f32_16x16x32_bf16 v[6:9], v[158:161], v[212:215], v[6:9]
	s_setprio 0
	s_setprio 1
	v_mfma_f32_16x16x32_bf16 v[58:61], v[162:165], v[178:181], v[58:61]
	v_mfma_f32_16x16x32_bf16 v[50:53], v[170:173], v[178:181], v[50:53]
	v_mfma_f32_16x16x32_bf16 v[42:45], v[162:165], v[186:189], v[42:45]
	v_mfma_f32_16x16x32_bf16 v[34:37], v[170:173], v[186:189], v[34:37]
	v_mfma_f32_16x16x32_bf16 v[26:29], v[162:165], v[194:197], v[26:29]
	v_mfma_f32_16x16x32_bf16 v[18:21], v[170:173], v[194:197], v[18:21]
	v_mfma_f32_16x16x32_bf16 v[10:13], v[162:165], v[208:211], v[10:13]
	v_mfma_f32_16x16x32_bf16 v[2:5], v[170:173], v[208:211], v[2:5]
	v_mfma_f32_16x16x32_bf16 v[58:61], v[166:169], v[182:185], v[58:61]
	v_mfma_f32_16x16x32_bf16 v[50:53], v[174:177], v[182:185], v[50:53]
	v_mfma_f32_16x16x32_bf16 v[42:45], v[166:169], v[190:193], v[42:45]
	v_mfma_f32_16x16x32_bf16 v[34:37], v[174:177], v[190:193], v[34:37]
	v_mfma_f32_16x16x32_bf16 v[26:29], v[166:169], v[198:201], v[26:29]
	v_mfma_f32_16x16x32_bf16 v[18:21], v[174:177], v[198:201], v[18:21]
	v_mfma_f32_16x16x32_bf16 v[10:13], v[166:169], v[212:215], v[10:13]
	v_mfma_f32_16x16x32_bf16 v[2:5], v[174:177], v[212:215], v[2:5]
	s_barrier
	s_setprio 0
	s_add_i32 s61, s61, 2
	s_add_u32 s28, s28, 0x100
	s_addc_u32 s29, s29, 0
	s_add_u32 s59, s59, 0x100
	s_addc_u32 s60, s60, 0
	s_cmp_gt_u32 s61, 29
	s_cbranch_scc0 .LBB0_1594
	s_and_b64 vcc, exec, s[14:15]
	s_cbranch_vccz .LBB0_1597
	s_barrier

.LBB0_1704:
	v_readlane_b32 s8, v254, 58
	v_readlane_b32 s9, v254, 59
	s_add_u32 s31, s8, 0xa000
	v_lshrrev_b32_e32 v20, 1, v14
	v_readlane_b32 s4, v253, 52
	s_addc_u32 s34, s9, 0
	v_and_b32_e32 v20, 24, v20
	s_lshl_b32 s0, s0, 5
	v_mov_b32_e32 v213, v203
	v_readlane_b32 s5, v253, 53
	v_and_b32_e32 v15, 15, v14
	v_lshlrev_b32_e32 v21, 1, v20
	v_lshlrev_b32_e32 v14, 2, v14
	s_and_b32 s3, s0, 0x60
	s_add_i32 m0, s27, 0x18000
	v_lshl_add_u64 v[2:3], v[2:3], 0, s[80:81]
	v_lshl_add_u64 v[16:17], s[4:5], 0, v[212:213]
	v_mov_b32_e32 v211, v203
	v_lshl_or_b32 v204, s1, 6, v15
	v_lshl_or_b32 v15, v15, 6, v21
	s_lshl_b32 s1, s1, 13
	v_and_b32_e32 v14, 32, v14
	s_lshl_b32 s0, s3, 7
	s_waitcnt vmcnt(2)
	s_barrier
	global_load_lds_dwordx4 v[2:3], off
	v_lshl_add_u64 v[2:3], v[4:5], 0, s[80:81]
	s_add_i32 m0, s27, 0x1a000
	s_add_i32 s35, s27, 0x8000
	s_add_i32 s36, s27, 0xa000
	v_lshl_add_u64 v[18:19], s[4:5], 0, v[210:211]
	v_bitop3_b32 v205, v15, s0, v14 bitop3:0xde
	v_add_u32_e32 v205, 0x10000, v205
	global_load_lds_dwordx4 v[2:3], off
	v_lshl_add_u64 v[2:3], v[16:17], 0, s[80:81]
	s_mov_b32 m0, s35
	s_add_u32 s0, s18, 0x160080
	v_bitop3_b32 v21, v15, s1, v14 bitop3:0xde
	global_load_lds_dwordx4 v[2:3], off
	v_lshl_add_u64 v[2:3], v[18:19], 0, s[80:81]
	s_mov_b32 m0, s36
	s_addc_u32 s1, s19, 0
	global_load_lds_dwordx4 v[2:3], off
	s_add_i32 m0, s27, 0x1c000
	v_lshl_add_u64 v[2:3], s[0:1], 0, v[202:203]
	global_load_lds_dwordx4 v[2:3], off
	v_lshl_add_u64 v[2:3], s[0:1], 0, v[208:209]
	s_add_i32 m0, s27, 0x1e000
	v_or_b32_e32 v238, s3, v20
	global_load_lds_dwordx4 v[2:3], off
	s_movk_i32 s3, 0x1600
	s_cmpk_lt_u32 s2, 0x100
	v_lshrrev_b32_e32 v3, 1, v11
	v_mul_lo_u32 v2, v10, s3
	s_mov_b32 s2, 0x16000
	v_mad_u64_u32 v[2:3], s[0:1], v3, s2, v[2:3]
	v_or_b32_e32 v2, v2, v12
	v_add_lshl_u32 v2, v2, v13, 1
	v_mov_b32_e32 v3, v203
	s_mov_b64 s[8:9], 0x160080
	v_lshl_add_u64 v[214:215], v[2:3], 0, s[8:9]
	v_lshrrev_b32_e32 v3, 1, v6
	v_mul_lo_u32 v2, v7, s3
	v_mad_u64_u32 v[2:3], s[0:1], v3, s2, v[2:3]
	s_waitcnt vmcnt(6)
	v_or_b32_e32 v2, v2, v8
	v_add_lshl_u32 v2, v2, v9, 1
	v_mov_b32_e32 v3, v203
	v_readlane_b32 s0, v253, 50
	s_cselect_b64 s[14:15], -1, 0
	v_lshl_add_u64 v[216:217], v[2:3], 0, s[8:9]
	s_mov_b32 s37, 0
	v_add_u32_e32 v239, 0, v21
	v_readlane_b32 s41, v254, 44
	s_mov_b32 s40, s0
	s_barrier
	v_readlane_b32 s1, v253, 51
	s_branch .LBB0_1707

.LBB0_1718:
	s_add_u32 s18, s4, 0x100
	s_addc_u32 s19, s5, 0
	s_add_i32 s0, 0, 0x10000
	s_cmpk_eq_i32 s59, 0x54
	s_cselect_b32 s23, s9, s19
	s_cselect_b32 s22, s8, s18
	s_cselect_b32 s21, s17, s58
	s_cselect_b32 s20, s16, s49
	s_add_i32 s33, 0, 0x14000
	ds_read_b128 v[78:81], v205
	ds_read_b128 v[82:85], v205 offset:1024
	ds_read_b128 v[94:97], v205 offset:2048
	ds_read_b128 v[98:101], v205 offset:3072
	ds_read_b128 v[106:109], v205 offset:16384
	ds_read_b128 v[110:113], v205 offset:17408
	ds_read_b128 v[126:129], v205 offset:18432
	ds_read_b128 v[134:137], v205 offset:19456
	s_add_i32 m0, s27, 0xc000
	ds_read_b128 v[146:149], v239
	ds_read_b128 v[158:161], v239 offset:1024
	ds_read_b128 v[166:169], v239 offset:2048
	ds_read_b128 v[174:177], v239 offset:3072
	ds_read_b128 v[178:181], v239 offset:4096
	ds_read_b128 v[182:185], v239 offset:5120
	ds_read_b128 v[186:189], v239 offset:6144
	ds_read_b128 v[190:193], v239 offset:7168
	global_load_lds_dwordx4 v214, s[4:5]
	s_add_i32 m0, s27, 0xe000
	s_nop 0
	global_load_lds_dwordx4 v216, s[4:5]
	s_waitcnt vmcnt(8)
	s_waitcnt lgkmcnt(0)
	s_setprio 1
	s_barrier
	v_mfma_f32_16x16x32_bf16 v[170:173], v[78:81], v[146:149], v[170:173]
	v_mfma_f32_16x16x32_bf16 v[162:165], v[94:97], v[146:149], v[162:165]
	v_mfma_f32_16x16x32_bf16 v[142:145], v[78:81], v[166:169], v[142:145]
	v_mfma_f32_16x16x32_bf16 v[138:141], v[94:97], v[166:169], v[138:141]
	v_mfma_f32_16x16x32_bf16 v[118:121], v[78:81], v[178:181], v[118:121]
	v_mfma_f32_16x16x32_bf16 v[114:117], v[94:97], v[178:181], v[114:117]
	v_mfma_f32_16x16x32_bf16 v[86:89], v[78:81], v[186:189], v[86:89]
	v_mfma_f32_16x16x32_bf16 v[74:77], v[94:97], v[186:189], v[74:77]
	v_mfma_f32_16x16x32_bf16 v[170:173], v[82:85], v[158:161], v[170:173]
	v_mfma_f32_16x16x32_bf16 v[162:165], v[98:101], v[158:161], v[162:165]
	v_mfma_f32_16x16x32_bf16 v[142:145], v[82:85], v[174:177], v[142:145]
	v_mfma_f32_16x16x32_bf16 v[138:141], v[98:101], v[174:177], v[138:141]
	v_mfma_f32_16x16x32_bf16 v[118:121], v[82:85], v[182:185], v[118:121]
	v_mfma_f32_16x16x32_bf16 v[114:117], v[98:101], v[182:185], v[114:117]
	v_mfma_f32_16x16x32_bf16 v[86:89], v[82:85], v[190:193], v[86:89]
	v_mfma_f32_16x16x32_bf16 v[74:77], v[98:101], v[190:193], v[74:77]
	s_setprio 0
	s_setprio 1
	v_mfma_f32_16x16x32_bf16 v[154:157], v[106:109], v[146:149], v[154:157]
	v_mfma_f32_16x16x32_bf16 v[130:133], v[106:109], v[166:169], v[130:133]
	v_mfma_f32_16x16x32_bf16 v[122:125], v[126:129], v[166:169], v[122:125]
	v_mfma_f32_16x16x32_bf16 v[102:105], v[106:109], v[178:181], v[102:105]
	v_mfma_f32_16x16x32_bf16 v[90:93], v[126:129], v[178:181], v[90:93]
	v_mfma_f32_16x16x32_bf16 v[70:73], v[106:109], v[186:189], v[70:73]
	v_mfma_f32_16x16x32_bf16 v[66:69], v[126:129], v[186:189], v[66:69]
	v_mfma_f32_16x16x32_bf16 v[154:157], v[110:113], v[158:161], v[154:157]
	v_mfma_f32_16x16x32_bf16 v[146:149], v[126:129], v[146:149], v[150:153]
	v_mfma_f32_16x16x32_bf16 v[130:133], v[110:113], v[174:177], v[130:133]
	v_mfma_f32_16x16x32_bf16 v[122:125], v[134:137], v[174:177], v[122:125]
	v_mfma_f32_16x16x32_bf16 v[102:105], v[110:113], v[182:185], v[102:105]
	v_mfma_f32_16x16x32_bf16 v[90:93], v[134:137], v[182:185], v[90:93]
	v_mfma_f32_16x16x32_bf16 v[70:73], v[110:113], v[190:193], v[70:73]
	v_mfma_f32_16x16x32_bf16 v[66:69], v[134:137], v[190:193], v[66:69]
	v_mfma_f32_16x16x32_bf16 v[146:149], v[134:137], v[158:161], v[146:149]
	s_barrier
	s_setprio 0
	s_add_i32 s0, s0, s26
	s_mov_b32 m0, s0
	ds_read_b128 v[150:153], v239 offset:16384
	ds_read_b128 v[158:161], v239 offset:17408
	ds_read_b128 v[166:169], v239 offset:18432
	ds_read_b128 v[174:177], v239 offset:19456
	ds_read_b128 v[178:181], v239 offset:20480
	ds_read_b128 v[182:185], v239 offset:21504
	ds_read_b128 v[186:189], v239 offset:22528
	ds_read_b128 v[190:193], v239 offset:23552
	global_load_lds_dwordx4 v202, s[20:21]
	s_add_i32 m0, s0, 0x2000
	s_add_u32 s0, s20, 0x160000
	s_addc_u32 s1, s21, 0
	s_add_i32 s4, s33, s26
	global_load_lds_dwordx4 v208, s[20:21]
	s_mov_b32 m0, s4
	s_nop 0
	global_load_lds_dwordx4 v202, s[0:1]
	s_add_i32 m0, s4, 0x2000
	s_nop 0
	global_load_lds_dwordx4 v208, s[0:1]
	s_mov_b32 m0, s27
	s_nop 0
	global_load_lds_dwordx4 v212, s[22:23]
	s_mov_b32 m0, s28
	s_nop 0
	global_load_lds_dwordx4 v210, s[22:23]
	s_waitcnt vmcnt(8)
	s_waitcnt lgkmcnt(0)
	s_setprio 1
	s_barrier
	v_mfma_f32_16x16x32_bf16 v[62:65], v[78:81], v[150:153], v[62:65]
	v_mfma_f32_16x16x32_bf16 v[58:61], v[94:97], v[150:153], v[58:61]
	v_mfma_f32_16x16x32_bf16 v[46:49], v[78:81], v[166:169], v[46:49]
	v_mfma_f32_16x16x32_bf16 v[42:45], v[94:97], v[166:169], v[42:45]
	v_mfma_f32_16x16x32_bf16 v[30:33], v[78:81], v[178:181], v[30:33]
	v_mfma_f32_16x16x32_bf16 v[26:29], v[94:97], v[178:181], v[26:29]
	v_mfma_f32_16x16x32_bf16 v[14:17], v[78:81], v[186:189], v[14:17]
	v_mfma_f32_16x16x32_bf16 v[10:13], v[94:97], v[186:189], v[10:13]
	v_mfma_f32_16x16x32_bf16 v[62:65], v[82:85], v[158:161], v[62:65]
	v_mfma_f32_16x16x32_bf16 v[58:61], v[98:101], v[158:161], v[58:61]
	v_mfma_f32_16x16x32_bf16 v[46:49], v[82:85], v[174:177], v[46:49]
	v_mfma_f32_16x16x32_bf16 v[42:45], v[98:101], v[174:177], v[42:45]
	v_mfma_f32_16x16x32_bf16 v[30:33], v[82:85], v[182:185], v[30:33]
	v_mfma_f32_16x16x32_bf16 v[26:29], v[98:101], v[182:185], v[26:29]
	v_mfma_f32_16x16x32_bf16 v[14:17], v[82:85], v[190:193], v[14:17]
	v_mfma_f32_16x16x32_bf16 v[10:13], v[98:101], v[190:193], v[10:13]
	s_setprio 0
	s_setprio 1
	v_mfma_f32_16x16x32_bf16 v[54:57], v[106:109], v[150:153], v[54:57]
	v_mfma_f32_16x16x32_bf16 v[50:53], v[126:129], v[150:153], v[50:53]
	v_mfma_f32_16x16x32_bf16 v[38:41], v[106:109], v[166:169], v[38:41]
	v_mfma_f32_16x16x32_bf16 v[34:37], v[126:129], v[166:169], v[34:37]
	v_mfma_f32_16x16x32_bf16 v[22:25], v[106:109], v[178:181], v[22:25]
	v_mfma_f32_16x16x32_bf16 v[18:21], v[126:129], v[178:181], v[18:21]
	v_mfma_f32_16x16x32_bf16 v[6:9], v[106:109], v[186:189], v[6:9]
	v_mfma_f32_16x16x32_bf16 v[2:5], v[126:129], v[186:189], v[2:5]
	v_mfma_f32_16x16x32_bf16 v[54:57], v[110:113], v[158:161], v[54:57]
	v_mfma_f32_16x16x32_bf16 v[50:53], v[134:137], v[158:161], v[50:53]
	v_mfma_f32_16x16x32_bf16 v[38:41], v[110:113], v[174:177], v[38:41]
	v_mfma_f32_16x16x32_bf16 v[34:37], v[134:137], v[174:177], v[34:37]
	v_mfma_f32_16x16x32_bf16 v[22:25], v[110:113], v[182:185], v[22:25]
	v_mfma_f32_16x16x32_bf16 v[18:21], v[134:137], v[182:185], v[18:21]
	v_mfma_f32_16x16x32_bf16 v[6:9], v[110:113], v[190:193], v[6:9]
	v_mfma_f32_16x16x32_bf16 v[2:5], v[134:137], v[190:193], v[2:5]
	s_barrier
	s_setprio 0
	s_add_i32 s4, 0, 0x18000
	s_add_i32 s5, 0, 0x1c000
	ds_read_b128 v[78:81], v205 offset:32768
	ds_read_b128 v[82:85], v205 offset:33792
	ds_read_b128 v[94:97], v205 offset:34816
	ds_read_b128 v[98:101], v205 offset:35840
	ds_read_b128 v[106:109], v205 offset:49152
	ds_read_b128 v[110:113], v205 offset:50176
	ds_read_b128 v[126:129], v205 offset:51200
	ds_read_b128 v[134:137], v205 offset:52224
	s_add_u32 s0, s22, 0x160000
	s_addc_u32 s1, s23, 0
	s_mov_b32 m0, s29
	ds_read_b128 v[150:153], v239 offset:32768
	ds_read_b128 v[158:161], v239 offset:33792
	ds_read_b128 v[166:169], v239 offset:34816
	ds_read_b128 v[174:177], v239 offset:35840
	ds_read_b128 v[178:181], v239 offset:36864
	ds_read_b128 v[182:185], v239 offset:37888
	ds_read_b128 v[186:189], v239 offset:38912
	ds_read_b128 v[190:193], v239 offset:39936
	global_load_lds_dwordx4 v212, s[0:1]
	s_mov_b32 m0, s30
	s_nop 0
	global_load_lds_dwordx4 v210, s[0:1]
	s_waitcnt vmcnt(8)
	s_waitcnt lgkmcnt(0)
	s_setprio 1
	s_barrier
	v_mfma_f32_16x16x32_bf16 v[170:173], v[78:81], v[150:153], v[170:173]
	v_mfma_f32_16x16x32_bf16 v[162:165], v[94:97], v[150:153], v[162:165]
	v_mfma_f32_16x16x32_bf16 v[142:145], v[78:81], v[166:169], v[142:145]
	v_mfma_f32_16x16x32_bf16 v[138:141], v[94:97], v[166:169], v[138:141]
	v_mfma_f32_16x16x32_bf16 v[118:121], v[78:81], v[178:181], v[118:121]
	v_mfma_f32_16x16x32_bf16 v[114:117], v[94:97], v[178:181], v[114:117]
	v_mfma_f32_16x16x32_bf16 v[86:89], v[78:81], v[186:189], v[86:89]
	v_mfma_f32_16x16x32_bf16 v[74:77], v[94:97], v[186:189], v[74:77]
	v_mfma_f32_16x16x32_bf16 v[170:173], v[82:85], v[158:161], v[170:173]
	v_mfma_f32_16x16x32_bf16 v[162:165], v[98:101], v[158:161], v[162:165]
	v_mfma_f32_16x16x32_bf16 v[142:145], v[82:85], v[174:177], v[142:145]
	v_mfma_f32_16x16x32_bf16 v[138:141], v[98:101], v[174:177], v[138:141]
	v_mfma_f32_16x16x32_bf16 v[118:121], v[82:85], v[182:185], v[118:121]
	v_mfma_f32_16x16x32_bf16 v[114:117], v[98:101], v[182:185], v[114:117]
	v_mfma_f32_16x16x32_bf16 v[86:89], v[82:85], v[190:193], v[86:89]
	v_mfma_f32_16x16x32_bf16 v[74:77], v[98:101], v[190:193], v[74:77]
	s_setprio 0
	s_setprio 1
	v_mfma_f32_16x16x32_bf16 v[154:157], v[106:109], v[150:153], v[154:157]
	v_mfma_f32_16x16x32_bf16 v[146:149], v[126:129], v[150:153], v[146:149]
	v_mfma_f32_16x16x32_bf16 v[130:133], v[106:109], v[166:169], v[130:133]
	v_mfma_f32_16x16x32_bf16 v[122:125], v[126:129], v[166:169], v[122:125]
	v_mfma_f32_16x16x32_bf16 v[102:105], v[106:109], v[178:181], v[102:105]
	v_mfma_f32_16x16x32_bf16 v[90:93], v[126:129], v[178:181], v[90:93]
	v_mfma_f32_16x16x32_bf16 v[70:73], v[106:109], v[186:189], v[70:73]
	v_mfma_f32_16x16x32_bf16 v[66:69], v[126:129], v[186:189], v[66:69]
	v_mfma_f32_16x16x32_bf16 v[154:157], v[110:113], v[158:161], v[154:157]
	v_mfma_f32_16x16x32_bf16 v[150:153], v[134:137], v[158:161], v[146:149]
	v_mfma_f32_16x16x32_bf16 v[130:133], v[110:113], v[174:177], v[130:133]
	v_mfma_f32_16x16x32_bf16 v[122:125], v[134:137], v[174:177], v[122:125]
	v_mfma_f32_16x16x32_bf16 v[102:105], v[110:113], v[182:185], v[102:105]
	v_mfma_f32_16x16x32_bf16 v[90:93], v[134:137], v[182:185], v[90:93]
	v_mfma_f32_16x16x32_bf16 v[70:73], v[110:113], v[190:193], v[70:73]
	v_mfma_f32_16x16x32_bf16 v[66:69], v[134:137], v[190:193], v[66:69]
	s_barrier
	s_setprio 0
	s_add_i32 s0, s4, s26
	s_add_u32 s100, s20, 0x80
	s_addc_u32 s101, s21, 0
	s_mov_b32 m0, s0
	ds_read_b128 v[146:149], v239 offset:49152
	ds_read_b128 v[158:161], v239 offset:50176
	ds_read_b128 v[166:169], v239 offset:51200
	ds_read_b128 v[174:177], v239 offset:52224
	ds_read_b128 v[178:181], v239 offset:53248
	ds_read_b128 v[182:185], v239 offset:54272
	ds_read_b128 v[186:189], v239 offset:55296
	ds_read_b128 v[190:193], v239 offset:56320
	global_load_lds_dwordx4 v202, s[100:101]
	s_add_i32 m0, s0, 0x2000
	s_add_u32 s100, s20, 0x80
	s_addc_u32 s101, s21, 0
	s_add_u32 s0, s20, 0x160080
	s_addc_u32 s1, s21, 0
	s_add_i32 s4, s5, s26
	global_load_lds_dwordx4 v208, s[100:101]
	s_mov_b32 m0, s4
	s_nop 0
	global_load_lds_dwordx4 v202, s[0:1]
	s_add_i32 m0, s4, 0x2000
	s_nop 0
	global_load_lds_dwordx4 v208, s[0:1]
	s_add_u32 s100, s22, 0x80
	s_addc_u32 s101, s23, 0
	s_mov_b32 m0, s35
	s_nop 0
	global_load_lds_dwordx4 v212, s[100:101]
	s_add_u32 s100, s22, 0x80
	s_addc_u32 s101, s23, 0
	s_mov_b32 m0, s36
	s_nop 0
	global_load_lds_dwordx4 v210, s[100:101]
	s_waitcnt vmcnt(8)
	s_waitcnt lgkmcnt(0)
	s_setprio 1
	s_barrier
	v_mfma_f32_16x16x32_bf16 v[62:65], v[78:81], v[146:149], v[62:65]
	v_mfma_f32_16x16x32_bf16 v[58:61], v[94:97], v[146:149], v[58:61]
	v_mfma_f32_16x16x32_bf16 v[46:49], v[78:81], v[166:169], v[46:49]
	v_mfma_f32_16x16x32_bf16 v[42:45], v[94:97], v[166:169], v[42:45]
	v_mfma_f32_16x16x32_bf16 v[30:33], v[78:81], v[178:181], v[30:33]
	v_mfma_f32_16x16x32_bf16 v[26:29], v[94:97], v[178:181], v[26:29]
	v_mfma_f32_16x16x32_bf16 v[14:17], v[78:81], v[186:189], v[14:17]
	v_mfma_f32_16x16x32_bf16 v[10:13], v[94:97], v[186:189], v[10:13]
	v_mfma_f32_16x16x32_bf16 v[62:65], v[82:85], v[158:161], v[62:65]
	v_mfma_f32_16x16x32_bf16 v[58:61], v[98:101], v[158:161], v[58:61]
	v_mfma_f32_16x16x32_bf16 v[46:49], v[82:85], v[174:177], v[46:49]
	v_mfma_f32_16x16x32_bf16 v[42:45], v[98:101], v[174:177], v[42:45]
	v_mfma_f32_16x16x32_bf16 v[30:33], v[82:85], v[182:185], v[30:33]
	v_mfma_f32_16x16x32_bf16 v[26:29], v[98:101], v[182:185], v[26:29]
	v_mfma_f32_16x16x32_bf16 v[14:17], v[82:85], v[190:193], v[14:17]
	v_mfma_f32_16x16x32_bf16 v[10:13], v[98:101], v[190:193], v[10:13]
	s_setprio 0
	s_setprio 1
	v_mfma_f32_16x16x32_bf16 v[54:57], v[106:109], v[146:149], v[54:57]
	v_mfma_f32_16x16x32_bf16 v[50:53], v[126:129], v[146:149], v[50:53]
	v_mfma_f32_16x16x32_bf16 v[38:41], v[106:109], v[166:169], v[38:41]
	v_mfma_f32_16x16x32_bf16 v[34:37], v[126:129], v[166:169], v[34:37]
	v_mfma_f32_16x16x32_bf16 v[22:25], v[106:109], v[178:181], v[22:25]
	v_mfma_f32_16x16x32_bf16 v[18:21], v[126:129], v[178:181], v[18:21]
	v_mfma_f32_16x16x32_bf16 v[6:9], v[106:109], v[186:189], v[6:9]
	v_mfma_f32_16x16x32_bf16 v[2:5], v[126:129], v[186:189], v[2:5]
	v_mfma_f32_16x16x32_bf16 v[54:57], v[110:113], v[158:161], v[54:57]
	v_mfma_f32_16x16x32_bf16 v[50:53], v[134:137], v[158:161], v[50:53]
	v_mfma_f32_16x16x32_bf16 v[38:41], v[110:113], v[174:177], v[38:41]
	v_mfma_f32_16x16x32_bf16 v[34:37], v[134:137], v[174:177], v[34:37]
	v_mfma_f32_16x16x32_bf16 v[22:25], v[110:113], v[182:185], v[22:25]
	v_mfma_f32_16x16x32_bf16 v[18:21], v[134:137], v[182:185], v[18:21]
	v_mfma_f32_16x16x32_bf16 v[6:9], v[110:113], v[190:193], v[6:9]
	v_mfma_f32_16x16x32_bf16 v[2:5], v[134:137], v[190:193], v[2:5]
	s_barrier
	s_setprio 0
	s_add_i32 s59, s59, 2
	s_add_u32 s49, s49, 0x100
	s_addc_u32 s58, s58, 0
	s_cmpk_gt_u32 s59, 0x55
	s_mov_b64 s[4:5], s[18:19]
	s_cbranch_scc0 .LBB0_1718
	s_and_b64 vcc, exec, s[14:15]
	s_cbranch_vccz .LBB0_1721
	s_barrier

.LBB0_1729:
	v_bfe_u32 v20, v14, 4, 2
	s_lshl_b32 s0, s0, 5
	v_and_b32_e32 v15, 15, v14
	v_lshlrev_b32_e32 v22, 4, v20
	v_lshlrev_b32_e32 v14, 2, v14
	s_and_b32 s3, s0, 0x60
	v_lshl_or_b32 v21, s1, 6, v15
	v_lshl_or_b32 v15, v15, 6, v22
	s_lshl_b32 s1, s1, 13
	v_and_b32_e32 v14, 32, v14
	s_lshl_b32 s0, s3, 7
	v_readlane_b32 s14, v253, 18
	v_bitop3_b32 v136, v15, s0, v14 bitop3:0xde
	v_add_u32_e32 v136, 0x10000, v136
	s_add_u32 s0, s16, 0x160080
	v_readlane_b32 s15, v253, 19
	v_bitop3_b32 v22, v15, s1, v14 bitop3:0xde
	s_addc_u32 s1, s17, 0
	s_add_i32 m0, s23, 0x18000
	v_lshl_add_u64 v[2:3], v[2:3], 0, s[80:81]
	v_lshl_add_u64 v[16:17], s[14:15], 0, v[202:203]
	s_waitcnt vmcnt(2)
	s_barrier
	global_load_lds_dwordx4 v[2:3], off
	v_lshl_add_u64 v[2:3], v[4:5], 0, s[80:81]
	s_add_i32 m0, s23, 0x1a000
	s_add_i32 s29, s23, 0x8000
	v_lshl_add_u64 v[18:19], s[14:15], 0, v[130:131]
	global_load_lds_dwordx4 v[2:3], off
	v_lshl_add_u64 v[2:3], v[16:17], 0, s[80:81]
	s_mov_b32 m0, s29
	s_add_i32 s30, s23, 0xa000
	global_load_lds_dwordx4 v[2:3], off
	v_lshl_add_u64 v[2:3], v[18:19], 0, s[80:81]
	s_mov_b32 m0, s30
	v_lshl_or_b32 v138, v20, 2, s3
	global_load_lds_dwordx4 v[2:3], off
	s_add_i32 m0, s23, 0x1c000
	v_lshl_add_u64 v[2:3], s[0:1], 0, v[202:203]
	global_load_lds_dwordx4 v[2:3], off
	v_lshl_add_u64 v[2:3], s[0:1], 0, v[130:131]
	s_add_i32 m0, s23, 0x1e000
	s_movk_i32 s3, 0x1600
	global_load_lds_dwordx4 v[2:3], off
	s_cmpk_lt_u32 s2, 0x100
	v_lshrrev_b32_e32 v3, 1, v11
	v_mul_lo_u32 v2, v13, s3
	s_mov_b32 s2, 0x16000
	v_mad_u64_u32 v[2:3], s[0:1], v3, s2, v[2:3]
	v_or_b32_e32 v2, v2, v10
	v_add_lshl_u32 v2, v2, v12, 1
	v_mov_b32_e32 v3, v203
	s_mov_b64 s[8:9], 0x160080
	v_lshl_add_u64 v[132:133], v[2:3], 0, s[8:9]
	v_lshrrev_b32_e32 v3, 1, v7
	v_mul_lo_u32 v2, v9, s3
	v_mad_u64_u32 v[2:3], s[0:1], v3, s2, v[2:3]
	s_waitcnt vmcnt(6)
	v_or_b32_e32 v2, v2, v6
	v_add_lshl_u32 v2, v2, v8, 1
	v_mov_b32_e32 v3, v203
	s_cselect_b64 s[6:7], -1, 0
	v_add_u32_e32 v137, 0xffffc000, v21
	v_lshl_add_u64 v[134:135], v[2:3], 0, s[8:9]
	s_mov_b32 s31, 0
	v_add_u32_e32 v139, 0, v22
	v_readlane_b32 s38, v253, 16
	v_readlane_b32 s39, v254, 41
	v_readlane_b32 s37, v253, 13
	s_barrier
	s_branch .LBB0_1732

.LBB0_1739:
	s_add_u32 s16, s14, 0x100
	s_addc_u32 s17, s15, 0
	s_add_i32 s0, 0, 0x10000
	s_cmp_eq_u32 s49, 4
	s_cselect_b32 s21, s9, s17
	s_cselect_b32 s20, s8, s16
	s_cselect_b32 s19, s11, s41
	s_cselect_b32 s18, s10, s40
	s_add_i32 s33, 0, 0x14000
	ds_read_b128 v[140:143], v136
	ds_read_b128 v[144:147], v136 offset:1024
	ds_read_b128 v[148:151], v136 offset:2048
	ds_read_b128 v[152:155], v136 offset:3072
	ds_read_b128 v[156:159], v136 offset:16384
	ds_read_b128 v[160:163], v136 offset:17408
	ds_read_b128 v[164:167], v136 offset:18432
	ds_read_b128 v[168:171], v136 offset:19456
	s_add_i32 m0, s23, 0xc000
	ds_read_b128 v[172:175], v139
	ds_read_b128 v[176:179], v139 offset:1024
	ds_read_b128 v[180:183], v139 offset:2048
	ds_read_b128 v[184:187], v139 offset:3072
	ds_read_b128 v[188:191], v139 offset:4096
	ds_read_b128 v[192:195], v139 offset:5120
	ds_read_b128 v[196:199], v139 offset:6144
	ds_read_b128 v[208:211], v139 offset:7168
	global_load_lds_dwordx4 v132, s[14:15]
	s_add_i32 m0, s23, 0xe000
	s_nop 0
	global_load_lds_dwordx4 v134, s[14:15]
	s_waitcnt vmcnt(8)
	s_waitcnt lgkmcnt(0)
	s_setprio 1
	s_barrier
	v_mfma_f32_16x16x32_bf16 v[126:129], v[140:143], v[172:175], v[126:129]
	v_mfma_f32_16x16x32_bf16 v[122:125], v[148:151], v[172:175], v[122:125]
	v_mfma_f32_16x16x32_bf16 v[118:121], v[140:143], v[180:183], v[118:121]
	v_mfma_f32_16x16x32_bf16 v[114:117], v[148:151], v[180:183], v[114:117]
	v_mfma_f32_16x16x32_bf16 v[106:109], v[140:143], v[188:191], v[106:109]
	v_mfma_f32_16x16x32_bf16 v[98:101], v[148:151], v[188:191], v[98:101]
	v_mfma_f32_16x16x32_bf16 v[90:93], v[140:143], v[196:199], v[90:93]
	v_mfma_f32_16x16x32_bf16 v[82:85], v[148:151], v[196:199], v[82:85]
	v_mfma_f32_16x16x32_bf16 v[126:129], v[144:147], v[176:179], v[126:129]
	v_mfma_f32_16x16x32_bf16 v[122:125], v[152:155], v[176:179], v[122:125]
	v_mfma_f32_16x16x32_bf16 v[118:121], v[144:147], v[184:187], v[118:121]
	v_mfma_f32_16x16x32_bf16 v[114:117], v[152:155], v[184:187], v[114:117]
	v_mfma_f32_16x16x32_bf16 v[106:109], v[144:147], v[192:195], v[106:109]
	v_mfma_f32_16x16x32_bf16 v[98:101], v[152:155], v[192:195], v[98:101]
	v_mfma_f32_16x16x32_bf16 v[90:93], v[144:147], v[208:211], v[90:93]
	v_mfma_f32_16x16x32_bf16 v[82:85], v[152:155], v[208:211], v[82:85]
	s_setprio 0
	s_setprio 1
	v_mfma_f32_16x16x32_bf16 v[110:113], v[156:159], v[172:175], v[110:113]
	v_mfma_f32_16x16x32_bf16 v[102:105], v[164:167], v[172:175], v[102:105]
	v_mfma_f32_16x16x32_bf16 v[94:97], v[156:159], v[180:183], v[94:97]
	v_mfma_f32_16x16x32_bf16 v[86:89], v[164:167], v[180:183], v[86:89]
	v_mfma_f32_16x16x32_bf16 v[78:81], v[156:159], v[188:191], v[78:81]
	v_mfma_f32_16x16x32_bf16 v[74:77], v[164:167], v[188:191], v[74:77]
	v_mfma_f32_16x16x32_bf16 v[70:73], v[156:159], v[196:199], v[70:73]
	v_mfma_f32_16x16x32_bf16 v[66:69], v[164:167], v[196:199], v[66:69]
	v_mfma_f32_16x16x32_bf16 v[110:113], v[160:163], v[176:179], v[110:113]
	v_mfma_f32_16x16x32_bf16 v[102:105], v[168:171], v[176:179], v[102:105]
	v_mfma_f32_16x16x32_bf16 v[94:97], v[160:163], v[184:187], v[94:97]
	v_mfma_f32_16x16x32_bf16 v[86:89], v[168:171], v[184:187], v[86:89]
	v_mfma_f32_16x16x32_bf16 v[78:81], v[160:163], v[192:195], v[78:81]
	v_mfma_f32_16x16x32_bf16 v[74:77], v[168:171], v[192:195], v[74:77]
	v_mfma_f32_16x16x32_bf16 v[70:73], v[160:163], v[208:211], v[70:73]
	v_mfma_f32_16x16x32_bf16 v[66:69], v[168:171], v[208:211], v[66:69]
	s_barrier
	s_setprio 0
	s_add_i32 s0, s0, s22
	s_mov_b32 m0, s0
	ds_read_b128 v[172:175], v139 offset:16384
	ds_read_b128 v[176:179], v139 offset:17408
	ds_read_b128 v[180:183], v139 offset:18432
	ds_read_b128 v[184:187], v139 offset:19456
	ds_read_b128 v[188:191], v139 offset:20480
	ds_read_b128 v[192:195], v139 offset:21504
	ds_read_b128 v[196:199], v139 offset:22528
	ds_read_b128 v[208:211], v139 offset:23552
	global_load_lds_dwordx4 v202, s[18:19]
	s_add_i32 m0, s0, 0x2000
	s_add_u32 s0, s18, 0x160000
	s_addc_u32 s1, s19, 0
	s_add_i32 s14, s33, s22
	global_load_lds_dwordx4 v130, s[18:19]
	s_mov_b32 m0, s14
	s_nop 0
	global_load_lds_dwordx4 v202, s[0:1]
	s_add_i32 m0, s14, 0x2000
	s_nop 0
	global_load_lds_dwordx4 v130, s[0:1]
	s_mov_b32 m0, s23
	s_nop 0
	global_load_lds_dwordx4 v202, s[20:21]
	s_mov_b32 m0, s26
	s_nop 0
	global_load_lds_dwordx4 v130, s[20:21]
	s_waitcnt vmcnt(8)
	s_waitcnt lgkmcnt(0)
	s_setprio 1
	s_barrier
	v_mfma_f32_16x16x32_bf16 v[62:65], v[140:143], v[172:175], v[62:65]
	v_mfma_f32_16x16x32_bf16 v[58:61], v[148:151], v[172:175], v[58:61]
	v_mfma_f32_16x16x32_bf16 v[54:57], v[140:143], v[180:183], v[54:57]
	v_mfma_f32_16x16x32_bf16 v[50:53], v[148:151], v[180:183], v[50:53]
	v_mfma_f32_16x16x32_bf16 v[38:41], v[140:143], v[188:191], v[38:41]
	v_mfma_f32_16x16x32_bf16 v[34:37], v[148:151], v[188:191], v[34:37]
	v_mfma_f32_16x16x32_bf16 v[22:25], v[140:143], v[196:199], v[22:25]
	v_mfma_f32_16x16x32_bf16 v[18:21], v[148:151], v[196:199], v[18:21]
	v_mfma_f32_16x16x32_bf16 v[62:65], v[144:147], v[176:179], v[62:65]
	v_mfma_f32_16x16x32_bf16 v[58:61], v[152:155], v[176:179], v[58:61]
	v_mfma_f32_16x16x32_bf16 v[54:57], v[144:147], v[184:187], v[54:57]
	v_mfma_f32_16x16x32_bf16 v[50:53], v[152:155], v[184:187], v[50:53]
	v_mfma_f32_16x16x32_bf16 v[38:41], v[144:147], v[192:195], v[38:41]
	v_mfma_f32_16x16x32_bf16 v[34:37], v[152:155], v[192:195], v[34:37]
	v_mfma_f32_16x16x32_bf16 v[22:25], v[144:147], v[208:211], v[22:25]
	v_mfma_f32_16x16x32_bf16 v[18:21], v[152:155], v[208:211], v[18:21]
	s_setprio 0
	s_setprio 1
	v_mfma_f32_16x16x32_bf16 v[46:49], v[156:159], v[172:175], v[46:49]
	v_mfma_f32_16x16x32_bf16 v[42:45], v[164:167], v[172:175], v[42:45]
	v_mfma_f32_16x16x32_bf16 v[30:33], v[156:159], v[180:183], v[30:33]
	v_mfma_f32_16x16x32_bf16 v[26:29], v[164:167], v[180:183], v[26:29]
	v_mfma_f32_16x16x32_bf16 v[14:17], v[156:159], v[188:191], v[14:17]
	v_mfma_f32_16x16x32_bf16 v[10:13], v[164:167], v[188:191], v[10:13]
	v_mfma_f32_16x16x32_bf16 v[6:9], v[156:159], v[196:199], v[6:9]
	v_mfma_f32_16x16x32_bf16 v[2:5], v[164:167], v[196:199], v[2:5]
	v_mfma_f32_16x16x32_bf16 v[46:49], v[160:163], v[176:179], v[46:49]
	v_mfma_f32_16x16x32_bf16 v[42:45], v[168:171], v[176:179], v[42:45]
	v_mfma_f32_16x16x32_bf16 v[30:33], v[160:163], v[184:187], v[30:33]
	v_mfma_f32_16x16x32_bf16 v[26:29], v[168:171], v[184:187], v[26:29]
	v_mfma_f32_16x16x32_bf16 v[14:17], v[160:163], v[192:195], v[14:17]
	v_mfma_f32_16x16x32_bf16 v[10:13], v[168:171], v[192:195], v[10:13]
	v_mfma_f32_16x16x32_bf16 v[6:9], v[160:163], v[208:211], v[6:9]
	v_mfma_f32_16x16x32_bf16 v[2:5], v[168:171], v[208:211], v[2:5]
	s_barrier
	s_setprio 0
	s_add_i32 s14, 0, 0x18000
	s_add_i32 s15, 0, 0x1c000
	ds_read_b128 v[140:143], v136 offset:32768
	ds_read_b128 v[144:147], v136 offset:33792
	ds_read_b128 v[148:151], v136 offset:34816
	ds_read_b128 v[152:155], v136 offset:35840
	ds_read_b128 v[156:159], v136 offset:49152
	ds_read_b128 v[160:163], v136 offset:50176
	ds_read_b128 v[164:167], v136 offset:51200
	ds_read_b128 v[168:171], v136 offset:52224
	s_add_u32 s0, s20, 0x160000
	s_addc_u32 s1, s21, 0
	s_mov_b32 m0, s27
	ds_read_b128 v[172:175], v139 offset:32768
	ds_read_b128 v[176:179], v139 offset:33792
	ds_read_b128 v[180:183], v139 offset:34816
	ds_read_b128 v[184:187], v139 offset:35840
	ds_read_b128 v[188:191], v139 offset:36864
	ds_read_b128 v[192:195], v139 offset:37888
	ds_read_b128 v[196:199], v139 offset:38912
	ds_read_b128 v[208:211], v139 offset:39936
	global_load_lds_dwordx4 v202, s[0:1]
	s_mov_b32 m0, s28
	s_nop 0
	global_load_lds_dwordx4 v130, s[0:1]
	s_waitcnt vmcnt(8)
	s_waitcnt lgkmcnt(0)
	s_setprio 1
	s_barrier
	v_mfma_f32_16x16x32_bf16 v[126:129], v[140:143], v[172:175], v[126:129]
	v_mfma_f32_16x16x32_bf16 v[122:125], v[148:151], v[172:175], v[122:125]
	v_mfma_f32_16x16x32_bf16 v[118:121], v[140:143], v[180:183], v[118:121]
	v_mfma_f32_16x16x32_bf16 v[114:117], v[148:151], v[180:183], v[114:117]
	v_mfma_f32_16x16x32_bf16 v[106:109], v[140:143], v[188:191], v[106:109]
	v_mfma_f32_16x16x32_bf16 v[98:101], v[148:151], v[188:191], v[98:101]
	v_mfma_f32_16x16x32_bf16 v[90:93], v[140:143], v[196:199], v[90:93]
	v_mfma_f32_16x16x32_bf16 v[82:85], v[148:151], v[196:199], v[82:85]
	v_mfma_f32_16x16x32_bf16 v[126:129], v[144:147], v[176:179], v[126:129]
	v_mfma_f32_16x16x32_bf16 v[122:125], v[152:155], v[176:179], v[122:125]
	v_mfma_f32_16x16x32_bf16 v[118:121], v[144:147], v[184:187], v[118:121]
	v_mfma_f32_16x16x32_bf16 v[114:117], v[152:155], v[184:187], v[114:117]
	v_mfma_f32_16x16x32_bf16 v[106:109], v[144:147], v[192:195], v[106:109]
	v_mfma_f32_16x16x32_bf16 v[98:101], v[152:155], v[192:195], v[98:101]
	v_mfma_f32_16x16x32_bf16 v[90:93], v[144:147], v[208:211], v[90:93]
	v_mfma_f32_16x16x32_bf16 v[82:85], v[152:155], v[208:211], v[82:85]
	s_setprio 0
	s_setprio 1
	v_mfma_f32_16x16x32_bf16 v[110:113], v[156:159], v[172:175], v[110:113]
	v_mfma_f32_16x16x32_bf16 v[102:105], v[164:167], v[172:175], v[102:105]
	v_mfma_f32_16x16x32_bf16 v[94:97], v[156:159], v[180:183], v[94:97]
	v_mfma_f32_16x16x32_bf16 v[86:89], v[164:167], v[180:183], v[86:89]
	v_mfma_f32_16x16x32_bf16 v[78:81], v[156:159], v[188:191], v[78:81]
	v_mfma_f32_16x16x32_bf16 v[74:77], v[164:167], v[188:191], v[74:77]
	v_mfma_f32_16x16x32_bf16 v[70:73], v[156:159], v[196:199], v[70:73]
	v_mfma_f32_16x16x32_bf16 v[66:69], v[164:167], v[196:199], v[66:69]
	v_mfma_f32_16x16x32_bf16 v[110:113], v[160:163], v[176:179], v[110:113]
	v_mfma_f32_16x16x32_bf16 v[102:105], v[168:171], v[176:179], v[102:105]
	v_mfma_f32_16x16x32_bf16 v[94:97], v[160:163], v[184:187], v[94:97]
	v_mfma_f32_16x16x32_bf16 v[86:89], v[168:171], v[184:187], v[86:89]
	v_mfma_f32_16x16x32_bf16 v[78:81], v[160:163], v[192:195], v[78:81]
	v_mfma_f32_16x16x32_bf16 v[74:77], v[168:171], v[192:195], v[74:77]
	v_mfma_f32_16x16x32_bf16 v[70:73], v[160:163], v[208:211], v[70:73]
	v_mfma_f32_16x16x32_bf16 v[66:69], v[168:171], v[208:211], v[66:69]
	s_barrier
	s_setprio 0
	s_add_i32 s0, s14, s22
	s_add_u32 s100, s18, 0x80
	s_addc_u32 s101, s19, 0
	s_mov_b32 m0, s0
	ds_read_b128 v[172:175], v139 offset:49152
	ds_read_b128 v[176:179], v139 offset:50176
	ds_read_b128 v[180:183], v139 offset:51200
	ds_read_b128 v[184:187], v139 offset:52224
	ds_read_b128 v[188:191], v139 offset:53248
	ds_read_b128 v[192:195], v139 offset:54272
	ds_read_b128 v[196:199], v139 offset:55296
	ds_read_b128 v[208:211], v139 offset:56320
	global_load_lds_dwordx4 v202, s[100:101]
	s_add_i32 m0, s0, 0x2000
	s_add_u32 s100, s18, 0x80
	s_addc_u32 s101, s19, 0
	s_add_u32 s0, s18, 0x160080
	s_addc_u32 s1, s19, 0
	s_add_i32 s14, s15, s22
	global_load_lds_dwordx4 v130, s[100:101]
	s_mov_b32 m0, s14
	s_nop 0
	global_load_lds_dwordx4 v202, s[0:1]
	s_add_i32 m0, s14, 0x2000
	s_nop 0
	global_load_lds_dwordx4 v130, s[0:1]
	s_add_u32 s100, s20, 0x80
	s_addc_u32 s101, s21, 0
	s_mov_b32 m0, s29
	s_nop 0
	global_load_lds_dwordx4 v202, s[100:101]
	s_add_u32 s100, s20, 0x80
	s_addc_u32 s101, s21, 0
	s_mov_b32 m0, s30
	s_nop 0
	global_load_lds_dwordx4 v130, s[100:101]
	s_waitcnt vmcnt(8)
	s_waitcnt lgkmcnt(0)
	s_setprio 1
	s_barrier
	v_mfma_f32_16x16x32_bf16 v[62:65], v[140:143], v[172:175], v[62:65]
	v_mfma_f32_16x16x32_bf16 v[58:61], v[148:151], v[172:175], v[58:61]
	v_mfma_f32_16x16x32_bf16 v[54:57], v[140:143], v[180:183], v[54:57]
	v_mfma_f32_16x16x32_bf16 v[50:53], v[148:151], v[180:183], v[50:53]
	v_mfma_f32_16x16x32_bf16 v[38:41], v[140:143], v[188:191], v[38:41]
	v_mfma_f32_16x16x32_bf16 v[34:37], v[148:151], v[188:191], v[34:37]
	v_mfma_f32_16x16x32_bf16 v[22:25], v[140:143], v[196:199], v[22:25]
	v_mfma_f32_16x16x32_bf16 v[18:21], v[148:151], v[196:199], v[18:21]
	v_mfma_f32_16x16x32_bf16 v[62:65], v[144:147], v[176:179], v[62:65]
	v_mfma_f32_16x16x32_bf16 v[58:61], v[152:155], v[176:179], v[58:61]
	v_mfma_f32_16x16x32_bf16 v[54:57], v[144:147], v[184:187], v[54:57]
	v_mfma_f32_16x16x32_bf16 v[50:53], v[152:155], v[184:187], v[50:53]
	v_mfma_f32_16x16x32_bf16 v[38:41], v[144:147], v[192:195], v[38:41]
	v_mfma_f32_16x16x32_bf16 v[34:37], v[152:155], v[192:195], v[34:37]
	v_mfma_f32_16x16x32_bf16 v[22:25], v[144:147], v[208:211], v[22:25]
	v_mfma_f32_16x16x32_bf16 v[18:21], v[152:155], v[208:211], v[18:21]
	s_setprio 0
	s_setprio 1
	v_mfma_f32_16x16x32_bf16 v[46:49], v[156:159], v[172:175], v[46:49]
	v_mfma_f32_16x16x32_bf16 v[42:45], v[164:167], v[172:175], v[42:45]
	v_mfma_f32_16x16x32_bf16 v[30:33], v[156:159], v[180:183], v[30:33]
	v_mfma_f32_16x16x32_bf16 v[26:29], v[164:167], v[180:183], v[26:29]
	v_mfma_f32_16x16x32_bf16 v[14:17], v[156:159], v[188:191], v[14:17]
	v_mfma_f32_16x16x32_bf16 v[10:13], v[164:167], v[188:191], v[10:13]
	v_mfma_f32_16x16x32_bf16 v[6:9], v[156:159], v[196:199], v[6:9]
	v_mfma_f32_16x16x32_bf16 v[2:5], v[164:167], v[196:199], v[2:5]
	v_mfma_f32_16x16x32_bf16 v[46:49], v[160:163], v[176:179], v[46:49]
	v_mfma_f32_16x16x32_bf16 v[42:45], v[168:171], v[176:179], v[42:45]
	v_mfma_f32_16x16x32_bf16 v[30:33], v[160:163], v[184:187], v[30:33]
	v_mfma_f32_16x16x32_bf16 v[26:29], v[168:171], v[184:187], v[26:29]
	v_mfma_f32_16x16x32_bf16 v[14:17], v[160:163], v[192:195], v[14:17]
	v_mfma_f32_16x16x32_bf16 v[10:13], v[168:171], v[192:195], v[10:13]
	v_mfma_f32_16x16x32_bf16 v[6:9], v[160:163], v[208:211], v[6:9]
	v_mfma_f32_16x16x32_bf16 v[2:5], v[168:171], v[208:211], v[2:5]
	s_barrier
	s_setprio 0
	s_add_i32 s49, s49, 2
	s_add_u32 s40, s40, 0x100
	s_addc_u32 s41, s41, 0
	s_cmp_gt_u32 s49, 5
	s_mov_b64 s[14:15], s[16:17]
	s_cbranch_scc0 .LBB0_1739
	s_and_b64 vcc, exec, s[6:7]
	s_cbranch_vccz .LBB0_1742
	s_barrier
